# speedup vs baseline: 1.1182x; 1.0299x over previous
; #define MFMA16(a, b, c) __builtin_amdgcn_mfma_f32_16x16x32_bf16((a), (b), (c), 0, 0, 0)
; DI void gld(u32x4v& r, const void* p) { asm volatile("global_load_dwordx4 %0, %1, off" : "=v"(r) : "v"(p) : "memory"); }
; #define WAIT_SET(N, a, b) asm volatile("s_waitcnt vmcnt(" #N ")" : "+v"(a[0]), "+v"(a[1]), "+v"(a[2]), "+v"(a[3]), "+v"(b[0]), "+v"(b[1]), "+v"(b[2]), "+v"(b[3]) :: "memory")
; DI void gemm_half(f32x4 (&acc)[4][4], const char* sa, const char* sb, int o0, int o1, u32x4v (&ra)[4], u32x4v (&rb)[4],
;                   char* stw, const bf16_t* Agn, const bf16_t* Bgn, int lda, int ldb) {
;   bf16x8 af0[4], bf0[4], af1[4], bf1[4];
; #pragma unroll
;   for (int i = 0; i < 4; ++i) { af0[i] = *(const bf16x8*)(sa + i * 16 * 128 + o0); bf0[i] = *(const bf16x8*)(sb + i * 16 * 128 + o0); }
;   __builtin_amdgcn_sched_barrier(0);
;   WAIT_SET(8, ra, rb);
; #pragma unroll
;   for (int g = 0; g < 8; ++g) {
; #pragma unroll
;     for (int ni = 0; ni < 4; ++ni) {
;       if (g < 4) acc[g][ni] = MFMA16(bf0[ni], af0[g], acc[g][ni]);
;       else acc[g - 4][ni] = MFMA16(bf1[ni], af1[g - 4], acc[g - 4][ni]);
;     }
;     if (g < 4) { af1[g] = *(const bf16x8*)(sa + g * 16 * 128 + o1); bf1[g] = *(const bf16x8*)(sb + g * 16 * 128 + o1);
;                  *(u32x4v*)(stw + g * 32 * 128) = ra[g]; gld(ra[g], Agn + (size_t)g * 32 * lda); }
;     else { *(u32x4v*)(stw + TILE_B + (g - 4) * 32 * 128) = rb[g - 4]; gld(rb[g - 4], Bgn + (size_t)(g - 4) * 32 * ldb); }
;     __builtin_amdgcn_sched_barrier(0);
;   }
; DI void gemm_kloop(f32x4 (&acc)[4][4], const bf16_t* Ag, const bf16_t* Bg, int lda, int ldb, int K, char* smem,
;                    u32x4v (&ra)[4], u32x4v (&rb)[4], u32x4v (&rc)[4], u32x4v (&rd)[4], bool pre,
;                    const bf16_t* Agn, const bf16_t* Bgn, bool hasnext) {
;     ...
;   for (int kt = 0; kt < nk; kt += 2) {
;     const bool last = kt + 2 >= nk;
;     const bf16_t* pa1 = last ? (hasnext ? Agn + 64 : Alast) : Ag + (size_t)(kt + 3) * 64;
;     const bf16_t* pb1 = last ? (hasnext ? Bgn + 64 : Blast) : Bg + (size_t)(kt + 3) * 64;
;     gemm_half(acc, sa0, sb0, o0, o1, rc, rd, st + 2 * TILE_B, pa1, pb1, lda, ldb);
;     __syncthreads();
;     const bf16_t* pa0 = kt + 4 < nk ? Ag + (size_t)(kt + 4) * 64 : ((last && hasnext) ? Agn : Alast);
;     const bf16_t* pb0 = kt + 4 < nk ? Bg + (size_t)(kt + 4) * 64 : ((last && hasnext) ? Bgn : Blast);
.LBB0_220:
	s_add_i32 s17, s17, 2
	s_cmp_gt_u32 s17, 5
	v_lshl_add_u64 v[182:183], v[146:147], 0, v[184:185]
	s_cselect_b64 vcc, -1, 0
	v_lshl_add_u64 v[158:159], v[182:183], 0, s[30:31]
	v_lshl_add_u64 v[208:209], v[148:149], 0, v[184:185]
	s_mov_b64 s[0:1], 0x600180
	v_cndmask_b32_e32 v207, v159, v133, vcc
	v_cndmask_b32_e32 v206, v158, v142, vcc
	v_lshl_add_u64 v[158:159], v[208:209], 0, s[0:1]
	v_add_u32_e32 v212, v154, v156
	v_add_u32_e32 v213, v155, v156
	v_cndmask_b32_e32 v211, v159, v143, vcc
	v_cndmask_b32_e32 v210, v158, v144, vcc
	ds_read_b128 v[158:161], v212
	ds_read_b128 v[162:165], v213 offset:16384
	ds_read_b128 v[166:169], v212 offset:2048
	ds_read_b128 v[170:173], v213 offset:18432
	ds_read_b128 v[174:177], v212 offset:4096
	ds_read_b128 v[178:181], v213 offset:20480
	ds_read_b128 v[186:189], v212 offset:6144
	ds_read_b128 v[190:193], v213 offset:22528
	s_waitcnt vmcnt(8)
	s_setprio 1
	v_add_u32_e32 v215, v154, v157
	v_add_u32_e32 v216, v155, v157
	v_add_u32_e32 v221, v152, v153
	s_waitcnt lgkmcnt(6)
	v_mfma_f32_16x16x32_bf16 v[124:127], v[162:165], v[158:161], v[124:127]
	ds_read_b128 v[194:197], v216 offset:16384
	s_waitcnt lgkmcnt(5)
	v_mfma_f32_16x16x32_bf16 v[120:123], v[170:173], v[158:161], v[120:123]
	s_waitcnt lgkmcnt(3)
	v_mfma_f32_16x16x32_bf16 v[116:119], v[178:181], v[158:161], v[116:119]
	s_waitcnt lgkmcnt(1)
	v_mfma_f32_16x16x32_bf16 v[112:115], v[190:193], v[158:161], v[112:115]
	ds_read_b128 v[158:161], v215
	ds_write_b128 v221, v[12:15] offset:32768
	global_load_dwordx4 v[12:15], v[206:207], off
	v_mfma_f32_16x16x32_bf16 v[108:111], v[162:165], v[166:169], v[108:111]
	v_mfma_f32_16x16x32_bf16 v[104:107], v[170:173], v[166:169], v[104:107]
	v_mfma_f32_16x16x32_bf16 v[100:103], v[178:181], v[166:169], v[100:103]
	v_mfma_f32_16x16x32_bf16 v[96:99], v[190:193], v[166:169], v[96:99]
	ds_read_b128 v[166:169], v215 offset:2048
	ds_read_b128 v[198:201], v216 offset:18432
	ds_write_b128 v221, v[24:27] offset:36864
	v_lshl_add_u64 v[24:25], v[206:207], 0, s[22:23]
	global_load_dwordx4 v[24:27], v[24:25], off
	s_setprio 2
	v_mfma_f32_16x16x32_bf16 v[92:95], v[162:165], v[174:177], v[92:95]
	v_mfma_f32_16x16x32_bf16 v[88:91], v[170:173], v[174:177], v[88:91]
	v_mfma_f32_16x16x32_bf16 v[84:87], v[178:181], v[174:177], v[84:87]
	v_mfma_f32_16x16x32_bf16 v[80:83], v[190:193], v[174:177], v[80:83]
	ds_read_b128 v[174:177], v215 offset:4096
	ds_read_b128 v[202:205], v216 offset:20480
	ds_write_b128 v221, v[40:43] offset:40960
	v_lshl_add_u64 v[40:41], v[206:207], 0, s[24:25]
	global_load_dwordx4 v[40:43], v[40:41], off
	v_mfma_f32_16x16x32_bf16 v[76:79], v[162:165], v[186:189], v[76:79]
	v_mfma_f32_16x16x32_bf16 v[72:75], v[170:173], v[186:189], v[72:75]
	ds_read_b128 v[162:165], v215 offset:6144
	ds_read_b128 v[170:173], v216 offset:22528
	ds_write_b128 v221, v[48:51] offset:45056
	v_lshl_add_u64 v[48:49], v[206:207], 0, s[26:27]
	v_mfma_f32_16x16x32_bf16 v[68:71], v[178:181], v[186:189], v[68:71]
	global_load_dwordx4 v[48:51], v[48:49], off
	v_mfma_f32_16x16x32_bf16 v[64:67], v[190:193], v[186:189], v[64:67]
	s_waitcnt lgkmcnt(10)
	v_mfma_f32_16x16x32_bf16 v[124:127], v[194:197], v[158:161], v[124:127]
	ds_write_b128 v221, v[16:19] offset:49152
	global_load_dwordx4 v[16:19], v[210:211], off
	s_waitcnt lgkmcnt(8)
	v_mfma_f32_16x16x32_bf16 v[120:123], v[198:201], v[158:161], v[120:123]
	s_waitcnt lgkmcnt(5)
	v_mfma_f32_16x16x32_bf16 v[116:119], v[202:205], v[158:161], v[116:119]
	s_waitcnt lgkmcnt(2)
	v_mfma_f32_16x16x32_bf16 v[112:115], v[170:173], v[158:161], v[112:115]
	s_setprio 3
	v_mfma_f32_16x16x32_bf16 v[108:111], v[194:197], v[166:169], v[108:111]
	ds_write_b128 v221, v[28:31] offset:53248
	v_lshl_add_u64 v[28:29], v[210:211], 0, s[22:23]
	global_load_dwordx4 v[28:31], v[28:29], off
	v_mfma_f32_16x16x32_bf16 v[104:107], v[198:201], v[166:169], v[104:107]
	v_mfma_f32_16x16x32_bf16 v[100:103], v[202:205], v[166:169], v[100:103]
	v_mfma_f32_16x16x32_bf16 v[96:99], v[170:173], v[166:169], v[96:99]
	v_mfma_f32_16x16x32_bf16 v[92:95], v[194:197], v[174:177], v[92:95]
	ds_write_b128 v221, v[44:47] offset:57344
	v_lshl_add_u64 v[44:45], v[210:211], 0, s[24:25]
	global_load_dwordx4 v[44:47], v[44:45], off
	v_mfma_f32_16x16x32_bf16 v[88:91], v[198:201], v[174:177], v[88:91]
	v_mfma_f32_16x16x32_bf16 v[84:87], v[202:205], v[174:177], v[84:87]
	v_mfma_f32_16x16x32_bf16 v[80:83], v[170:173], v[174:177], v[80:83]
	v_mfma_f32_16x16x32_bf16 v[76:79], v[194:197], v[162:165], v[76:79]
	ds_write_b128 v221, v[52:55] offset:61440
	v_lshl_add_u64 v[52:53], v[210:211], 0, s[26:27]
	global_load_dwordx4 v[52:55], v[52:53], off
	v_mfma_f32_16x16x32_bf16 v[72:75], v[198:201], v[162:165], v[72:75]
	v_mfma_f32_16x16x32_bf16 v[68:71], v[202:205], v[162:165], v[68:71]
	v_mfma_f32_16x16x32_bf16 v[64:67], v[170:173], v[162:165], v[64:67]
	s_cmp_lt_u32 s17, 4
	s_cselect_b64 s[0:1], -1, 0
	s_and_b64 s[4:5], s[12:13], vcc
	v_lshl_add_u64 v[158:159], v[182:183], 0, s[34:35]
	v_cndmask_b32_e64 v160, v138, v134, s[4:5]
	v_cndmask_b32_e64 v161, v139, v135, s[4:5]
	s_mov_b64 s[20:21], 0x600200
	v_cndmask_b32_e64 v183, v161, v159, s[0:1]
	v_cndmask_b32_e64 v182, v160, v158, s[0:1]
	v_lshl_add_u64 v[158:159], v[208:209], 0, s[20:21]
	v_cndmask_b32_e64 v160, v140, v136, s[4:5]
	v_cndmask_b32_e64 v161, v141, v137, s[4:5]
	s_setprio 0
	s_waitcnt lgkmcnt(0)
	s_barrier
; #define MFMA16(a, b, c) __builtin_amdgcn_mfma_f32_16x16x32_bf16((a), (b), (c), 0, 0, 0)
; DI void gld(u32x4v& r, const void* p) { asm volatile("global_load_dwordx4 %0, %1, off" : "=v"(r) : "v"(p) : "memory"); }
; #define WAIT_SET(N, a, b) asm volatile("s_waitcnt vmcnt(" #N ")" : "+v"(a[0]), "+v"(a[1]), "+v"(a[2]), "+v"(a[3]), "+v"(b[0]), "+v"(b[1]), "+v"(b[2]), "+v"(b[3]) :: "memory")
; DI void gemm_half(f32x4 (&acc)[4][4], const char* sa, const char* sb, int o0, int o1, u32x4v (&ra)[4], u32x4v (&rb)[4],
;                   char* stw, const bf16_t* Agn, const bf16_t* Bgn, int lda, int ldb) {
;   bf16x8 af0[4], bf0[4], af1[4], bf1[4];
; #pragma unroll
;   for (int i = 0; i < 4; ++i) { af0[i] = *(const bf16x8*)(sa + i * 16 * 128 + o0); bf0[i] = *(const bf16x8*)(sb + i * 16 * 128 + o0); }
;   __builtin_amdgcn_sched_barrier(0);
;   WAIT_SET(8, ra, rb);
; #pragma unroll
;   for (int g = 0; g < 8; ++g) {
; #pragma unroll
;     for (int ni = 0; ni < 4; ++ni) {
;       if (g < 4) acc[g][ni] = MFMA16(bf0[ni], af0[g], acc[g][ni]);
;       else acc[g - 4][ni] = MFMA16(bf1[ni], af1[g - 4], acc[g - 4][ni]);
;     }
;     if (g < 4) { af1[g] = *(const bf16x8*)(sa + g * 16 * 128 + o1); bf1[g] = *(const bf16x8*)(sb + g * 16 * 128 + o1);
;                  *(u32x4v*)(stw + g * 32 * 128) = ra[g]; gld(ra[g], Agn + (size_t)g * 32 * lda); }
;     else { *(u32x4v*)(stw + TILE_B + (g - 4) * 32 * 128) = rb[g - 4]; gld(rb[g - 4], Bgn + (size_t)(g - 4) * 32 * ldb); }
;     __builtin_amdgcn_sched_barrier(0);
;   }
; DI void gemm_kloop(f32x4 (&acc)[4][4], const bf16_t* Ag, const bf16_t* Bg, int lda, int ldb, int K, char* smem,
;                    u32x4v (&ra)[4], u32x4v (&rb)[4], u32x4v (&rc)[4], u32x4v (&rd)[4], bool pre,
;                    const bf16_t* Agn, const bf16_t* Bgn, bool hasnext) {
;     ...
;     const bf16_t* pa0 = kt + 4 < nk ? Ag + (size_t)(kt + 4) * 64 : ((last && hasnext) ? Agn : Alast);
;     const bf16_t* pb0 = kt + 4 < nk ? Bg + (size_t)(kt + 4) * 64 : ((last && hasnext) ? Bgn : Blast);
;     gemm_half(acc, sa0 + 2 * TILE_B, sb0 + 2 * TILE_B, o0, o1, ra, rb, st, pa0, pb0, lda, ldb);
;     __syncthreads();
;   }
;   if (!hasnext) { WAIT_SET(0, ra, rb); WAIT_SET(0, rc, rd); }
	v_cndmask_b32_e64 v207, v161, v159, s[0:1]
	v_cndmask_b32_e64 v206, v160, v158, s[0:1]
	ds_read_b128 v[158:161], v212 offset:32768
	ds_read_b128 v[162:165], v213 offset:49152
	ds_read_b128 v[166:169], v212 offset:34816
	ds_read_b128 v[170:173], v213 offset:51200
	ds_read_b128 v[174:177], v212 offset:36864
	ds_read_b128 v[178:181], v213 offset:53248
	ds_read_b128 v[186:189], v212 offset:38912
	ds_read_b128 v[190:193], v213 offset:55296
	s_waitcnt vmcnt(8)
	s_setprio 1
	s_waitcnt lgkmcnt(6)
	v_mfma_f32_16x16x32_bf16 v[124:127], v[162:165], v[158:161], v[124:127]
	s_waitcnt lgkmcnt(4)
	v_mfma_f32_16x16x32_bf16 v[120:123], v[170:173], v[158:161], v[120:123]
	s_waitcnt lgkmcnt(2)
	v_mfma_f32_16x16x32_bf16 v[116:119], v[178:181], v[158:161], v[116:119]
	s_waitcnt lgkmcnt(0)
	v_mfma_f32_16x16x32_bf16 v[112:115], v[190:193], v[158:161], v[112:115]
	ds_read_b128 v[158:161], v215 offset:32768
	ds_read_b128 v[194:197], v216 offset:49152
	ds_write_b128 v221, v[0:3]
	global_load_dwordx4 v[0:3], v[182:183], off
	v_mfma_f32_16x16x32_bf16 v[108:111], v[162:165], v[166:169], v[108:111]
	v_mfma_f32_16x16x32_bf16 v[104:107], v[170:173], v[166:169], v[104:107]
	v_mfma_f32_16x16x32_bf16 v[100:103], v[178:181], v[166:169], v[100:103]
	v_mfma_f32_16x16x32_bf16 v[96:99], v[190:193], v[166:169], v[96:99]
	ds_read_b128 v[166:169], v215 offset:34816
	ds_read_b128 v[198:201], v216 offset:51200
	ds_write_b128 v221, v[8:11] offset:4096
	v_lshl_add_u64 v[8:9], v[182:183], 0, s[22:23]
	global_load_dwordx4 v[8:11], v[8:9], off
	s_setprio 2
	v_mfma_f32_16x16x32_bf16 v[92:95], v[162:165], v[174:177], v[92:95]
	v_mfma_f32_16x16x32_bf16 v[88:91], v[170:173], v[174:177], v[88:91]
	v_mfma_f32_16x16x32_bf16 v[84:87], v[178:181], v[174:177], v[84:87]
	v_mfma_f32_16x16x32_bf16 v[80:83], v[190:193], v[174:177], v[80:83]
	ds_read_b128 v[174:177], v215 offset:36864
	ds_read_b128 v[202:205], v216 offset:53248
	ds_write_b128 v221, v[32:35] offset:8192
	v_lshl_add_u64 v[32:33], v[182:183], 0, s[24:25]
	global_load_dwordx4 v[32:35], v[32:33], off
	v_mfma_f32_16x16x32_bf16 v[76:79], v[162:165], v[186:189], v[76:79]
	v_mfma_f32_16x16x32_bf16 v[72:75], v[170:173], v[186:189], v[72:75]
	ds_read_b128 v[162:165], v215 offset:38912
	ds_read_b128 v[170:173], v216 offset:55296
	ds_write_b128 v221, v[56:59] offset:12288
	v_lshl_add_u64 v[56:57], v[182:183], 0, s[26:27]
	v_mfma_f32_16x16x32_bf16 v[68:71], v[178:181], v[186:189], v[68:71]
	global_load_dwordx4 v[56:59], v[56:57], off
	v_mfma_f32_16x16x32_bf16 v[64:67], v[190:193], v[186:189], v[64:67]
	s_waitcnt lgkmcnt(10)
	v_mfma_f32_16x16x32_bf16 v[124:127], v[194:197], v[158:161], v[124:127]
	ds_write_b128 v221, v[4:7] offset:16384
	global_load_dwordx4 v[4:7], v[206:207], off
	s_waitcnt lgkmcnt(8)
	v_mfma_f32_16x16x32_bf16 v[120:123], v[198:201], v[158:161], v[120:123]
	s_waitcnt lgkmcnt(5)
	v_mfma_f32_16x16x32_bf16 v[116:119], v[202:205], v[158:161], v[116:119]
	s_waitcnt lgkmcnt(2)
	v_mfma_f32_16x16x32_bf16 v[112:115], v[170:173], v[158:161], v[112:115]
	s_setprio 3
	v_mfma_f32_16x16x32_bf16 v[108:111], v[194:197], v[166:169], v[108:111]
	ds_write_b128 v221, v[20:23] offset:20480
	v_lshl_add_u64 v[20:21], v[206:207], 0, s[22:23]
	global_load_dwordx4 v[20:23], v[20:21], off
	v_mfma_f32_16x16x32_bf16 v[104:107], v[198:201], v[166:169], v[104:107]
	v_mfma_f32_16x16x32_bf16 v[100:103], v[202:205], v[166:169], v[100:103]
	v_mfma_f32_16x16x32_bf16 v[96:99], v[170:173], v[166:169], v[96:99]
	v_mfma_f32_16x16x32_bf16 v[92:95], v[194:197], v[174:177], v[92:95]
	ds_write_b128 v221, v[36:39] offset:24576
	v_lshl_add_u64 v[36:37], v[206:207], 0, s[24:25]
	global_load_dwordx4 v[36:39], v[36:37], off
	v_mfma_f32_16x16x32_bf16 v[88:91], v[198:201], v[174:177], v[88:91]
	v_mfma_f32_16x16x32_bf16 v[84:87], v[202:205], v[174:177], v[84:87]
	v_mfma_f32_16x16x32_bf16 v[80:83], v[170:173], v[174:177], v[80:83]
	v_mfma_f32_16x16x32_bf16 v[76:79], v[194:197], v[162:165], v[76:79]
	ds_write_b128 v221, v[60:63] offset:28672
	v_lshl_add_u64 v[60:61], v[206:207], 0, s[26:27]
	global_load_dwordx4 v[60:63], v[60:61], off
	v_mfma_f32_16x16x32_bf16 v[72:75], v[198:201], v[162:165], v[72:75]
	v_mfma_f32_16x16x32_bf16 v[68:71], v[202:205], v[162:165], v[68:71]
	v_mfma_f32_16x16x32_bf16 v[64:67], v[170:173], v[162:165], v[64:67]
	v_lshl_add_u64 v[146:147], v[146:147], 0, s[28:29]
	v_lshl_add_u64 v[148:149], v[148:149], 0, s[28:29]
	s_and_b64 vcc, exec, vcc
	s_setprio 0
	s_waitcnt lgkmcnt(0)
	s_barrier
	s_cbranch_vccz .LBB0_220
	s_and_b64 vcc, exec, s[10:11]
	s_cbranch_vccz .LBB0_209
	s_waitcnt vmcnt(0)
	s_waitcnt vmcnt(0)
	s_branch .LBB0_209

; #define MFMA16(a, b, c) __builtin_amdgcn_mfma_f32_16x16x32_bf16((a), (b), (c), 0, 0, 0)
; DI void gld(u32x4v& r, const void* p) { asm volatile("global_load_dwordx4 %0, %1, off" : "=v"(r) : "v"(p) : "memory"); }
; #define WAIT_SET(N, a, b) asm volatile("s_waitcnt vmcnt(" #N ")" : "+v"(a[0]), "+v"(a[1]), "+v"(a[2]), "+v"(a[3]), "+v"(b[0]), "+v"(b[1]), "+v"(b[2]), "+v"(b[3]) :: "memory")
; DI void gemm_half(f32x4 (&acc)[4][4], const char* sa, const char* sb, int o0, int o1, u32x4v (&ra)[4], u32x4v (&rb)[4],
;                   char* stw, const bf16_t* Agn, const bf16_t* Bgn, int lda, int ldb) {
;   bf16x8 af0[4], bf0[4], af1[4], bf1[4];
; #pragma unroll
;   for (int i = 0; i < 4; ++i) { af0[i] = *(const bf16x8*)(sa + i * 16 * 128 + o0); bf0[i] = *(const bf16x8*)(sb + i * 16 * 128 + o0); }
;   __builtin_amdgcn_sched_barrier(0);
;   WAIT_SET(8, ra, rb);
; #pragma unroll
;   for (int g = 0; g < 8; ++g) {
; #pragma unroll
;     for (int ni = 0; ni < 4; ++ni) {
;       if (g < 4) acc[g][ni] = MFMA16(bf0[ni], af0[g], acc[g][ni]);
;       else acc[g - 4][ni] = MFMA16(bf1[ni], af1[g - 4], acc[g - 4][ni]);
;     }
;     if (g < 4) { af1[g] = *(const bf16x8*)(sa + g * 16 * 128 + o1); bf1[g] = *(const bf16x8*)(sb + g * 16 * 128 + o1);
;                  *(u32x4v*)(stw + g * 32 * 128) = ra[g]; gld(ra[g], Agn + (size_t)g * 32 * lda); }
;     else { *(u32x4v*)(stw + TILE_B + (g - 4) * 32 * 128) = rb[g - 4]; gld(rb[g - 4], Bgn + (size_t)(g - 4) * 32 * ldb); }
;     __builtin_amdgcn_sched_barrier(0);
;   }
; DI void gemm_kloop(f32x4 (&acc)[4][4], const bf16_t* Ag, const bf16_t* Bg, int lda, int ldb, int K, char* smem,
;                    u32x4v (&ra)[4], u32x4v (&rb)[4], u32x4v (&rc)[4], u32x4v (&rd)[4], bool pre,
;                    const bf16_t* Agn, const bf16_t* Bgn, bool hasnext) {
;     ...
;   for (int kt = 0; kt < nk; kt += 2) {
;     const bool last = kt + 2 >= nk;
;     const bf16_t* pa1 = last ? (hasnext ? Agn + 64 : Alast) : Ag + (size_t)(kt + 3) * 64;
;     const bf16_t* pb1 = last ? (hasnext ? Bgn + 64 : Blast) : Bg + (size_t)(kt + 3) * 64;
;     gemm_half(acc, sa0, sb0, o0, o1, rc, rd, st + 2 * TILE_B, pa1, pb1, lda, ldb);
;     __syncthreads();
;     const bf16_t* pa0 = kt + 4 < nk ? Ag + (size_t)(kt + 4) * 64 : ((last && hasnext) ? Agn : Alast);
;     const bf16_t* pb0 = kt + 4 < nk ? Bg + (size_t)(kt + 4) * 64 : ((last && hasnext) ? Bgn : Blast);
.LBB0_280:
	s_add_i32 s2, s2, 2
	s_cmp_gt_u32 s2, 29
	v_lshl_add_u64 v[206:207], v[146:147], 0, v[132:133]
	s_cselect_b64 vcc, -1, 0
	v_lshl_add_u64 v[160:161], v[206:207], 0, s[26:27]
	v_lshl_add_u64 v[210:211], v[148:149], 0, v[132:133]
	v_cndmask_b32_e32 v209, v161, v143, vcc
	v_cndmask_b32_e32 v208, v160, v142, vcc
	v_lshl_add_u64 v[160:161], v[210:211], 0, s[30:31]
	v_add_u32_e32 v159, v155, v157
	v_add_u32_e32 v215, v156, v157
	v_cndmask_b32_e32 v213, v161, v145, vcc
	v_cndmask_b32_e32 v212, v160, v144, vcc
	ds_read_b128 v[160:163], v159
	ds_read_b128 v[164:167], v215 offset:16384
	ds_read_b128 v[168:171], v159 offset:2048
	ds_read_b128 v[172:175], v215 offset:18432
	ds_read_b128 v[176:179], v159 offset:4096
	ds_read_b128 v[180:183], v215 offset:20480
	ds_read_b128 v[186:189], v159 offset:6144
	ds_read_b128 v[190:193], v215 offset:22528
	s_waitcnt vmcnt(8)
	s_setprio 1
	v_add_u32_e32 v216, v155, v158
	v_add_u32_e32 v221, v156, v158
	v_add_u32_e32 v224, v153, v154
	s_waitcnt lgkmcnt(6)
	v_mfma_f32_16x16x32_bf16 v[124:127], v[164:167], v[160:163], v[124:127]
	ds_read_b128 v[194:197], v221 offset:16384
	s_waitcnt lgkmcnt(5)
	v_mfma_f32_16x16x32_bf16 v[120:123], v[172:175], v[160:163], v[120:123]
	s_waitcnt lgkmcnt(3)
	v_mfma_f32_16x16x32_bf16 v[116:119], v[180:183], v[160:163], v[116:119]
	s_waitcnt lgkmcnt(1)
	v_mfma_f32_16x16x32_bf16 v[112:115], v[190:193], v[160:163], v[112:115]
	ds_read_b128 v[160:163], v216
	ds_write_b128 v224, v[12:15] offset:32768
	global_load_dwordx4 v[12:15], v[208:209], off
	v_mfma_f32_16x16x32_bf16 v[108:111], v[164:167], v[168:171], v[108:111]
	v_mfma_f32_16x16x32_bf16 v[104:107], v[172:175], v[168:171], v[104:107]
	v_mfma_f32_16x16x32_bf16 v[100:103], v[180:183], v[168:171], v[100:103]
	v_mfma_f32_16x16x32_bf16 v[96:99], v[190:193], v[168:171], v[96:99]
	ds_read_b128 v[168:171], v216 offset:2048
	ds_read_b128 v[198:201], v221 offset:18432
	ds_write_b128 v224, v[24:27] offset:36864
	v_lshl_add_u64 v[24:25], v[208:209], 0, s[20:21]
	global_load_dwordx4 v[24:27], v[24:25], off
	s_setprio 2
	v_mfma_f32_16x16x32_bf16 v[92:95], v[164:167], v[176:179], v[92:95]
	v_mfma_f32_16x16x32_bf16 v[88:91], v[172:175], v[176:179], v[88:91]
	v_mfma_f32_16x16x32_bf16 v[84:87], v[180:183], v[176:179], v[84:87]
	v_mfma_f32_16x16x32_bf16 v[80:83], v[190:193], v[176:179], v[80:83]
	ds_read_b128 v[176:179], v216 offset:4096
	ds_read_b128 v[202:205], v221 offset:20480
	ds_write_b128 v224, v[40:43] offset:40960
	v_lshl_add_u64 v[40:41], v[208:209], 0, s[22:23]
	global_load_dwordx4 v[40:43], v[40:41], off
	v_mfma_f32_16x16x32_bf16 v[76:79], v[164:167], v[186:189], v[76:79]
	v_mfma_f32_16x16x32_bf16 v[72:75], v[172:175], v[186:189], v[72:75]
	ds_read_b128 v[164:167], v216 offset:6144
	ds_read_b128 v[172:175], v221 offset:22528
	ds_write_b128 v224, v[48:51] offset:45056
	v_lshl_add_u64 v[48:49], v[208:209], 0, s[24:25]
	v_mfma_f32_16x16x32_bf16 v[68:71], v[180:183], v[186:189], v[68:71]
	global_load_dwordx4 v[48:51], v[48:49], off
	v_mfma_f32_16x16x32_bf16 v[64:67], v[190:193], v[186:189], v[64:67]
	s_waitcnt lgkmcnt(10)
	v_mfma_f32_16x16x32_bf16 v[124:127], v[194:197], v[160:163], v[124:127]
	ds_write_b128 v224, v[16:19] offset:49152
	global_load_dwordx4 v[16:19], v[212:213], off
	s_waitcnt lgkmcnt(8)
	v_mfma_f32_16x16x32_bf16 v[120:123], v[198:201], v[160:163], v[120:123]
	s_waitcnt lgkmcnt(5)
	v_mfma_f32_16x16x32_bf16 v[116:119], v[202:205], v[160:163], v[116:119]
	s_waitcnt lgkmcnt(2)
	v_mfma_f32_16x16x32_bf16 v[112:115], v[172:175], v[160:163], v[112:115]
	s_setprio 3
	v_mfma_f32_16x16x32_bf16 v[108:111], v[194:197], v[168:171], v[108:111]
	ds_write_b128 v224, v[28:31] offset:53248
	v_lshl_add_u64 v[28:29], v[212:213], 0, s[20:21]
	global_load_dwordx4 v[28:31], v[28:29], off
	v_mfma_f32_16x16x32_bf16 v[104:107], v[198:201], v[168:171], v[104:107]
	v_mfma_f32_16x16x32_bf16 v[100:103], v[202:205], v[168:171], v[100:103]
	v_mfma_f32_16x16x32_bf16 v[96:99], v[172:175], v[168:171], v[96:99]
	v_mfma_f32_16x16x32_bf16 v[92:95], v[194:197], v[176:179], v[92:95]
	ds_write_b128 v224, v[44:47] offset:57344
	v_lshl_add_u64 v[44:45], v[212:213], 0, s[22:23]
	global_load_dwordx4 v[44:47], v[44:45], off
	v_mfma_f32_16x16x32_bf16 v[88:91], v[198:201], v[176:179], v[88:91]
	v_mfma_f32_16x16x32_bf16 v[84:87], v[202:205], v[176:179], v[84:87]
	v_mfma_f32_16x16x32_bf16 v[80:83], v[172:175], v[176:179], v[80:83]
	v_mfma_f32_16x16x32_bf16 v[76:79], v[194:197], v[164:167], v[76:79]
	ds_write_b128 v224, v[52:55] offset:61440
	v_lshl_add_u64 v[52:53], v[212:213], 0, s[24:25]
	global_load_dwordx4 v[52:55], v[52:53], off
	v_mfma_f32_16x16x32_bf16 v[72:75], v[198:201], v[164:167], v[72:75]
	v_mfma_f32_16x16x32_bf16 v[68:71], v[202:205], v[164:167], v[68:71]
	v_mfma_f32_16x16x32_bf16 v[64:67], v[172:175], v[164:167], v[64:67]
	s_cmp_lt_u32 s2, 28
	s_cselect_b64 s[4:5], -1, 0
	s_and_b64 s[6:7], s[0:1], vcc
	v_lshl_add_u64 v[160:161], v[206:207], 0, s[34:35]
	v_cndmask_b32_e64 v162, v138, v134, s[6:7]
	v_cndmask_b32_e64 v163, v139, v135, s[6:7]
	v_cndmask_b32_e64 v207, v163, v161, s[4:5]
	v_cndmask_b32_e64 v206, v162, v160, s[4:5]
	v_lshl_add_u64 v[160:161], v[210:211], 0, s[36:37]
	v_cndmask_b32_e64 v162, v140, v136, s[6:7]
	v_cndmask_b32_e64 v163, v141, v137, s[6:7]
	s_setprio 0
	s_waitcnt lgkmcnt(0)
	s_barrier
; #define MFMA16(a, b, c) __builtin_amdgcn_mfma_f32_16x16x32_bf16((a), (b), (c), 0, 0, 0)
; DI void gld(u32x4v& r, const void* p) { asm volatile("global_load_dwordx4 %0, %1, off" : "=v"(r) : "v"(p) : "memory"); }
; #define WAIT_SET(N, a, b) asm volatile("s_waitcnt vmcnt(" #N ")" : "+v"(a[0]), "+v"(a[1]), "+v"(a[2]), "+v"(a[3]), "+v"(b[0]), "+v"(b[1]), "+v"(b[2]), "+v"(b[3]) :: "memory")
; DI void gemm_half(f32x4 (&acc)[4][4], const char* sa, const char* sb, int o0, int o1, u32x4v (&ra)[4], u32x4v (&rb)[4],
;                   char* stw, const bf16_t* Agn, const bf16_t* Bgn, int lda, int ldb) {
;   bf16x8 af0[4], bf0[4], af1[4], bf1[4];
; #pragma unroll
;   for (int i = 0; i < 4; ++i) { af0[i] = *(const bf16x8*)(sa + i * 16 * 128 + o0); bf0[i] = *(const bf16x8*)(sb + i * 16 * 128 + o0); }
;   __builtin_amdgcn_sched_barrier(0);
;   WAIT_SET(8, ra, rb);
; #pragma unroll
;   for (int g = 0; g < 8; ++g) {
; #pragma unroll
;     for (int ni = 0; ni < 4; ++ni) {
;       if (g < 4) acc[g][ni] = MFMA16(bf0[ni], af0[g], acc[g][ni]);
;       else acc[g - 4][ni] = MFMA16(bf1[ni], af1[g - 4], acc[g - 4][ni]);
;     }
;     if (g < 4) { af1[g] = *(const bf16x8*)(sa + g * 16 * 128 + o1); bf1[g] = *(const bf16x8*)(sb + g * 16 * 128 + o1);
;                  *(u32x4v*)(stw + g * 32 * 128) = ra[g]; gld(ra[g], Agn + (size_t)g * 32 * lda); }
;     else { *(u32x4v*)(stw + TILE_B + (g - 4) * 32 * 128) = rb[g - 4]; gld(rb[g - 4], Bgn + (size_t)(g - 4) * 32 * ldb); }
;     __builtin_amdgcn_sched_barrier(0);
;   }
; DI void gemm_kloop(f32x4 (&acc)[4][4], const bf16_t* Ag, const bf16_t* Bg, int lda, int ldb, int K, char* smem,
;                    u32x4v (&ra)[4], u32x4v (&rb)[4], u32x4v (&rc)[4], u32x4v (&rd)[4], bool pre,
;                    const bf16_t* Agn, const bf16_t* Bgn, bool hasnext) {
;     ...
;     const bf16_t* pa0 = kt + 4 < nk ? Ag + (size_t)(kt + 4) * 64 : ((last && hasnext) ? Agn : Alast);
;     const bf16_t* pb0 = kt + 4 < nk ? Bg + (size_t)(kt + 4) * 64 : ((last && hasnext) ? Bgn : Blast);
;     gemm_half(acc, sa0 + 2 * TILE_B, sb0 + 2 * TILE_B, o0, o1, ra, rb, st, pa0, pb0, lda, ldb);
;     __syncthreads();
;   }
;   if (!hasnext) { WAIT_SET(0, ra, rb); WAIT_SET(0, rc, rd); }
	v_cndmask_b32_e64 v209, v163, v161, s[4:5]
	v_cndmask_b32_e64 v208, v162, v160, s[4:5]
	ds_read_b128 v[160:163], v159 offset:32768
	ds_read_b128 v[164:167], v215 offset:49152
	ds_read_b128 v[168:171], v159 offset:34816
	ds_read_b128 v[172:175], v215 offset:51200
	ds_read_b128 v[176:179], v159 offset:36864
	ds_read_b128 v[180:183], v215 offset:53248
	ds_read_b128 v[186:189], v159 offset:38912
	ds_read_b128 v[190:193], v215 offset:55296
	s_waitcnt vmcnt(8)
	s_setprio 1
	s_waitcnt lgkmcnt(6)
	v_mfma_f32_16x16x32_bf16 v[124:127], v[164:167], v[160:163], v[124:127]
	s_waitcnt lgkmcnt(4)
	v_mfma_f32_16x16x32_bf16 v[120:123], v[172:175], v[160:163], v[120:123]
	s_waitcnt lgkmcnt(2)
	v_mfma_f32_16x16x32_bf16 v[116:119], v[180:183], v[160:163], v[116:119]
	s_waitcnt lgkmcnt(0)
	v_mfma_f32_16x16x32_bf16 v[112:115], v[190:193], v[160:163], v[112:115]
	ds_read_b128 v[160:163], v216 offset:32768
	ds_read_b128 v[194:197], v221 offset:49152
	ds_write_b128 v224, v[0:3]
	global_load_dwordx4 v[0:3], v[206:207], off
	v_mfma_f32_16x16x32_bf16 v[108:111], v[164:167], v[168:171], v[108:111]
	v_mfma_f32_16x16x32_bf16 v[104:107], v[172:175], v[168:171], v[104:107]
	v_mfma_f32_16x16x32_bf16 v[100:103], v[180:183], v[168:171], v[100:103]
	v_mfma_f32_16x16x32_bf16 v[96:99], v[190:193], v[168:171], v[96:99]
	ds_read_b128 v[168:171], v216 offset:34816
	ds_read_b128 v[198:201], v221 offset:51200
	ds_write_b128 v224, v[8:11] offset:4096
	v_lshl_add_u64 v[8:9], v[206:207], 0, s[20:21]
	global_load_dwordx4 v[8:11], v[8:9], off
	s_setprio 2
	v_mfma_f32_16x16x32_bf16 v[92:95], v[164:167], v[176:179], v[92:95]
	v_mfma_f32_16x16x32_bf16 v[88:91], v[172:175], v[176:179], v[88:91]
	v_mfma_f32_16x16x32_bf16 v[84:87], v[180:183], v[176:179], v[84:87]
	v_mfma_f32_16x16x32_bf16 v[80:83], v[190:193], v[176:179], v[80:83]
	ds_read_b128 v[176:179], v216 offset:36864
	ds_read_b128 v[202:205], v221 offset:53248
	ds_write_b128 v224, v[32:35] offset:8192
	v_lshl_add_u64 v[32:33], v[206:207], 0, s[22:23]
	global_load_dwordx4 v[32:35], v[32:33], off
	v_mfma_f32_16x16x32_bf16 v[76:79], v[164:167], v[186:189], v[76:79]
	v_mfma_f32_16x16x32_bf16 v[72:75], v[172:175], v[186:189], v[72:75]
	ds_read_b128 v[164:167], v216 offset:38912
	ds_read_b128 v[172:175], v221 offset:55296
	ds_write_b128 v224, v[56:59] offset:12288
	v_lshl_add_u64 v[56:57], v[206:207], 0, s[24:25]
	v_mfma_f32_16x16x32_bf16 v[68:71], v[180:183], v[186:189], v[68:71]
	global_load_dwordx4 v[56:59], v[56:57], off
	v_mfma_f32_16x16x32_bf16 v[64:67], v[190:193], v[186:189], v[64:67]
	s_waitcnt lgkmcnt(10)
	v_mfma_f32_16x16x32_bf16 v[124:127], v[194:197], v[160:163], v[124:127]
	ds_write_b128 v224, v[4:7] offset:16384
	global_load_dwordx4 v[4:7], v[208:209], off
	s_waitcnt lgkmcnt(8)
	v_mfma_f32_16x16x32_bf16 v[120:123], v[198:201], v[160:163], v[120:123]
	s_waitcnt lgkmcnt(5)
	v_mfma_f32_16x16x32_bf16 v[116:119], v[202:205], v[160:163], v[116:119]
	s_waitcnt lgkmcnt(2)
	v_mfma_f32_16x16x32_bf16 v[112:115], v[172:175], v[160:163], v[112:115]
	s_setprio 3
	v_mfma_f32_16x16x32_bf16 v[108:111], v[194:197], v[168:171], v[108:111]
	ds_write_b128 v224, v[20:23] offset:20480
	v_lshl_add_u64 v[20:21], v[208:209], 0, s[20:21]
	global_load_dwordx4 v[20:23], v[20:21], off
	v_mfma_f32_16x16x32_bf16 v[104:107], v[198:201], v[168:171], v[104:107]
	v_mfma_f32_16x16x32_bf16 v[100:103], v[202:205], v[168:171], v[100:103]
	v_mfma_f32_16x16x32_bf16 v[96:99], v[172:175], v[168:171], v[96:99]
	v_mfma_f32_16x16x32_bf16 v[92:95], v[194:197], v[176:179], v[92:95]
	ds_write_b128 v224, v[36:39] offset:24576
	v_lshl_add_u64 v[36:37], v[208:209], 0, s[22:23]
	global_load_dwordx4 v[36:39], v[36:37], off
	v_mfma_f32_16x16x32_bf16 v[88:91], v[198:201], v[176:179], v[88:91]
	v_mfma_f32_16x16x32_bf16 v[84:87], v[202:205], v[176:179], v[84:87]
	v_mfma_f32_16x16x32_bf16 v[80:83], v[172:175], v[176:179], v[80:83]
	v_mfma_f32_16x16x32_bf16 v[76:79], v[194:197], v[164:167], v[76:79]
	ds_write_b128 v224, v[60:63] offset:28672
	v_lshl_add_u64 v[60:61], v[208:209], 0, s[24:25]
	global_load_dwordx4 v[60:63], v[60:61], off
	v_mfma_f32_16x16x32_bf16 v[72:75], v[198:201], v[164:167], v[72:75]
	v_mfma_f32_16x16x32_bf16 v[68:71], v[202:205], v[164:167], v[68:71]
	v_mfma_f32_16x16x32_bf16 v[64:67], v[172:175], v[164:167], v[64:67]
	v_lshl_add_u64 v[146:147], v[146:147], 0, s[28:29]
	v_lshl_add_u64 v[148:149], v[148:149], 0, s[28:29]
	s_and_b64 vcc, exec, vcc
	s_setprio 0
	s_waitcnt lgkmcnt(0)
	s_barrier
	s_cbranch_vccz .LBB0_280
	s_and_b64 vcc, exec, s[10:11]
	s_cbranch_vccz .LBB0_274
	s_waitcnt vmcnt(0)
	s_waitcnt vmcnt(0)
	s_branch .LBB0_274

; #define MFMA16(a, b, c) __builtin_amdgcn_mfma_f32_16x16x32_bf16((a), (b), (c), 0, 0, 0)
; DI void gld(u32x4v& r, const void* p) { asm volatile("global_load_dwordx4 %0, %1, off" : "=v"(r) : "v"(p) : "memory"); }
; #define WAIT_SET(N, a, b) asm volatile("s_waitcnt vmcnt(" #N ")" : "+v"(a[0]), "+v"(a[1]), "+v"(a[2]), "+v"(a[3]), "+v"(b[0]), "+v"(b[1]), "+v"(b[2]), "+v"(b[3]) :: "memory")
; DI void gemm_half(f32x4 (&acc)[4][4], const char* sa, const char* sb, int o0, int o1, u32x4v (&ra)[4], u32x4v (&rb)[4],
;                   char* stw, const bf16_t* Agn, const bf16_t* Bgn, int lda, int ldb) {
;   bf16x8 af0[4], bf0[4], af1[4], bf1[4];
; #pragma unroll
;   for (int i = 0; i < 4; ++i) { af0[i] = *(const bf16x8*)(sa + i * 16 * 128 + o0); bf0[i] = *(const bf16x8*)(sb + i * 16 * 128 + o0); }
;   __builtin_amdgcn_sched_barrier(0);
;   WAIT_SET(8, ra, rb);
; #pragma unroll
;   for (int g = 0; g < 8; ++g) {
; #pragma unroll
;     for (int ni = 0; ni < 4; ++ni) {
;       if (g < 4) acc[g][ni] = MFMA16(bf0[ni], af0[g], acc[g][ni]);
;       else acc[g - 4][ni] = MFMA16(bf1[ni], af1[g - 4], acc[g - 4][ni]);
;     }
;     if (g < 4) { af1[g] = *(const bf16x8*)(sa + g * 16 * 128 + o1); bf1[g] = *(const bf16x8*)(sb + g * 16 * 128 + o1);
;                  *(u32x4v*)(stw + g * 32 * 128) = ra[g]; gld(ra[g], Agn + (size_t)g * 32 * lda); }
;     else { *(u32x4v*)(stw + TILE_B + (g - 4) * 32 * 128) = rb[g - 4]; gld(rb[g - 4], Bgn + (size_t)(g - 4) * 32 * ldb); }
;     __builtin_amdgcn_sched_barrier(0);
;   }
; DI void gemm_kloop(f32x4 (&acc)[4][4], const bf16_t* Ag, const bf16_t* Bg, int lda, int ldb, int K, char* smem,
;                    u32x4v (&ra)[4], u32x4v (&rb)[4], u32x4v (&rc)[4], u32x4v (&rd)[4], bool pre,
;                    const bf16_t* Agn, const bf16_t* Bgn, bool hasnext) {
;     ...
;   for (int kt = 0; kt < nk; kt += 2) {
;     const bool last = kt + 2 >= nk;
;     const bf16_t* pa1 = last ? (hasnext ? Agn + 64 : Alast) : Ag + (size_t)(kt + 3) * 64;
;     const bf16_t* pb1 = last ? (hasnext ? Bgn + 64 : Blast) : Bg + (size_t)(kt + 3) * 64;
;     gemm_half(acc, sa0, sb0, o0, o1, rc, rd, st + 2 * TILE_B, pa1, pb1, lda, ldb);
;     __syncthreads();
;     const bf16_t* pa0 = kt + 4 < nk ? Ag + (size_t)(kt + 4) * 64 : ((last && hasnext) ? Agn : Alast);
;     const bf16_t* pb0 = kt + 4 < nk ? Bg + (size_t)(kt + 4) * 64 : ((last && hasnext) ? Bgn : Blast);
.LBB0_291:
	s_add_i32 s2, s2, 2
	s_cmp_gt_u32 s2, 29
	v_lshl_add_u64 v[210:211], v[148:149], 0, v[134:135]
	s_mov_b64 s[4:5], 0x39c00180
	s_cselect_b64 vcc, -1, 0
	v_lshl_add_u64 v[164:165], v[210:211], 0, s[4:5]
	v_lshl_add_u64 v[226:227], v[150:151], 0, v[134:135]
	s_mov_b64 s[4:5], 0x200180
	v_cndmask_b32_e32 v213, v165, v145, vcc
	v_cndmask_b32_e32 v212, v164, v144, vcc
	v_lshl_add_u64 v[164:165], v[226:227], 0, s[4:5]
	v_add_u32_e32 v163, v159, v161
	v_add_u32_e32 v215, v160, v161
	v_cndmask_b32_e32 v229, v165, v147, vcc
	v_cndmask_b32_e32 v228, v164, v146, vcc
	ds_read_b128 v[164:167], v163
	ds_read_b128 v[168:171], v215 offset:16384
	ds_read_b128 v[172:175], v163 offset:2048
	ds_read_b128 v[176:179], v215 offset:18432
	ds_read_b128 v[180:183], v163 offset:4096
	ds_read_b128 v[186:189], v215 offset:20480
	ds_read_b128 v[190:193], v163 offset:6144
	ds_read_b128 v[194:197], v215 offset:22528
	s_waitcnt vmcnt(8)
	s_setprio 1
	v_add_u32_e32 v216, v159, v162
	v_add_u32_e32 v221, v160, v162
	v_add_u32_e32 v224, v157, v158
	s_waitcnt lgkmcnt(6)
	v_mfma_f32_16x16x32_bf16 v[124:127], v[168:171], v[164:167], v[124:127]
	ds_read_b128 v[198:201], v221 offset:16384
	s_waitcnt lgkmcnt(5)
	v_mfma_f32_16x16x32_bf16 v[120:123], v[176:179], v[164:167], v[120:123]
	s_waitcnt lgkmcnt(3)
	v_mfma_f32_16x16x32_bf16 v[116:119], v[186:189], v[164:167], v[116:119]
	s_waitcnt lgkmcnt(1)
	v_mfma_f32_16x16x32_bf16 v[112:115], v[194:197], v[164:167], v[112:115]
	ds_read_b128 v[164:167], v216
	ds_write_b128 v224, v[12:15] offset:32768
	global_load_dwordx4 v[12:15], v[212:213], off
	v_mfma_f32_16x16x32_bf16 v[108:111], v[168:171], v[172:175], v[108:111]
	v_mfma_f32_16x16x32_bf16 v[104:107], v[176:179], v[172:175], v[104:107]
	v_mfma_f32_16x16x32_bf16 v[100:103], v[186:189], v[172:175], v[100:103]
	v_mfma_f32_16x16x32_bf16 v[96:99], v[194:197], v[172:175], v[96:99]
	ds_read_b128 v[172:175], v216 offset:2048
	ds_read_b128 v[202:205], v221 offset:18432
	ds_write_b128 v224, v[24:27] offset:36864
	v_lshl_add_u64 v[24:25], v[212:213], 0, s[22:23]
	global_load_dwordx4 v[24:27], v[24:25], off
	s_setprio 2
	v_mfma_f32_16x16x32_bf16 v[92:95], v[168:171], v[180:183], v[92:95]
	v_mfma_f32_16x16x32_bf16 v[88:91], v[176:179], v[180:183], v[88:91]
	v_mfma_f32_16x16x32_bf16 v[84:87], v[186:189], v[180:183], v[84:87]
	v_mfma_f32_16x16x32_bf16 v[80:83], v[194:197], v[180:183], v[80:83]
	ds_read_b128 v[180:183], v216 offset:4096
	ds_read_b128 v[206:209], v221 offset:20480
	ds_write_b128 v224, v[40:43] offset:40960
	v_lshl_add_u64 v[40:41], v[212:213], 0, s[24:25]
	global_load_dwordx4 v[40:43], v[40:41], off
	v_mfma_f32_16x16x32_bf16 v[76:79], v[168:171], v[190:193], v[76:79]
	v_mfma_f32_16x16x32_bf16 v[72:75], v[176:179], v[190:193], v[72:75]
	ds_read_b128 v[168:171], v216 offset:6144
	ds_read_b128 v[176:179], v221 offset:22528
	ds_write_b128 v224, v[48:51] offset:45056
	v_lshl_add_u64 v[48:49], v[212:213], 0, s[26:27]
	v_mfma_f32_16x16x32_bf16 v[68:71], v[186:189], v[190:193], v[68:71]
	global_load_dwordx4 v[48:51], v[48:49], off
	v_mfma_f32_16x16x32_bf16 v[64:67], v[194:197], v[190:193], v[64:67]
	s_waitcnt lgkmcnt(10)
	v_mfma_f32_16x16x32_bf16 v[124:127], v[198:201], v[164:167], v[124:127]
	ds_write_b128 v224, v[16:19] offset:49152
	global_load_dwordx4 v[16:19], v[228:229], off
	s_waitcnt lgkmcnt(8)
	v_mfma_f32_16x16x32_bf16 v[120:123], v[202:205], v[164:167], v[120:123]
	s_waitcnt lgkmcnt(5)
	v_mfma_f32_16x16x32_bf16 v[116:119], v[206:209], v[164:167], v[116:119]
	s_waitcnt lgkmcnt(2)
	v_mfma_f32_16x16x32_bf16 v[112:115], v[176:179], v[164:167], v[112:115]
	s_setprio 3
	v_mfma_f32_16x16x32_bf16 v[108:111], v[198:201], v[172:175], v[108:111]
	ds_write_b128 v224, v[28:31] offset:53248
	v_lshl_add_u64 v[28:29], v[228:229], 0, s[22:23]
	global_load_dwordx4 v[28:31], v[28:29], off
	v_mfma_f32_16x16x32_bf16 v[104:107], v[202:205], v[172:175], v[104:107]
	v_mfma_f32_16x16x32_bf16 v[100:103], v[206:209], v[172:175], v[100:103]
	v_mfma_f32_16x16x32_bf16 v[96:99], v[176:179], v[172:175], v[96:99]
	v_mfma_f32_16x16x32_bf16 v[92:95], v[198:201], v[180:183], v[92:95]
	ds_write_b128 v224, v[44:47] offset:57344
	v_lshl_add_u64 v[44:45], v[228:229], 0, s[24:25]
	global_load_dwordx4 v[44:47], v[44:45], off
	v_mfma_f32_16x16x32_bf16 v[88:91], v[202:205], v[180:183], v[88:91]
	v_mfma_f32_16x16x32_bf16 v[84:87], v[206:209], v[180:183], v[84:87]
	v_mfma_f32_16x16x32_bf16 v[80:83], v[176:179], v[180:183], v[80:83]
	v_mfma_f32_16x16x32_bf16 v[76:79], v[198:201], v[168:171], v[76:79]
	ds_write_b128 v224, v[52:55] offset:61440
	v_lshl_add_u64 v[52:53], v[228:229], 0, s[26:27]
	global_load_dwordx4 v[52:55], v[52:53], off
	v_mfma_f32_16x16x32_bf16 v[72:75], v[202:205], v[168:171], v[72:75]
	v_mfma_f32_16x16x32_bf16 v[68:71], v[206:209], v[168:171], v[68:71]
	v_mfma_f32_16x16x32_bf16 v[64:67], v[176:179], v[168:171], v[64:67]
	s_cmp_lt_u32 s2, 28
	s_mov_b64 s[6:7], 0x39c00200
	s_cselect_b64 s[4:5], -1, 0
	v_lshl_add_u64 v[164:165], v[210:211], 0, s[6:7]
	s_and_b64 s[6:7], s[0:1], vcc
	v_cndmask_b32_e64 v166, v140, v136, s[6:7]
	v_cndmask_b32_e64 v167, v141, v137, s[6:7]
	s_mov_b64 s[20:21], 0x200200
	v_cndmask_b32_e64 v211, v167, v165, s[4:5]
	v_cndmask_b32_e64 v210, v166, v164, s[4:5]
	v_lshl_add_u64 v[164:165], v[226:227], 0, s[20:21]
	v_cndmask_b32_e64 v166, v142, v138, s[6:7]
	v_cndmask_b32_e64 v167, v143, v139, s[6:7]
	s_setprio 0
	s_waitcnt lgkmcnt(0)
	s_barrier
; #define MFMA16(a, b, c) __builtin_amdgcn_mfma_f32_16x16x32_bf16((a), (b), (c), 0, 0, 0)
; DI void gld(u32x4v& r, const void* p) { asm volatile("global_load_dwordx4 %0, %1, off" : "=v"(r) : "v"(p) : "memory"); }
; #define WAIT_SET(N, a, b) asm volatile("s_waitcnt vmcnt(" #N ")" : "+v"(a[0]), "+v"(a[1]), "+v"(a[2]), "+v"(a[3]), "+v"(b[0]), "+v"(b[1]), "+v"(b[2]), "+v"(b[3]) :: "memory")
; DI void gemm_half(f32x4 (&acc)[4][4], const char* sa, const char* sb, int o0, int o1, u32x4v (&ra)[4], u32x4v (&rb)[4],
;                   char* stw, const bf16_t* Agn, const bf16_t* Bgn, int lda, int ldb) {
;   bf16x8 af0[4], bf0[4], af1[4], bf1[4];
; #pragma unroll
;   for (int i = 0; i < 4; ++i) { af0[i] = *(const bf16x8*)(sa + i * 16 * 128 + o0); bf0[i] = *(const bf16x8*)(sb + i * 16 * 128 + o0); }
;   __builtin_amdgcn_sched_barrier(0);
;   WAIT_SET(8, ra, rb);
; #pragma unroll
;   for (int g = 0; g < 8; ++g) {
; #pragma unroll
;     for (int ni = 0; ni < 4; ++ni) {
;       if (g < 4) acc[g][ni] = MFMA16(bf0[ni], af0[g], acc[g][ni]);
;       else acc[g - 4][ni] = MFMA16(bf1[ni], af1[g - 4], acc[g - 4][ni]);
;     }
;     if (g < 4) { af1[g] = *(const bf16x8*)(sa + g * 16 * 128 + o1); bf1[g] = *(const bf16x8*)(sb + g * 16 * 128 + o1);
;                  *(u32x4v*)(stw + g * 32 * 128) = ra[g]; gld(ra[g], Agn + (size_t)g * 32 * lda); }
;     else { *(u32x4v*)(stw + TILE_B + (g - 4) * 32 * 128) = rb[g - 4]; gld(rb[g - 4], Bgn + (size_t)(g - 4) * 32 * ldb); }
;     __builtin_amdgcn_sched_barrier(0);
;   }
; DI void gemm_kloop(f32x4 (&acc)[4][4], const bf16_t* Ag, const bf16_t* Bg, int lda, int ldb, int K, char* smem,
;                    u32x4v (&ra)[4], u32x4v (&rb)[4], u32x4v (&rc)[4], u32x4v (&rd)[4], bool pre,
;                    const bf16_t* Agn, const bf16_t* Bgn, bool hasnext) {
;     ...
;     const bf16_t* pa0 = kt + 4 < nk ? Ag + (size_t)(kt + 4) * 64 : ((last && hasnext) ? Agn : Alast);
;     const bf16_t* pb0 = kt + 4 < nk ? Bg + (size_t)(kt + 4) * 64 : ((last && hasnext) ? Bgn : Blast);
;     gemm_half(acc, sa0 + 2 * TILE_B, sb0 + 2 * TILE_B, o0, o1, ra, rb, st, pa0, pb0, lda, ldb);
;     __syncthreads();
;   }
;   if (!hasnext) { WAIT_SET(0, ra, rb); WAIT_SET(0, rc, rd); }
	v_cndmask_b32_e64 v213, v167, v165, s[4:5]
	v_cndmask_b32_e64 v212, v166, v164, s[4:5]
	ds_read_b128 v[164:167], v163 offset:32768
	ds_read_b128 v[168:171], v215 offset:49152
	ds_read_b128 v[172:175], v163 offset:34816
	ds_read_b128 v[176:179], v215 offset:51200
	ds_read_b128 v[180:183], v163 offset:36864
	ds_read_b128 v[186:189], v215 offset:53248
	ds_read_b128 v[190:193], v163 offset:38912
	ds_read_b128 v[194:197], v215 offset:55296
	s_waitcnt vmcnt(8)
	s_setprio 1
	s_waitcnt lgkmcnt(6)
	v_mfma_f32_16x16x32_bf16 v[124:127], v[168:171], v[164:167], v[124:127]
	s_waitcnt lgkmcnt(4)
	v_mfma_f32_16x16x32_bf16 v[120:123], v[176:179], v[164:167], v[120:123]
	s_waitcnt lgkmcnt(2)
	v_mfma_f32_16x16x32_bf16 v[116:119], v[186:189], v[164:167], v[116:119]
	s_waitcnt lgkmcnt(0)
	v_mfma_f32_16x16x32_bf16 v[112:115], v[194:197], v[164:167], v[112:115]
	ds_read_b128 v[164:167], v216 offset:32768
	ds_read_b128 v[198:201], v221 offset:49152
	ds_write_b128 v224, v[0:3]
	global_load_dwordx4 v[0:3], v[210:211], off
	v_mfma_f32_16x16x32_bf16 v[108:111], v[168:171], v[172:175], v[108:111]
	v_mfma_f32_16x16x32_bf16 v[104:107], v[176:179], v[172:175], v[104:107]
	v_mfma_f32_16x16x32_bf16 v[100:103], v[186:189], v[172:175], v[100:103]
	v_mfma_f32_16x16x32_bf16 v[96:99], v[194:197], v[172:175], v[96:99]
	ds_read_b128 v[172:175], v216 offset:34816
	ds_read_b128 v[202:205], v221 offset:51200
	ds_write_b128 v224, v[8:11] offset:4096
	v_lshl_add_u64 v[8:9], v[210:211], 0, s[22:23]
	global_load_dwordx4 v[8:11], v[8:9], off
	s_setprio 2
	v_mfma_f32_16x16x32_bf16 v[92:95], v[168:171], v[180:183], v[92:95]
	v_mfma_f32_16x16x32_bf16 v[88:91], v[176:179], v[180:183], v[88:91]
	v_mfma_f32_16x16x32_bf16 v[84:87], v[186:189], v[180:183], v[84:87]
	v_mfma_f32_16x16x32_bf16 v[80:83], v[194:197], v[180:183], v[80:83]
	ds_read_b128 v[180:183], v216 offset:36864
	ds_read_b128 v[206:209], v221 offset:53248
	ds_write_b128 v224, v[32:35] offset:8192
	v_lshl_add_u64 v[32:33], v[210:211], 0, s[24:25]
	global_load_dwordx4 v[32:35], v[32:33], off
	v_mfma_f32_16x16x32_bf16 v[76:79], v[168:171], v[190:193], v[76:79]
	v_mfma_f32_16x16x32_bf16 v[72:75], v[176:179], v[190:193], v[72:75]
	ds_read_b128 v[168:171], v216 offset:38912
	ds_read_b128 v[176:179], v221 offset:55296
	ds_write_b128 v224, v[56:59] offset:12288
	v_lshl_add_u64 v[56:57], v[210:211], 0, s[26:27]
	v_mfma_f32_16x16x32_bf16 v[68:71], v[186:189], v[190:193], v[68:71]
	global_load_dwordx4 v[56:59], v[56:57], off
	v_mfma_f32_16x16x32_bf16 v[64:67], v[194:197], v[190:193], v[64:67]
	s_waitcnt lgkmcnt(10)
	v_mfma_f32_16x16x32_bf16 v[124:127], v[198:201], v[164:167], v[124:127]
	ds_write_b128 v224, v[4:7] offset:16384
	global_load_dwordx4 v[4:7], v[212:213], off
	s_waitcnt lgkmcnt(8)
	v_mfma_f32_16x16x32_bf16 v[120:123], v[202:205], v[164:167], v[120:123]
	s_waitcnt lgkmcnt(5)
	v_mfma_f32_16x16x32_bf16 v[116:119], v[206:209], v[164:167], v[116:119]
	s_waitcnt lgkmcnt(2)
	v_mfma_f32_16x16x32_bf16 v[112:115], v[176:179], v[164:167], v[112:115]
	s_setprio 3
	v_mfma_f32_16x16x32_bf16 v[108:111], v[198:201], v[172:175], v[108:111]
	ds_write_b128 v224, v[20:23] offset:20480
	v_lshl_add_u64 v[20:21], v[212:213], 0, s[22:23]
	global_load_dwordx4 v[20:23], v[20:21], off
	v_mfma_f32_16x16x32_bf16 v[104:107], v[202:205], v[172:175], v[104:107]
	v_mfma_f32_16x16x32_bf16 v[100:103], v[206:209], v[172:175], v[100:103]
	v_mfma_f32_16x16x32_bf16 v[96:99], v[176:179], v[172:175], v[96:99]
	v_mfma_f32_16x16x32_bf16 v[92:95], v[198:201], v[180:183], v[92:95]
	ds_write_b128 v224, v[36:39] offset:24576
	v_lshl_add_u64 v[36:37], v[212:213], 0, s[24:25]
	global_load_dwordx4 v[36:39], v[36:37], off
	v_mfma_f32_16x16x32_bf16 v[88:91], v[202:205], v[180:183], v[88:91]
	v_mfma_f32_16x16x32_bf16 v[84:87], v[206:209], v[180:183], v[84:87]
	v_mfma_f32_16x16x32_bf16 v[80:83], v[176:179], v[180:183], v[80:83]
	v_mfma_f32_16x16x32_bf16 v[76:79], v[198:201], v[168:171], v[76:79]
	ds_write_b128 v224, v[60:63] offset:28672
	v_lshl_add_u64 v[60:61], v[212:213], 0, s[26:27]
	global_load_dwordx4 v[60:63], v[60:61], off
	v_mfma_f32_16x16x32_bf16 v[72:75], v[202:205], v[168:171], v[72:75]
	v_mfma_f32_16x16x32_bf16 v[68:71], v[206:209], v[168:171], v[68:71]
	v_mfma_f32_16x16x32_bf16 v[64:67], v[176:179], v[168:171], v[64:67]
	v_lshl_add_u64 v[148:149], v[148:149], 0, s[28:29]
	v_lshl_add_u64 v[150:151], v[150:151], 0, s[28:29]
	s_and_b64 vcc, exec, vcc
	s_setprio 0
	s_waitcnt lgkmcnt(0)
	s_barrier
	s_cbranch_vccz .LBB0_291
	s_and_b64 vcc, exec, s[10:11]
	s_cbranch_vccz .LBB0_294
	s_waitcnt vmcnt(0)
	s_waitcnt vmcnt(0)

; #define MFMA16(a, b, c) __builtin_amdgcn_mfma_f32_16x16x32_bf16((a), (b), (c), 0, 0, 0)
; DI void gld(u32x4v& r, const void* p) { asm volatile("global_load_dwordx4 %0, %1, off" : "=v"(r) : "v"(p) : "memory"); }
; #define WAIT_SET(N, a, b) asm volatile("s_waitcnt vmcnt(" #N ")" : "+v"(a[0]), "+v"(a[1]), "+v"(a[2]), "+v"(a[3]), "+v"(b[0]), "+v"(b[1]), "+v"(b[2]), "+v"(b[3]) :: "memory")
; DI void gemm_half(f32x4 (&acc)[4][4], const char* sa, const char* sb, int o0, int o1, u32x4v (&ra)[4], u32x4v (&rb)[4],
;                   char* stw, const bf16_t* Agn, const bf16_t* Bgn, int lda, int ldb) {
;   bf16x8 af0[4], bf0[4], af1[4], bf1[4];
; #pragma unroll
;   for (int i = 0; i < 4; ++i) { af0[i] = *(const bf16x8*)(sa + i * 16 * 128 + o0); bf0[i] = *(const bf16x8*)(sb + i * 16 * 128 + o0); }
;   __builtin_amdgcn_sched_barrier(0);
;   WAIT_SET(8, ra, rb);
; #pragma unroll
;   for (int g = 0; g < 8; ++g) {
; #pragma unroll
;     for (int ni = 0; ni < 4; ++ni) {
;       if (g < 4) acc[g][ni] = MFMA16(bf0[ni], af0[g], acc[g][ni]);
;       else acc[g - 4][ni] = MFMA16(bf1[ni], af1[g - 4], acc[g - 4][ni]);
;     }
;     if (g < 4) { af1[g] = *(const bf16x8*)(sa + g * 16 * 128 + o1); bf1[g] = *(const bf16x8*)(sb + g * 16 * 128 + o1);
;                  *(u32x4v*)(stw + g * 32 * 128) = ra[g]; gld(ra[g], Agn + (size_t)g * 32 * lda); }
;     else { *(u32x4v*)(stw + TILE_B + (g - 4) * 32 * 128) = rb[g - 4]; gld(rb[g - 4], Bgn + (size_t)(g - 4) * 32 * ldb); }
;     __builtin_amdgcn_sched_barrier(0);
;   }
; DI void gemm_kloop(f32x4 (&acc)[4][4], const bf16_t* Ag, const bf16_t* Bg, int lda, int ldb, int K, char* smem,
;                    u32x4v (&ra)[4], u32x4v (&rb)[4], u32x4v (&rc)[4], u32x4v (&rd)[4], bool pre,
;                    const bf16_t* Agn, const bf16_t* Bgn, bool hasnext) {
;     ...
;   for (int kt = 0; kt < nk; kt += 2) {
;     const bool last = kt + 2 >= nk;
;     const bf16_t* pa1 = last ? (hasnext ? Agn + 64 : Alast) : Ag + (size_t)(kt + 3) * 64;
;     const bf16_t* pb1 = last ? (hasnext ? Bgn + 64 : Blast) : Bg + (size_t)(kt + 3) * 64;
;     gemm_half(acc, sa0, sb0, o0, o1, rc, rd, st + 2 * TILE_B, pa1, pb1, lda, ldb);
;     __syncthreads();
;     const bf16_t* pa0 = kt + 4 < nk ? Ag + (size_t)(kt + 4) * 64 : ((last && hasnext) ? Agn : Alast);
;     const bf16_t* pb0 = kt + 4 < nk ? Bg + (size_t)(kt + 4) * 64 : ((last && hasnext) ? Bgn : Blast);
.LBB0_423:
	s_add_i32 s15, s15, 2
	s_cmp_gt_u32 s15, 29
	v_lshl_add_u64 v[182:183], v[146:147], 0, v[184:185]
	s_cselect_b64 vcc, -1, 0
	v_lshl_add_u64 v[158:159], v[182:183], 0, s[26:27]
	v_lshl_add_u64 v[208:209], v[148:149], 0, v[184:185]
	s_mov_b64 s[0:1], 0x4880180
	v_cndmask_b32_e32 v207, v159, v133, vcc
	v_cndmask_b32_e32 v206, v158, v142, vcc
	v_lshl_add_u64 v[158:159], v[208:209], 0, s[0:1]
	v_add_u32_e32 v212, v154, v156
	v_add_u32_e32 v213, v155, v156
	v_cndmask_b32_e32 v211, v159, v143, vcc
	v_cndmask_b32_e32 v210, v158, v144, vcc
	ds_read_b128 v[158:161], v212
	ds_read_b128 v[162:165], v213 offset:16384
	ds_read_b128 v[166:169], v212 offset:2048
	ds_read_b128 v[170:173], v213 offset:18432
	ds_read_b128 v[174:177], v212 offset:4096
	ds_read_b128 v[178:181], v213 offset:20480
	ds_read_b128 v[186:189], v212 offset:6144
	ds_read_b128 v[190:193], v213 offset:22528
	s_waitcnt vmcnt(8)
	s_setprio 1
	v_add_u32_e32 v215, v154, v157
	v_add_u32_e32 v216, v155, v157
	v_add_u32_e32 v221, v152, v153
	s_waitcnt lgkmcnt(6)
	v_mfma_f32_16x16x32_bf16 v[124:127], v[162:165], v[158:161], v[124:127]
	ds_read_b128 v[194:197], v216 offset:16384
	s_waitcnt lgkmcnt(5)
	v_mfma_f32_16x16x32_bf16 v[120:123], v[170:173], v[158:161], v[120:123]
	s_waitcnt lgkmcnt(3)
	v_mfma_f32_16x16x32_bf16 v[116:119], v[178:181], v[158:161], v[116:119]
	s_waitcnt lgkmcnt(1)
	v_mfma_f32_16x16x32_bf16 v[112:115], v[190:193], v[158:161], v[112:115]
	ds_read_b128 v[158:161], v215
	ds_write_b128 v221, v[12:15] offset:32768
	global_load_dwordx4 v[12:15], v[206:207], off
	v_mfma_f32_16x16x32_bf16 v[108:111], v[162:165], v[166:169], v[108:111]
	v_mfma_f32_16x16x32_bf16 v[104:107], v[170:173], v[166:169], v[104:107]
	v_mfma_f32_16x16x32_bf16 v[100:103], v[178:181], v[166:169], v[100:103]
	v_mfma_f32_16x16x32_bf16 v[96:99], v[190:193], v[166:169], v[96:99]
	ds_read_b128 v[166:169], v215 offset:2048
	ds_read_b128 v[198:201], v216 offset:18432
	ds_write_b128 v221, v[24:27] offset:36864
	v_lshl_add_u64 v[24:25], v[206:207], 0, s[20:21]
	global_load_dwordx4 v[24:27], v[24:25], off
	s_setprio 2
	v_mfma_f32_16x16x32_bf16 v[92:95], v[162:165], v[174:177], v[92:95]
	v_mfma_f32_16x16x32_bf16 v[88:91], v[170:173], v[174:177], v[88:91]
	v_mfma_f32_16x16x32_bf16 v[84:87], v[178:181], v[174:177], v[84:87]
	v_mfma_f32_16x16x32_bf16 v[80:83], v[190:193], v[174:177], v[80:83]
	ds_read_b128 v[174:177], v215 offset:4096
	ds_read_b128 v[202:205], v216 offset:20480
	ds_write_b128 v221, v[40:43] offset:40960
	v_lshl_add_u64 v[40:41], v[206:207], 0, s[22:23]
	global_load_dwordx4 v[40:43], v[40:41], off
	v_mfma_f32_16x16x32_bf16 v[76:79], v[162:165], v[186:189], v[76:79]
	v_mfma_f32_16x16x32_bf16 v[72:75], v[170:173], v[186:189], v[72:75]
	ds_read_b128 v[162:165], v215 offset:6144
	ds_read_b128 v[170:173], v216 offset:22528
	ds_write_b128 v221, v[48:51] offset:45056
	v_lshl_add_u64 v[48:49], v[206:207], 0, s[24:25]
	v_mfma_f32_16x16x32_bf16 v[68:71], v[178:181], v[186:189], v[68:71]
	global_load_dwordx4 v[48:51], v[48:49], off
	v_mfma_f32_16x16x32_bf16 v[64:67], v[190:193], v[186:189], v[64:67]
	s_waitcnt lgkmcnt(10)
	v_mfma_f32_16x16x32_bf16 v[124:127], v[194:197], v[158:161], v[124:127]
	ds_write_b128 v221, v[16:19] offset:49152
	global_load_dwordx4 v[16:19], v[210:211], off
	s_waitcnt lgkmcnt(8)
	v_mfma_f32_16x16x32_bf16 v[120:123], v[198:201], v[158:161], v[120:123]
	s_waitcnt lgkmcnt(5)
	v_mfma_f32_16x16x32_bf16 v[116:119], v[202:205], v[158:161], v[116:119]
	s_waitcnt lgkmcnt(2)
	v_mfma_f32_16x16x32_bf16 v[112:115], v[170:173], v[158:161], v[112:115]
	s_setprio 3
	v_mfma_f32_16x16x32_bf16 v[108:111], v[194:197], v[166:169], v[108:111]
	ds_write_b128 v221, v[28:31] offset:53248
	v_lshl_add_u64 v[28:29], v[210:211], 0, s[20:21]
	global_load_dwordx4 v[28:31], v[28:29], off
	v_mfma_f32_16x16x32_bf16 v[104:107], v[198:201], v[166:169], v[104:107]
	v_mfma_f32_16x16x32_bf16 v[100:103], v[202:205], v[166:169], v[100:103]
	v_mfma_f32_16x16x32_bf16 v[96:99], v[170:173], v[166:169], v[96:99]
	v_mfma_f32_16x16x32_bf16 v[92:95], v[194:197], v[174:177], v[92:95]
	ds_write_b128 v221, v[44:47] offset:57344
	v_lshl_add_u64 v[44:45], v[210:211], 0, s[22:23]
	global_load_dwordx4 v[44:47], v[44:45], off
	v_mfma_f32_16x16x32_bf16 v[88:91], v[198:201], v[174:177], v[88:91]
	v_mfma_f32_16x16x32_bf16 v[84:87], v[202:205], v[174:177], v[84:87]
	v_mfma_f32_16x16x32_bf16 v[80:83], v[170:173], v[174:177], v[80:83]
	v_mfma_f32_16x16x32_bf16 v[76:79], v[194:197], v[162:165], v[76:79]
	ds_write_b128 v221, v[52:55] offset:61440
	v_lshl_add_u64 v[52:53], v[210:211], 0, s[24:25]
	global_load_dwordx4 v[52:55], v[52:53], off
	v_mfma_f32_16x16x32_bf16 v[72:75], v[198:201], v[162:165], v[72:75]
	v_mfma_f32_16x16x32_bf16 v[68:71], v[202:205], v[162:165], v[68:71]
	v_mfma_f32_16x16x32_bf16 v[64:67], v[170:173], v[162:165], v[64:67]
	s_cmp_lt_u32 s15, 28
	s_cselect_b64 s[0:1], -1, 0
	s_and_b64 s[4:5], s[10:11], vcc
	v_lshl_add_u64 v[158:159], v[182:183], 0, s[30:31]
	v_cndmask_b32_e64 v160, v138, v134, s[4:5]
	v_cndmask_b32_e64 v161, v139, v135, s[4:5]
	s_mov_b64 s[16:17], 0x4880200
	v_cndmask_b32_e64 v183, v161, v159, s[0:1]
	v_cndmask_b32_e64 v182, v160, v158, s[0:1]
	v_lshl_add_u64 v[158:159], v[208:209], 0, s[16:17]
	v_cndmask_b32_e64 v160, v140, v136, s[4:5]
	v_cndmask_b32_e64 v161, v141, v137, s[4:5]
	s_setprio 0
	s_waitcnt lgkmcnt(0)
	s_barrier
; #define MFMA16(a, b, c) __builtin_amdgcn_mfma_f32_16x16x32_bf16((a), (b), (c), 0, 0, 0)
; DI void gld(u32x4v& r, const void* p) { asm volatile("global_load_dwordx4 %0, %1, off" : "=v"(r) : "v"(p) : "memory"); }
; #define WAIT_SET(N, a, b) asm volatile("s_waitcnt vmcnt(" #N ")" : "+v"(a[0]), "+v"(a[1]), "+v"(a[2]), "+v"(a[3]), "+v"(b[0]), "+v"(b[1]), "+v"(b[2]), "+v"(b[3]) :: "memory")
; DI void gemm_half(f32x4 (&acc)[4][4], const char* sa, const char* sb, int o0, int o1, u32x4v (&ra)[4], u32x4v (&rb)[4],
;                   char* stw, const bf16_t* Agn, const bf16_t* Bgn, int lda, int ldb) {
;   bf16x8 af0[4], bf0[4], af1[4], bf1[4];
; #pragma unroll
;   for (int i = 0; i < 4; ++i) { af0[i] = *(const bf16x8*)(sa + i * 16 * 128 + o0); bf0[i] = *(const bf16x8*)(sb + i * 16 * 128 + o0); }
;   __builtin_amdgcn_sched_barrier(0);
;   WAIT_SET(8, ra, rb);
; #pragma unroll
;   for (int g = 0; g < 8; ++g) {
; #pragma unroll
;     for (int ni = 0; ni < 4; ++ni) {
;       if (g < 4) acc[g][ni] = MFMA16(bf0[ni], af0[g], acc[g][ni]);
;       else acc[g - 4][ni] = MFMA16(bf1[ni], af1[g - 4], acc[g - 4][ni]);
;     }
;     if (g < 4) { af1[g] = *(const bf16x8*)(sa + g * 16 * 128 + o1); bf1[g] = *(const bf16x8*)(sb + g * 16 * 128 + o1);
;                  *(u32x4v*)(stw + g * 32 * 128) = ra[g]; gld(ra[g], Agn + (size_t)g * 32 * lda); }
;     else { *(u32x4v*)(stw + TILE_B + (g - 4) * 32 * 128) = rb[g - 4]; gld(rb[g - 4], Bgn + (size_t)(g - 4) * 32 * ldb); }
;     __builtin_amdgcn_sched_barrier(0);
;   }
; DI void gemm_kloop(f32x4 (&acc)[4][4], const bf16_t* Ag, const bf16_t* Bg, int lda, int ldb, int K, char* smem,
;                    u32x4v (&ra)[4], u32x4v (&rb)[4], u32x4v (&rc)[4], u32x4v (&rd)[4], bool pre,
;                    const bf16_t* Agn, const bf16_t* Bgn, bool hasnext) {
;     ...
;     const bf16_t* pa0 = kt + 4 < nk ? Ag + (size_t)(kt + 4) * 64 : ((last && hasnext) ? Agn : Alast);
;     const bf16_t* pb0 = kt + 4 < nk ? Bg + (size_t)(kt + 4) * 64 : ((last && hasnext) ? Bgn : Blast);
;     gemm_half(acc, sa0 + 2 * TILE_B, sb0 + 2 * TILE_B, o0, o1, ra, rb, st, pa0, pb0, lda, ldb);
;     __syncthreads();
;   }
;   if (!hasnext) { WAIT_SET(0, ra, rb); WAIT_SET(0, rc, rd); }
	v_cndmask_b32_e64 v207, v161, v159, s[0:1]
	v_cndmask_b32_e64 v206, v160, v158, s[0:1]
	ds_read_b128 v[158:161], v212 offset:32768
	ds_read_b128 v[162:165], v213 offset:49152
	ds_read_b128 v[166:169], v212 offset:34816
	ds_read_b128 v[170:173], v213 offset:51200
	ds_read_b128 v[174:177], v212 offset:36864
	ds_read_b128 v[178:181], v213 offset:53248
	ds_read_b128 v[186:189], v212 offset:38912
	ds_read_b128 v[190:193], v213 offset:55296
	s_waitcnt vmcnt(8)
	s_setprio 1
	s_waitcnt lgkmcnt(6)
	v_mfma_f32_16x16x32_bf16 v[124:127], v[162:165], v[158:161], v[124:127]
	s_waitcnt lgkmcnt(4)
	v_mfma_f32_16x16x32_bf16 v[120:123], v[170:173], v[158:161], v[120:123]
	s_waitcnt lgkmcnt(2)
	v_mfma_f32_16x16x32_bf16 v[116:119], v[178:181], v[158:161], v[116:119]
	s_waitcnt lgkmcnt(0)
	v_mfma_f32_16x16x32_bf16 v[112:115], v[190:193], v[158:161], v[112:115]
	ds_read_b128 v[158:161], v215 offset:32768
	ds_read_b128 v[194:197], v216 offset:49152
	ds_write_b128 v221, v[0:3]
	global_load_dwordx4 v[0:3], v[182:183], off
	v_mfma_f32_16x16x32_bf16 v[108:111], v[162:165], v[166:169], v[108:111]
	v_mfma_f32_16x16x32_bf16 v[104:107], v[170:173], v[166:169], v[104:107]
	v_mfma_f32_16x16x32_bf16 v[100:103], v[178:181], v[166:169], v[100:103]
	v_mfma_f32_16x16x32_bf16 v[96:99], v[190:193], v[166:169], v[96:99]
	ds_read_b128 v[166:169], v215 offset:34816
	ds_read_b128 v[198:201], v216 offset:51200
	ds_write_b128 v221, v[8:11] offset:4096
	v_lshl_add_u64 v[8:9], v[182:183], 0, s[20:21]
	global_load_dwordx4 v[8:11], v[8:9], off
	s_setprio 2
	v_mfma_f32_16x16x32_bf16 v[92:95], v[162:165], v[174:177], v[92:95]
	v_mfma_f32_16x16x32_bf16 v[88:91], v[170:173], v[174:177], v[88:91]
	v_mfma_f32_16x16x32_bf16 v[84:87], v[178:181], v[174:177], v[84:87]
	v_mfma_f32_16x16x32_bf16 v[80:83], v[190:193], v[174:177], v[80:83]
	ds_read_b128 v[174:177], v215 offset:36864
	ds_read_b128 v[202:205], v216 offset:53248
	ds_write_b128 v221, v[32:35] offset:8192
	v_lshl_add_u64 v[32:33], v[182:183], 0, s[22:23]
	global_load_dwordx4 v[32:35], v[32:33], off
	v_mfma_f32_16x16x32_bf16 v[76:79], v[162:165], v[186:189], v[76:79]
	v_mfma_f32_16x16x32_bf16 v[72:75], v[170:173], v[186:189], v[72:75]
	ds_read_b128 v[162:165], v215 offset:38912
	ds_read_b128 v[170:173], v216 offset:55296
	ds_write_b128 v221, v[56:59] offset:12288
	v_lshl_add_u64 v[56:57], v[182:183], 0, s[24:25]
	v_mfma_f32_16x16x32_bf16 v[68:71], v[178:181], v[186:189], v[68:71]
	global_load_dwordx4 v[56:59], v[56:57], off
	v_mfma_f32_16x16x32_bf16 v[64:67], v[190:193], v[186:189], v[64:67]
	s_waitcnt lgkmcnt(10)
	v_mfma_f32_16x16x32_bf16 v[124:127], v[194:197], v[158:161], v[124:127]
	ds_write_b128 v221, v[4:7] offset:16384
	global_load_dwordx4 v[4:7], v[206:207], off
	s_waitcnt lgkmcnt(8)
	v_mfma_f32_16x16x32_bf16 v[120:123], v[198:201], v[158:161], v[120:123]
	s_waitcnt lgkmcnt(5)
	v_mfma_f32_16x16x32_bf16 v[116:119], v[202:205], v[158:161], v[116:119]
	s_waitcnt lgkmcnt(2)
	v_mfma_f32_16x16x32_bf16 v[112:115], v[170:173], v[158:161], v[112:115]
	s_setprio 3
	v_mfma_f32_16x16x32_bf16 v[108:111], v[194:197], v[166:169], v[108:111]
	ds_write_b128 v221, v[20:23] offset:20480
	v_lshl_add_u64 v[20:21], v[206:207], 0, s[20:21]
	global_load_dwordx4 v[20:23], v[20:21], off
	v_mfma_f32_16x16x32_bf16 v[104:107], v[198:201], v[166:169], v[104:107]
	v_mfma_f32_16x16x32_bf16 v[100:103], v[202:205], v[166:169], v[100:103]
	v_mfma_f32_16x16x32_bf16 v[96:99], v[170:173], v[166:169], v[96:99]
	v_mfma_f32_16x16x32_bf16 v[92:95], v[194:197], v[174:177], v[92:95]
	ds_write_b128 v221, v[36:39] offset:24576
	v_lshl_add_u64 v[36:37], v[206:207], 0, s[22:23]
	global_load_dwordx4 v[36:39], v[36:37], off
	v_mfma_f32_16x16x32_bf16 v[88:91], v[198:201], v[174:177], v[88:91]
	v_mfma_f32_16x16x32_bf16 v[84:87], v[202:205], v[174:177], v[84:87]
	v_mfma_f32_16x16x32_bf16 v[80:83], v[170:173], v[174:177], v[80:83]
	v_mfma_f32_16x16x32_bf16 v[76:79], v[194:197], v[162:165], v[76:79]
	ds_write_b128 v221, v[60:63] offset:28672
	v_lshl_add_u64 v[60:61], v[206:207], 0, s[24:25]
	global_load_dwordx4 v[60:63], v[60:61], off
	v_mfma_f32_16x16x32_bf16 v[72:75], v[198:201], v[162:165], v[72:75]
	v_mfma_f32_16x16x32_bf16 v[68:71], v[202:205], v[162:165], v[68:71]
	v_mfma_f32_16x16x32_bf16 v[64:67], v[170:173], v[162:165], v[64:67]
	v_lshl_add_u64 v[146:147], v[146:147], 0, s[28:29]
	v_lshl_add_u64 v[148:149], v[148:149], 0, s[28:29]
	s_and_b64 vcc, exec, vcc
	s_setprio 0
	s_waitcnt lgkmcnt(0)
	s_barrier
	s_cbranch_vccz .LBB0_423
	s_and_b64 vcc, exec, s[6:7]
	s_cbranch_vccz .LBB0_412
	s_waitcnt vmcnt(0)
	s_waitcnt vmcnt(0)
	s_branch .LBB0_412

; #define MFMA16(a, b, c) __builtin_amdgcn_mfma_f32_16x16x32_bf16((a), (b), (c), 0, 0, 0)
; DI void gld(u32x4v& r, const void* p) { asm volatile("global_load_dwordx4 %0, %1, off" : "=v"(r) : "v"(p) : "memory"); }
; #define WAIT_SET(N, a, b) asm volatile("s_waitcnt vmcnt(" #N ")" : "+v"(a[0]), "+v"(a[1]), "+v"(a[2]), "+v"(a[3]), "+v"(b[0]), "+v"(b[1]), "+v"(b[2]), "+v"(b[3]) :: "memory")
; DI void gemm_half(f32x4 (&acc)[4][4], const char* sa, const char* sb, int o0, int o1, u32x4v (&ra)[4], u32x4v (&rb)[4],
;                   char* stw, const bf16_t* Agn, const bf16_t* Bgn, int lda, int ldb) {
;   bf16x8 af0[4], bf0[4], af1[4], bf1[4];
; #pragma unroll
;   for (int i = 0; i < 4; ++i) { af0[i] = *(const bf16x8*)(sa + i * 16 * 128 + o0); bf0[i] = *(const bf16x8*)(sb + i * 16 * 128 + o0); }
;   __builtin_amdgcn_sched_barrier(0);
;   WAIT_SET(8, ra, rb);
; #pragma unroll
;   for (int g = 0; g < 8; ++g) {
; #pragma unroll
;     for (int ni = 0; ni < 4; ++ni) {
;       if (g < 4) acc[g][ni] = MFMA16(bf0[ni], af0[g], acc[g][ni]);
;       else acc[g - 4][ni] = MFMA16(bf1[ni], af1[g - 4], acc[g - 4][ni]);
;     }
;     if (g < 4) { af1[g] = *(const bf16x8*)(sa + g * 16 * 128 + o1); bf1[g] = *(const bf16x8*)(sb + g * 16 * 128 + o1);
;                  *(u32x4v*)(stw + g * 32 * 128) = ra[g]; gld(ra[g], Agn + (size_t)g * 32 * lda); }
;     else { *(u32x4v*)(stw + TILE_B + (g - 4) * 32 * 128) = rb[g - 4]; gld(rb[g - 4], Bgn + (size_t)(g - 4) * 32 * ldb); }
;     __builtin_amdgcn_sched_barrier(0);
;   }
; DI void gemm_kloop(f32x4 (&acc)[4][4], const bf16_t* Ag, const bf16_t* Bg, int lda, int ldb, int K, char* smem,
;                    u32x4v (&ra)[4], u32x4v (&rb)[4], u32x4v (&rc)[4], u32x4v (&rd)[4], bool pre,
;                    const bf16_t* Agn, const bf16_t* Bgn, bool hasnext) {
;     ...
;   for (int kt = 0; kt < nk; kt += 2) {
;     const bool last = kt + 2 >= nk;
;     const bf16_t* pa1 = last ? (hasnext ? Agn + 64 : Alast) : Ag + (size_t)(kt + 3) * 64;
;     const bf16_t* pb1 = last ? (hasnext ? Bgn + 64 : Blast) : Bg + (size_t)(kt + 3) * 64;
;     gemm_half(acc, sa0, sb0, o0, o1, rc, rd, st + 2 * TILE_B, pa1, pb1, lda, ldb);
;     __syncthreads();
;     const bf16_t* pa0 = kt + 4 < nk ? Ag + (size_t)(kt + 4) * 64 : ((last && hasnext) ? Agn : Alast);
;     const bf16_t* pb0 = kt + 4 < nk ? Bg + (size_t)(kt + 4) * 64 : ((last && hasnext) ? Bgn : Blast);
.LBB0_445:
	s_add_i32 s37, s37, 2
	s_cmp_gt_u32 s37, 29
	v_lshl_add_u64 v[206:207], v[144:145], 0, v[184:185]
	s_cselect_b64 vcc, -1, 0
	v_lshl_add_u64 v[160:161], v[206:207], 0, s[46:47]
	v_cndmask_b32_e32 v209, v161, v141, vcc
	v_cndmask_b32_e32 v208, v160, v140, vcc
	v_lshl_add_u64 v[160:161], v[148:149], 0, v[184:185]
	v_add_u32_e32 v159, v155, v157
	v_add_u32_e32 v212, v156, v157
	v_cndmask_b32_e32 v211, v161, v143, vcc
	v_cndmask_b32_e32 v210, v160, v142, vcc
	ds_read_b128 v[160:163], v159
	ds_read_b128 v[164:167], v212 offset:16384
	ds_read_b128 v[168:171], v159 offset:2048
	ds_read_b128 v[172:175], v212 offset:18432
	ds_read_b128 v[176:179], v159 offset:4096
	ds_read_b128 v[180:183], v212 offset:20480
	ds_read_b128 v[186:189], v159 offset:6144
	ds_read_b128 v[190:193], v212 offset:22528
	s_waitcnt vmcnt(8)
	s_setprio 1
	v_add_u32_e32 v213, v155, v158
	v_add_u32_e32 v215, v156, v158
	v_add_u32_e32 v216, v153, v154
	s_waitcnt lgkmcnt(6)
	v_mfma_f32_16x16x32_bf16 v[124:127], v[164:167], v[160:163], v[124:127]
	ds_read_b128 v[194:197], v215 offset:16384
	s_waitcnt lgkmcnt(5)
	v_mfma_f32_16x16x32_bf16 v[120:123], v[172:175], v[160:163], v[120:123]
	s_waitcnt lgkmcnt(3)
	v_mfma_f32_16x16x32_bf16 v[116:119], v[180:183], v[160:163], v[116:119]
	s_waitcnt lgkmcnt(1)
	v_mfma_f32_16x16x32_bf16 v[112:115], v[190:193], v[160:163], v[112:115]
	ds_read_b128 v[160:163], v213
	ds_write_b128 v216, v[12:15] offset:32768
	global_load_dwordx4 v[12:15], v[208:209], off
	v_mfma_f32_16x16x32_bf16 v[108:111], v[164:167], v[168:171], v[108:111]
	v_mfma_f32_16x16x32_bf16 v[104:107], v[172:175], v[168:171], v[104:107]
	v_mfma_f32_16x16x32_bf16 v[100:103], v[180:183], v[168:171], v[100:103]
	v_mfma_f32_16x16x32_bf16 v[96:99], v[190:193], v[168:171], v[96:99]
	ds_read_b128 v[168:171], v213 offset:2048
	ds_read_b128 v[198:201], v215 offset:18432
	ds_write_b128 v216, v[24:27] offset:36864
	v_lshl_add_u64 v[24:25], v[208:209], 0, s[40:41]
	global_load_dwordx4 v[24:27], v[24:25], off
	s_setprio 2
	v_mfma_f32_16x16x32_bf16 v[92:95], v[164:167], v[176:179], v[92:95]
	v_mfma_f32_16x16x32_bf16 v[88:91], v[172:175], v[176:179], v[88:91]
	v_mfma_f32_16x16x32_bf16 v[84:87], v[180:183], v[176:179], v[84:87]
	v_mfma_f32_16x16x32_bf16 v[80:83], v[190:193], v[176:179], v[80:83]
	ds_read_b128 v[176:179], v213 offset:4096
	ds_read_b128 v[202:205], v215 offset:20480
	ds_write_b128 v216, v[40:43] offset:40960
	v_lshl_add_u64 v[40:41], v[208:209], 0, s[42:43]
	global_load_dwordx4 v[40:43], v[40:41], off
	v_mfma_f32_16x16x32_bf16 v[76:79], v[164:167], v[186:189], v[76:79]
	v_mfma_f32_16x16x32_bf16 v[72:75], v[172:175], v[186:189], v[72:75]
	ds_read_b128 v[164:167], v213 offset:6144
	ds_read_b128 v[172:175], v215 offset:22528
	ds_write_b128 v216, v[48:51] offset:45056
	v_lshl_add_u64 v[48:49], v[208:209], 0, s[44:45]
	v_mfma_f32_16x16x32_bf16 v[68:71], v[180:183], v[186:189], v[68:71]
	global_load_dwordx4 v[48:51], v[48:49], off
	v_mfma_f32_16x16x32_bf16 v[64:67], v[190:193], v[186:189], v[64:67]
	s_waitcnt lgkmcnt(10)
	v_mfma_f32_16x16x32_bf16 v[124:127], v[194:197], v[160:163], v[124:127]
	ds_write_b128 v216, v[16:19] offset:49152
	global_load_dwordx4 v[16:19], v[210:211], off
	s_waitcnt lgkmcnt(8)
	v_mfma_f32_16x16x32_bf16 v[120:123], v[198:201], v[160:163], v[120:123]
	s_waitcnt lgkmcnt(5)
	v_mfma_f32_16x16x32_bf16 v[116:119], v[202:205], v[160:163], v[116:119]
	s_waitcnt lgkmcnt(2)
	v_mfma_f32_16x16x32_bf16 v[112:115], v[172:175], v[160:163], v[112:115]
	s_setprio 3
	v_mfma_f32_16x16x32_bf16 v[108:111], v[194:197], v[168:171], v[108:111]
	ds_write_b128 v216, v[28:31] offset:53248
	v_lshl_add_u64 v[28:29], v[210:211], 0, s[40:41]
	global_load_dwordx4 v[28:31], v[28:29], off
	v_mfma_f32_16x16x32_bf16 v[104:107], v[198:201], v[168:171], v[104:107]
	v_mfma_f32_16x16x32_bf16 v[100:103], v[202:205], v[168:171], v[100:103]
	v_mfma_f32_16x16x32_bf16 v[96:99], v[172:175], v[168:171], v[96:99]
	v_mfma_f32_16x16x32_bf16 v[92:95], v[194:197], v[176:179], v[92:95]
	ds_write_b128 v216, v[44:47] offset:57344
	v_lshl_add_u64 v[44:45], v[210:211], 0, s[42:43]
	global_load_dwordx4 v[44:47], v[44:45], off
	v_mfma_f32_16x16x32_bf16 v[88:91], v[198:201], v[176:179], v[88:91]
	v_mfma_f32_16x16x32_bf16 v[84:87], v[202:205], v[176:179], v[84:87]
	v_mfma_f32_16x16x32_bf16 v[80:83], v[172:175], v[176:179], v[80:83]
	v_mfma_f32_16x16x32_bf16 v[76:79], v[194:197], v[164:167], v[76:79]
	ds_write_b128 v216, v[52:55] offset:61440
	v_lshl_add_u64 v[52:53], v[210:211], 0, s[44:45]
	global_load_dwordx4 v[52:55], v[52:53], off
	v_mfma_f32_16x16x32_bf16 v[72:75], v[198:201], v[164:167], v[72:75]
	v_mfma_f32_16x16x32_bf16 v[68:71], v[202:205], v[164:167], v[68:71]
	v_mfma_f32_16x16x32_bf16 v[64:67], v[172:175], v[164:167], v[64:67]
	s_cmp_lt_u32 s37, 28
	s_cselect_b64 s[0:1], -1, 0
	s_and_b64 s[4:5], s[26:27], vcc
	v_lshl_add_u64 v[160:161], v[206:207], 0, s[50:51]
	v_cndmask_b32_e64 v162, v136, v132, s[4:5]
	v_cndmask_b32_e64 v163, v137, v133, s[4:5]
	v_cndmask_b32_e64 v207, v163, v161, s[0:1]
	v_cndmask_b32_e64 v206, v162, v160, s[0:1]
	v_lshl_add_u64 v[160:161], v[146:147], 0, v[184:185]
	v_cndmask_b32_e64 v162, v138, v134, s[4:5]
	v_cndmask_b32_e64 v163, v139, v135, s[4:5]
	s_setprio 0
	s_waitcnt lgkmcnt(0)
	s_barrier
; #define MFMA16(a, b, c) __builtin_amdgcn_mfma_f32_16x16x32_bf16((a), (b), (c), 0, 0, 0)
; DI void gld(u32x4v& r, const void* p) { asm volatile("global_load_dwordx4 %0, %1, off" : "=v"(r) : "v"(p) : "memory"); }
; #define WAIT_SET(N, a, b) asm volatile("s_waitcnt vmcnt(" #N ")" : "+v"(a[0]), "+v"(a[1]), "+v"(a[2]), "+v"(a[3]), "+v"(b[0]), "+v"(b[1]), "+v"(b[2]), "+v"(b[3]) :: "memory")
; DI void gemm_half(f32x4 (&acc)[4][4], const char* sa, const char* sb, int o0, int o1, u32x4v (&ra)[4], u32x4v (&rb)[4],
;                   char* stw, const bf16_t* Agn, const bf16_t* Bgn, int lda, int ldb) {
;   bf16x8 af0[4], bf0[4], af1[4], bf1[4];
; #pragma unroll
;   for (int i = 0; i < 4; ++i) { af0[i] = *(const bf16x8*)(sa + i * 16 * 128 + o0); bf0[i] = *(const bf16x8*)(sb + i * 16 * 128 + o0); }
;   __builtin_amdgcn_sched_barrier(0);
;   WAIT_SET(8, ra, rb);
; #pragma unroll
;   for (int g = 0; g < 8; ++g) {
; #pragma unroll
;     for (int ni = 0; ni < 4; ++ni) {
;       if (g < 4) acc[g][ni] = MFMA16(bf0[ni], af0[g], acc[g][ni]);
;       else acc[g - 4][ni] = MFMA16(bf1[ni], af1[g - 4], acc[g - 4][ni]);
;     }
;     if (g < 4) { af1[g] = *(const bf16x8*)(sa + g * 16 * 128 + o1); bf1[g] = *(const bf16x8*)(sb + g * 16 * 128 + o1);
;                  *(u32x4v*)(stw + g * 32 * 128) = ra[g]; gld(ra[g], Agn + (size_t)g * 32 * lda); }
;     else { *(u32x4v*)(stw + TILE_B + (g - 4) * 32 * 128) = rb[g - 4]; gld(rb[g - 4], Bgn + (size_t)(g - 4) * 32 * ldb); }
;     __builtin_amdgcn_sched_barrier(0);
;   }
; DI void gemm_kloop(f32x4 (&acc)[4][4], const bf16_t* Ag, const bf16_t* Bg, int lda, int ldb, int K, char* smem,
;                    u32x4v (&ra)[4], u32x4v (&rb)[4], u32x4v (&rc)[4], u32x4v (&rd)[4], bool pre,
;                    const bf16_t* Agn, const bf16_t* Bgn, bool hasnext) {
;     ...
;     const bf16_t* pa0 = kt + 4 < nk ? Ag + (size_t)(kt + 4) * 64 : ((last && hasnext) ? Agn : Alast);
;     const bf16_t* pb0 = kt + 4 < nk ? Bg + (size_t)(kt + 4) * 64 : ((last && hasnext) ? Bgn : Blast);
;     gemm_half(acc, sa0 + 2 * TILE_B, sb0 + 2 * TILE_B, o0, o1, ra, rb, st, pa0, pb0, lda, ldb);
;     __syncthreads();
;   }
;   if (!hasnext) { WAIT_SET(0, ra, rb); WAIT_SET(0, rc, rd); }
	v_cndmask_b32_e64 v209, v163, v161, s[0:1]
	v_cndmask_b32_e64 v208, v162, v160, s[0:1]
	ds_read_b128 v[160:163], v159 offset:32768
	ds_read_b128 v[164:167], v212 offset:49152
	ds_read_b128 v[168:171], v159 offset:34816
	ds_read_b128 v[172:175], v212 offset:51200
	ds_read_b128 v[176:179], v159 offset:36864
	ds_read_b128 v[180:183], v212 offset:53248
	ds_read_b128 v[186:189], v159 offset:38912
	ds_read_b128 v[190:193], v212 offset:55296
	s_waitcnt vmcnt(8)
	s_setprio 1
	s_waitcnt lgkmcnt(6)
	v_mfma_f32_16x16x32_bf16 v[124:127], v[164:167], v[160:163], v[124:127]
	s_waitcnt lgkmcnt(4)
	v_mfma_f32_16x16x32_bf16 v[120:123], v[172:175], v[160:163], v[120:123]
	s_waitcnt lgkmcnt(2)
	v_mfma_f32_16x16x32_bf16 v[116:119], v[180:183], v[160:163], v[116:119]
	s_waitcnt lgkmcnt(0)
	v_mfma_f32_16x16x32_bf16 v[112:115], v[190:193], v[160:163], v[112:115]
	ds_read_b128 v[160:163], v213 offset:32768
	ds_read_b128 v[194:197], v215 offset:49152
	ds_write_b128 v216, v[0:3]
	global_load_dwordx4 v[0:3], v[206:207], off
	v_mfma_f32_16x16x32_bf16 v[108:111], v[164:167], v[168:171], v[108:111]
	v_mfma_f32_16x16x32_bf16 v[104:107], v[172:175], v[168:171], v[104:107]
	v_mfma_f32_16x16x32_bf16 v[100:103], v[180:183], v[168:171], v[100:103]
	v_mfma_f32_16x16x32_bf16 v[96:99], v[190:193], v[168:171], v[96:99]
	ds_read_b128 v[168:171], v213 offset:34816
	ds_read_b128 v[198:201], v215 offset:51200
	ds_write_b128 v216, v[8:11] offset:4096
	v_lshl_add_u64 v[8:9], v[206:207], 0, s[40:41]
	global_load_dwordx4 v[8:11], v[8:9], off
	s_setprio 2
	v_mfma_f32_16x16x32_bf16 v[92:95], v[164:167], v[176:179], v[92:95]
	v_mfma_f32_16x16x32_bf16 v[88:91], v[172:175], v[176:179], v[88:91]
	v_mfma_f32_16x16x32_bf16 v[84:87], v[180:183], v[176:179], v[84:87]
	v_mfma_f32_16x16x32_bf16 v[80:83], v[190:193], v[176:179], v[80:83]
	ds_read_b128 v[176:179], v213 offset:36864
	ds_read_b128 v[202:205], v215 offset:53248
	ds_write_b128 v216, v[32:35] offset:8192
	v_lshl_add_u64 v[32:33], v[206:207], 0, s[42:43]
	global_load_dwordx4 v[32:35], v[32:33], off
	v_mfma_f32_16x16x32_bf16 v[76:79], v[164:167], v[186:189], v[76:79]
	v_mfma_f32_16x16x32_bf16 v[72:75], v[172:175], v[186:189], v[72:75]
	ds_read_b128 v[164:167], v213 offset:38912
	ds_read_b128 v[172:175], v215 offset:55296
	ds_write_b128 v216, v[56:59] offset:12288
	v_lshl_add_u64 v[56:57], v[206:207], 0, s[44:45]
	v_mfma_f32_16x16x32_bf16 v[68:71], v[180:183], v[186:189], v[68:71]
	global_load_dwordx4 v[56:59], v[56:57], off
	v_mfma_f32_16x16x32_bf16 v[64:67], v[190:193], v[186:189], v[64:67]
	s_waitcnt lgkmcnt(10)
	v_mfma_f32_16x16x32_bf16 v[124:127], v[194:197], v[160:163], v[124:127]
	ds_write_b128 v216, v[4:7] offset:16384
	global_load_dwordx4 v[4:7], v[208:209], off
	s_waitcnt lgkmcnt(8)
	v_mfma_f32_16x16x32_bf16 v[120:123], v[198:201], v[160:163], v[120:123]
	s_waitcnt lgkmcnt(5)
	v_mfma_f32_16x16x32_bf16 v[116:119], v[202:205], v[160:163], v[116:119]
	s_waitcnt lgkmcnt(2)
	v_mfma_f32_16x16x32_bf16 v[112:115], v[172:175], v[160:163], v[112:115]
	s_setprio 3
	v_mfma_f32_16x16x32_bf16 v[108:111], v[194:197], v[168:171], v[108:111]
	ds_write_b128 v216, v[20:23] offset:20480
	v_lshl_add_u64 v[20:21], v[208:209], 0, s[40:41]
	global_load_dwordx4 v[20:23], v[20:21], off
	v_mfma_f32_16x16x32_bf16 v[104:107], v[198:201], v[168:171], v[104:107]
	v_mfma_f32_16x16x32_bf16 v[100:103], v[202:205], v[168:171], v[100:103]
	v_mfma_f32_16x16x32_bf16 v[96:99], v[172:175], v[168:171], v[96:99]
	v_mfma_f32_16x16x32_bf16 v[92:95], v[194:197], v[176:179], v[92:95]
	ds_write_b128 v216, v[36:39] offset:24576
	v_lshl_add_u64 v[36:37], v[208:209], 0, s[42:43]
	global_load_dwordx4 v[36:39], v[36:37], off
	v_mfma_f32_16x16x32_bf16 v[88:91], v[198:201], v[176:179], v[88:91]
	v_mfma_f32_16x16x32_bf16 v[84:87], v[202:205], v[176:179], v[84:87]
	v_mfma_f32_16x16x32_bf16 v[80:83], v[172:175], v[176:179], v[80:83]
	v_mfma_f32_16x16x32_bf16 v[76:79], v[194:197], v[164:167], v[76:79]
	ds_write_b128 v216, v[60:63] offset:28672
	v_lshl_add_u64 v[60:61], v[208:209], 0, s[44:45]
	global_load_dwordx4 v[60:63], v[60:61], off
	v_mfma_f32_16x16x32_bf16 v[72:75], v[198:201], v[164:167], v[72:75]
	v_mfma_f32_16x16x32_bf16 v[68:71], v[202:205], v[164:167], v[68:71]
	v_mfma_f32_16x16x32_bf16 v[64:67], v[172:175], v[164:167], v[64:67]
	v_lshl_add_u64 v[144:145], v[144:145], 0, s[48:49]
	v_lshl_add_u64 v[146:147], v[146:147], 0, s[48:49]
	v_lshl_add_u64 v[148:149], v[148:149], 0, s[48:49]
	s_and_b64 vcc, exec, vcc
	s_setprio 0
	s_waitcnt lgkmcnt(0)
	s_barrier
	s_cbranch_vccz .LBB0_445
	s_and_b64 vcc, exec, s[24:25]
	s_cbranch_vccz .LBB0_434
	s_waitcnt vmcnt(0)
	s_waitcnt vmcnt(0)
	s_branch .LBB0_434

; #define MFMA16(a, b, c) __builtin_amdgcn_mfma_f32_16x16x32_bf16((a), (b), (c), 0, 0, 0)
; DI void gld(u32x4v& r, const void* p) { asm volatile("global_load_dwordx4 %0, %1, off" : "=v"(r) : "v"(p) : "memory"); }
; #define WAIT_SET(N, a, b) asm volatile("s_waitcnt vmcnt(" #N ")" : "+v"(a[0]), "+v"(a[1]), "+v"(a[2]), "+v"(a[3]), "+v"(b[0]), "+v"(b[1]), "+v"(b[2]), "+v"(b[3]) :: "memory")
; DI void gemm_half(f32x4 (&acc)[4][4], const char* sa, const char* sb, int o0, int o1, u32x4v (&ra)[4], u32x4v (&rb)[4],
;                   char* stw, const bf16_t* Agn, const bf16_t* Bgn, int lda, int ldb) {
;   bf16x8 af0[4], bf0[4], af1[4], bf1[4];
; #pragma unroll
;   for (int i = 0; i < 4; ++i) { af0[i] = *(const bf16x8*)(sa + i * 16 * 128 + o0); bf0[i] = *(const bf16x8*)(sb + i * 16 * 128 + o0); }
;   __builtin_amdgcn_sched_barrier(0);
;   WAIT_SET(8, ra, rb);
; #pragma unroll
;   for (int g = 0; g < 8; ++g) {
; #pragma unroll
;     for (int ni = 0; ni < 4; ++ni) {
;       if (g < 4) acc[g][ni] = MFMA16(bf0[ni], af0[g], acc[g][ni]);
;       else acc[g - 4][ni] = MFMA16(bf1[ni], af1[g - 4], acc[g - 4][ni]);
;     }
;     if (g < 4) { af1[g] = *(const bf16x8*)(sa + g * 16 * 128 + o1); bf1[g] = *(const bf16x8*)(sb + g * 16 * 128 + o1);
;                  *(u32x4v*)(stw + g * 32 * 128) = ra[g]; gld(ra[g], Agn + (size_t)g * 32 * lda); }
;     else { *(u32x4v*)(stw + TILE_B + (g - 4) * 32 * 128) = rb[g - 4]; gld(rb[g - 4], Bgn + (size_t)(g - 4) * 32 * ldb); }
;     __builtin_amdgcn_sched_barrier(0);
;   }
; DI void gemm_kloop(f32x4 (&acc)[4][4], const bf16_t* Ag, const bf16_t* Bg, int lda, int ldb, int K, char* smem,
;                    u32x4v (&ra)[4], u32x4v (&rb)[4], u32x4v (&rc)[4], u32x4v (&rd)[4], bool pre,
;                    const bf16_t* Agn, const bf16_t* Bgn, bool hasnext) {
;     ...
;   for (int kt = 0; kt < nk; kt += 2) {
;     const bool last = kt + 2 >= nk;
;     const bf16_t* pa1 = last ? (hasnext ? Agn + 64 : Alast) : Ag + (size_t)(kt + 3) * 64;
;     const bf16_t* pb1 = last ? (hasnext ? Bgn + 64 : Blast) : Bg + (size_t)(kt + 3) * 64;
;     gemm_half(acc, sa0, sb0, o0, o1, rc, rd, st + 2 * TILE_B, pa1, pb1, lda, ldb);
;     __syncthreads();
;     const bf16_t* pa0 = kt + 4 < nk ? Ag + (size_t)(kt + 4) * 64 : ((last && hasnext) ? Agn : Alast);
;     const bf16_t* pb0 = kt + 4 < nk ? Bg + (size_t)(kt + 4) * 64 : ((last && hasnext) ? Bgn : Blast);
.LBB0_461:
	s_add_i32 s39, s39, 2
	s_cmp_gt_u32 s39, 13
	s_cselect_b64 vcc, -1, 0
	v_lshl_add_u64 v[162:163], v[150:151], 0, v[184:185]
	v_cndmask_b32_e32 v183, v163, v133, vcc
	v_cndmask_b32_e32 v182, v162, v142, vcc
	v_lshl_add_u64 v[162:163], v[152:153], 0, v[184:185]
	v_add_u32_e32 v212, v158, v160
	v_add_u32_e32 v213, v159, v160
	v_cndmask_b32_e32 v211, v163, v143, vcc
	v_cndmask_b32_e32 v210, v162, v144, vcc
	ds_read_b128 v[162:165], v212
	ds_read_b128 v[166:169], v213 offset:16384
	ds_read_b128 v[170:173], v212 offset:2048
	ds_read_b128 v[174:177], v213 offset:18432
	ds_read_b128 v[178:181], v212 offset:4096
	ds_read_b128 v[186:189], v213 offset:20480
	ds_read_b128 v[190:193], v212 offset:6144
	ds_read_b128 v[194:197], v213 offset:22528
	s_waitcnt vmcnt(8)
	s_setprio 1
	v_add_u32_e32 v215, v158, v161
	v_add_u32_e32 v216, v159, v161
	v_add_u32_e32 v221, v156, v157
	s_waitcnt lgkmcnt(6)
	v_mfma_f32_16x16x32_bf16 v[124:127], v[166:169], v[162:165], v[124:127]
	ds_read_b128 v[198:201], v216 offset:16384
	s_waitcnt lgkmcnt(5)
	v_mfma_f32_16x16x32_bf16 v[120:123], v[174:177], v[162:165], v[120:123]
	s_waitcnt lgkmcnt(3)
	v_mfma_f32_16x16x32_bf16 v[116:119], v[186:189], v[162:165], v[116:119]
	s_waitcnt lgkmcnt(1)
	v_mfma_f32_16x16x32_bf16 v[112:115], v[194:197], v[162:165], v[112:115]
	ds_read_b128 v[162:165], v215
	ds_write_b128 v221, v[12:15] offset:32768
	global_load_dwordx4 v[12:15], v[182:183], off
	v_mfma_f32_16x16x32_bf16 v[108:111], v[166:169], v[170:173], v[108:111]
	v_mfma_f32_16x16x32_bf16 v[104:107], v[174:177], v[170:173], v[104:107]
	v_mfma_f32_16x16x32_bf16 v[100:103], v[186:189], v[170:173], v[100:103]
	v_mfma_f32_16x16x32_bf16 v[96:99], v[194:197], v[170:173], v[96:99]
	ds_read_b128 v[170:173], v215 offset:2048
	ds_read_b128 v[202:205], v216 offset:18432
	ds_write_b128 v221, v[24:27] offset:36864
	v_lshl_add_u64 v[24:25], v[182:183], 0, s[40:41]
	global_load_dwordx4 v[24:27], v[24:25], off
	s_setprio 2
	v_mfma_f32_16x16x32_bf16 v[92:95], v[166:169], v[178:181], v[92:95]
	v_mfma_f32_16x16x32_bf16 v[88:91], v[174:177], v[178:181], v[88:91]
	v_mfma_f32_16x16x32_bf16 v[84:87], v[186:189], v[178:181], v[84:87]
	v_mfma_f32_16x16x32_bf16 v[80:83], v[194:197], v[178:181], v[80:83]
	ds_read_b128 v[178:181], v215 offset:4096
	ds_read_b128 v[206:209], v216 offset:20480
	ds_write_b128 v221, v[40:43] offset:40960
	v_lshl_add_u64 v[40:41], v[182:183], 0, s[46:47]
	global_load_dwordx4 v[40:43], v[40:41], off
	v_mfma_f32_16x16x32_bf16 v[76:79], v[166:169], v[190:193], v[76:79]
	v_mfma_f32_16x16x32_bf16 v[72:75], v[174:177], v[190:193], v[72:75]
	ds_read_b128 v[166:169], v215 offset:6144
	ds_read_b128 v[174:177], v216 offset:22528
	ds_write_b128 v221, v[48:51] offset:45056
	v_lshl_add_u64 v[48:49], v[182:183], 0, s[44:45]
	v_mfma_f32_16x16x32_bf16 v[68:71], v[186:189], v[190:193], v[68:71]
	global_load_dwordx4 v[48:51], v[48:49], off
	v_mfma_f32_16x16x32_bf16 v[64:67], v[194:197], v[190:193], v[64:67]
	s_waitcnt lgkmcnt(10)
	v_mfma_f32_16x16x32_bf16 v[124:127], v[198:201], v[162:165], v[124:127]
	ds_write_b128 v221, v[16:19] offset:49152
	global_load_dwordx4 v[16:19], v[210:211], off
	s_waitcnt lgkmcnt(8)
	v_mfma_f32_16x16x32_bf16 v[120:123], v[202:205], v[162:165], v[120:123]
	s_waitcnt lgkmcnt(5)
	v_mfma_f32_16x16x32_bf16 v[116:119], v[206:209], v[162:165], v[116:119]
	s_waitcnt lgkmcnt(2)
	v_mfma_f32_16x16x32_bf16 v[112:115], v[174:177], v[162:165], v[112:115]
	s_setprio 3
	v_mfma_f32_16x16x32_bf16 v[108:111], v[198:201], v[170:173], v[108:111]
	ds_write_b128 v221, v[28:31] offset:53248
	v_lshl_add_u64 v[28:29], v[210:211], 0, s[40:41]
	global_load_dwordx4 v[28:31], v[28:29], off
	v_mfma_f32_16x16x32_bf16 v[104:107], v[202:205], v[170:173], v[104:107]
	v_mfma_f32_16x16x32_bf16 v[100:103], v[206:209], v[170:173], v[100:103]
	v_mfma_f32_16x16x32_bf16 v[96:99], v[174:177], v[170:173], v[96:99]
	v_mfma_f32_16x16x32_bf16 v[92:95], v[198:201], v[178:181], v[92:95]
	ds_write_b128 v221, v[44:47] offset:57344
	v_lshl_add_u64 v[44:45], v[210:211], 0, s[46:47]
	global_load_dwordx4 v[44:47], v[44:45], off
	v_mfma_f32_16x16x32_bf16 v[88:91], v[202:205], v[178:181], v[88:91]
	v_mfma_f32_16x16x32_bf16 v[84:87], v[206:209], v[178:181], v[84:87]
	v_mfma_f32_16x16x32_bf16 v[80:83], v[174:177], v[178:181], v[80:83]
	v_mfma_f32_16x16x32_bf16 v[76:79], v[198:201], v[166:169], v[76:79]
	ds_write_b128 v221, v[52:55] offset:61440
	v_lshl_add_u64 v[52:53], v[210:211], 0, s[44:45]
	global_load_dwordx4 v[52:55], v[52:53], off
	v_mfma_f32_16x16x32_bf16 v[72:75], v[202:205], v[166:169], v[72:75]
	v_mfma_f32_16x16x32_bf16 v[68:71], v[206:209], v[166:169], v[68:71]
	v_mfma_f32_16x16x32_bf16 v[64:67], v[174:177], v[166:169], v[64:67]
	s_cmp_lt_u32 s39, 12
	s_cselect_b64 s[0:1], -1, 0
	s_and_b64 s[4:5], s[28:29], vcc
	v_lshl_add_u64 v[162:163], v[146:147], 0, v[184:185]
	v_cndmask_b32_e64 v164, v138, v134, s[4:5]
	v_cndmask_b32_e64 v165, v139, v135, s[4:5]
	v_cndmask_b32_e64 v183, v165, v163, s[0:1]
	v_cndmask_b32_e64 v182, v164, v162, s[0:1]
	v_lshl_add_u64 v[162:163], v[148:149], 0, v[184:185]
	v_cndmask_b32_e64 v164, v140, v136, s[4:5]
	v_cndmask_b32_e64 v165, v141, v137, s[4:5]
	s_setprio 0
	s_waitcnt lgkmcnt(0)
	s_barrier
; #define MFMA16(a, b, c) __builtin_amdgcn_mfma_f32_16x16x32_bf16((a), (b), (c), 0, 0, 0)
; DI void gld(u32x4v& r, const void* p) { asm volatile("global_load_dwordx4 %0, %1, off" : "=v"(r) : "v"(p) : "memory"); }
; #define WAIT_SET(N, a, b) asm volatile("s_waitcnt vmcnt(" #N ")" : "+v"(a[0]), "+v"(a[1]), "+v"(a[2]), "+v"(a[3]), "+v"(b[0]), "+v"(b[1]), "+v"(b[2]), "+v"(b[3]) :: "memory")
; DI void gemm_half(f32x4 (&acc)[4][4], const char* sa, const char* sb, int o0, int o1, u32x4v (&ra)[4], u32x4v (&rb)[4],
;                   char* stw, const bf16_t* Agn, const bf16_t* Bgn, int lda, int ldb) {
;   bf16x8 af0[4], bf0[4], af1[4], bf1[4];
; #pragma unroll
;   for (int i = 0; i < 4; ++i) { af0[i] = *(const bf16x8*)(sa + i * 16 * 128 + o0); bf0[i] = *(const bf16x8*)(sb + i * 16 * 128 + o0); }
;   __builtin_amdgcn_sched_barrier(0);
;   WAIT_SET(8, ra, rb);
; #pragma unroll
;   for (int g = 0; g < 8; ++g) {
; #pragma unroll
;     for (int ni = 0; ni < 4; ++ni) {
;       if (g < 4) acc[g][ni] = MFMA16(bf0[ni], af0[g], acc[g][ni]);
;       else acc[g - 4][ni] = MFMA16(bf1[ni], af1[g - 4], acc[g - 4][ni]);
;     }
;     if (g < 4) { af1[g] = *(const bf16x8*)(sa + g * 16 * 128 + o1); bf1[g] = *(const bf16x8*)(sb + g * 16 * 128 + o1);
;                  *(u32x4v*)(stw + g * 32 * 128) = ra[g]; gld(ra[g], Agn + (size_t)g * 32 * lda); }
;     else { *(u32x4v*)(stw + TILE_B + (g - 4) * 32 * 128) = rb[g - 4]; gld(rb[g - 4], Bgn + (size_t)(g - 4) * 32 * ldb); }
;     __builtin_amdgcn_sched_barrier(0);
;   }
; DI void gemm_kloop(f32x4 (&acc)[4][4], const bf16_t* Ag, const bf16_t* Bg, int lda, int ldb, int K, char* smem,
;                    u32x4v (&ra)[4], u32x4v (&rb)[4], u32x4v (&rc)[4], u32x4v (&rd)[4], bool pre,
;                    const bf16_t* Agn, const bf16_t* Bgn, bool hasnext) {
;     ...
;     const bf16_t* pa0 = kt + 4 < nk ? Ag + (size_t)(kt + 4) * 64 : ((last && hasnext) ? Agn : Alast);
;     const bf16_t* pb0 = kt + 4 < nk ? Bg + (size_t)(kt + 4) * 64 : ((last && hasnext) ? Bgn : Blast);
;     gemm_half(acc, sa0 + 2 * TILE_B, sb0 + 2 * TILE_B, o0, o1, ra, rb, st, pa0, pb0, lda, ldb);
;     __syncthreads();
;   }
;   if (!hasnext) { WAIT_SET(0, ra, rb); WAIT_SET(0, rc, rd); }
	v_cndmask_b32_e64 v211, v165, v163, s[0:1]
	v_cndmask_b32_e64 v210, v164, v162, s[0:1]
	ds_read_b128 v[162:165], v212 offset:32768
	ds_read_b128 v[166:169], v213 offset:49152
	ds_read_b128 v[170:173], v212 offset:34816
	ds_read_b128 v[174:177], v213 offset:51200
	ds_read_b128 v[178:181], v212 offset:36864
	ds_read_b128 v[186:189], v213 offset:53248
	ds_read_b128 v[190:193], v212 offset:38912
	ds_read_b128 v[194:197], v213 offset:55296
	s_waitcnt vmcnt(8)
	s_setprio 1
	s_waitcnt lgkmcnt(6)
	v_mfma_f32_16x16x32_bf16 v[124:127], v[166:169], v[162:165], v[124:127]
	s_waitcnt lgkmcnt(4)
	v_mfma_f32_16x16x32_bf16 v[120:123], v[174:177], v[162:165], v[120:123]
	s_waitcnt lgkmcnt(2)
	v_mfma_f32_16x16x32_bf16 v[116:119], v[186:189], v[162:165], v[116:119]
	s_waitcnt lgkmcnt(0)
	v_mfma_f32_16x16x32_bf16 v[112:115], v[194:197], v[162:165], v[112:115]
	ds_read_b128 v[162:165], v215 offset:32768
	ds_read_b128 v[198:201], v216 offset:49152
	ds_write_b128 v221, v[0:3]
	global_load_dwordx4 v[0:3], v[182:183], off
	v_mfma_f32_16x16x32_bf16 v[108:111], v[166:169], v[170:173], v[108:111]
	v_mfma_f32_16x16x32_bf16 v[104:107], v[174:177], v[170:173], v[104:107]
	v_mfma_f32_16x16x32_bf16 v[100:103], v[186:189], v[170:173], v[100:103]
	v_mfma_f32_16x16x32_bf16 v[96:99], v[194:197], v[170:173], v[96:99]
	ds_read_b128 v[170:173], v215 offset:34816
	ds_read_b128 v[202:205], v216 offset:51200
	ds_write_b128 v221, v[8:11] offset:4096
	v_lshl_add_u64 v[8:9], v[182:183], 0, s[40:41]
	global_load_dwordx4 v[8:11], v[8:9], off
	s_setprio 2
	v_mfma_f32_16x16x32_bf16 v[92:95], v[166:169], v[178:181], v[92:95]
	v_mfma_f32_16x16x32_bf16 v[88:91], v[174:177], v[178:181], v[88:91]
	v_mfma_f32_16x16x32_bf16 v[84:87], v[186:189], v[178:181], v[84:87]
	v_mfma_f32_16x16x32_bf16 v[80:83], v[194:197], v[178:181], v[80:83]
	ds_read_b128 v[178:181], v215 offset:36864
	ds_read_b128 v[206:209], v216 offset:53248
	ds_write_b128 v221, v[32:35] offset:8192
	v_lshl_add_u64 v[32:33], v[182:183], 0, s[46:47]
	global_load_dwordx4 v[32:35], v[32:33], off
	v_mfma_f32_16x16x32_bf16 v[76:79], v[166:169], v[190:193], v[76:79]
	v_mfma_f32_16x16x32_bf16 v[72:75], v[174:177], v[190:193], v[72:75]
	ds_read_b128 v[166:169], v215 offset:38912
	ds_read_b128 v[174:177], v216 offset:55296
	ds_write_b128 v221, v[56:59] offset:12288
	v_lshl_add_u64 v[56:57], v[182:183], 0, s[44:45]
	v_mfma_f32_16x16x32_bf16 v[68:71], v[186:189], v[190:193], v[68:71]
	global_load_dwordx4 v[56:59], v[56:57], off
	v_mfma_f32_16x16x32_bf16 v[64:67], v[194:197], v[190:193], v[64:67]
	s_waitcnt lgkmcnt(10)
	v_mfma_f32_16x16x32_bf16 v[124:127], v[198:201], v[162:165], v[124:127]
	ds_write_b128 v221, v[4:7] offset:16384
	global_load_dwordx4 v[4:7], v[210:211], off
	s_waitcnt lgkmcnt(8)
	v_mfma_f32_16x16x32_bf16 v[120:123], v[202:205], v[162:165], v[120:123]
	s_waitcnt lgkmcnt(5)
	v_mfma_f32_16x16x32_bf16 v[116:119], v[206:209], v[162:165], v[116:119]
	s_waitcnt lgkmcnt(2)
	v_mfma_f32_16x16x32_bf16 v[112:115], v[174:177], v[162:165], v[112:115]
	s_setprio 3
	v_mfma_f32_16x16x32_bf16 v[108:111], v[198:201], v[170:173], v[108:111]
	ds_write_b128 v221, v[20:23] offset:20480
	v_lshl_add_u64 v[20:21], v[210:211], 0, s[40:41]
	global_load_dwordx4 v[20:23], v[20:21], off
	v_mfma_f32_16x16x32_bf16 v[104:107], v[202:205], v[170:173], v[104:107]
	v_mfma_f32_16x16x32_bf16 v[100:103], v[206:209], v[170:173], v[100:103]
	v_mfma_f32_16x16x32_bf16 v[96:99], v[174:177], v[170:173], v[96:99]
	v_mfma_f32_16x16x32_bf16 v[92:95], v[198:201], v[178:181], v[92:95]
	ds_write_b128 v221, v[36:39] offset:24576
	v_lshl_add_u64 v[36:37], v[210:211], 0, s[46:47]
	global_load_dwordx4 v[36:39], v[36:37], off
	v_mfma_f32_16x16x32_bf16 v[88:91], v[202:205], v[178:181], v[88:91]
	v_mfma_f32_16x16x32_bf16 v[84:87], v[206:209], v[178:181], v[84:87]
	v_mfma_f32_16x16x32_bf16 v[80:83], v[174:177], v[178:181], v[80:83]
	v_mfma_f32_16x16x32_bf16 v[76:79], v[198:201], v[166:169], v[76:79]
	ds_write_b128 v221, v[60:63] offset:28672
	v_lshl_add_u64 v[60:61], v[210:211], 0, s[44:45]
	global_load_dwordx4 v[60:63], v[60:61], off
	v_mfma_f32_16x16x32_bf16 v[72:75], v[202:205], v[166:169], v[72:75]
	v_mfma_f32_16x16x32_bf16 v[68:71], v[206:209], v[166:169], v[68:71]
	v_mfma_f32_16x16x32_bf16 v[64:67], v[174:177], v[166:169], v[64:67]
	v_lshl_add_u64 v[146:147], v[146:147], 0, s[42:43]
	v_lshl_add_u64 v[148:149], v[148:149], 0, s[42:43]
	v_lshl_add_u64 v[150:151], v[150:151], 0, s[42:43]
	v_lshl_add_u64 v[152:153], v[152:153], 0, s[42:43]
	s_and_b64 vcc, exec, vcc
	s_setprio 0
	s_waitcnt lgkmcnt(0)
	s_barrier
	s_cbranch_vccz .LBB0_461
	s_and_b64 vcc, exec, s[26:27]
	s_cbranch_vccz .LBB0_464
	s_waitcnt vmcnt(0)
	s_waitcnt vmcnt(0)

; #define MFMA16(a, b, c) __builtin_amdgcn_mfma_f32_16x16x32_bf16((a), (b), (c), 0, 0, 0)
; DI void score_phase(const bf16_t* PROJ, unsigned short* SC, int c, char* smem, int bid, int nb) {
;     ...
;     for (int h = 0; h < 16; ++h) {
;       const bf16x8 qa0 = *(const bf16x8*)(rowp0 + C_IQ + h * 64 + fq * 8), qa1 = *(const bf16x8*)(rowp0 + C_IQ + h * 64 + 32 + fq * 8);
;       const bf16x8 qb0f = *(const bf16x8*)(rowp1 + C_IQ + h * 64 + fq * 8), qb1f = *(const bf16x8*)(rowp1 + C_IQ + h * 64 + 32 + fq * 8);
;       const float w0 = sW[fr * 17 + h], w1 = sW[(16 + fr) * 17 + h];
; #pragma unroll
;       for (int nj = 0; nj < 8; ++nj) {
;         f32x4 d = MFMA16(kf[nj][0], qa0, ((f32x4){0.f, 0.f, 0.f, 0.f}));
;         d = MFMA16(kf[nj][1], qa1, d);
;         f32x4 e = MFMA16(kf[nj][0], qb0f, ((f32x4){0.f, 0.f, 0.f, 0.f}));
;         e = MFMA16(kf[nj][1], qb1f, e);
; #pragma unroll
;         for (int r = 0; r < 4; ++r) { sc[0][nj][r] += w0 * fmaxf(d[r], 0.f); sc[1][nj][r] += w1 * fmaxf(e[r], 0.f); }
;       }
.LBB0_1061:
	v_lshl_add_u64 v[72:73], v[136:137], 0, s[6:7]
	v_add_co_u32_e32 v68, vcc, s2, v72
	s_add_u32 s6, s6, 0x80
	s_nop 0
	v_addc_co_u32_e32 v69, vcc, 0, v73, vcc
	v_add_co_u32_e32 v76, vcc, s3, v72
	global_load_dwordx4 v[64:67], v[68:69], off offset:128
	s_nop 0
	global_load_dwordx4 v[68:71], v[68:69], off offset:192
	v_addc_co_u32_e32 v77, vcc, 0, v73, vcc
	global_load_dwordx4 v[72:75], v[76:77], off offset:128
	s_nop 0
	global_load_dwordx4 v[76:79], v[76:77], off offset:192
	ds_read_b32 v152, v158
	ds_read_b32 v150, v158 offset:1088
	s_addc_u32 s7, s7, 0
	v_add_u32_e32 v158, 4, v158
	s_cmpk_eq_i32 s6, 0x800
	s_waitcnt vmcnt(3)
	s_setprio 1
	v_mfma_f32_16x16x32_bf16 v[160:163], v[0:3], v[64:67], 0
	s_waitcnt vmcnt(1)
	v_mfma_f32_16x16x32_bf16 v[164:167], v[0:3], v[72:75], 0
	v_mfma_f32_16x16x32_bf16 v[160:163], v[4:7], v[68:71], v[160:163]
	s_waitcnt vmcnt(0)
	v_mfma_f32_16x16x32_bf16 v[164:167], v[4:7], v[76:79], v[164:167]
	s_nop 5
	v_max_f32_e32 v160, 0, v160
	s_nop 0
	v_max_f32_e32 v164, 0, v164
	v_max_f32_e32 v161, 0, v161
	v_max_f32_e32 v165, 0, v165
	s_waitcnt lgkmcnt(1)
	v_pk_fma_f32 v[146:147], v[152:153], v[160:161], v[146:147] op_sel_hi:[0,1,1]
	v_max_f32_e32 v160, 0, v162
	v_max_f32_e32 v162, 0, v166
	v_max_f32_e32 v161, 0, v163
	v_max_f32_e32 v163, 0, v167
	v_pk_fma_f32 v[148:149], v[152:153], v[160:161], v[148:149] op_sel_hi:[0,1,1]
	s_waitcnt lgkmcnt(0)
	v_pk_fma_f32 v[114:115], v[150:151], v[162:163], v[114:115] op_sel_hi:[0,1,1]
	v_mfma_f32_16x16x32_bf16 v[160:163], v[8:11], v[64:67], 0
	v_fma_f32 v112, v150, v164, v112
	v_fma_f32 v113, v150, v165, v113
	v_mfma_f32_16x16x32_bf16 v[164:167], v[8:11], v[72:75], 0
	v_mfma_f32_16x16x32_bf16 v[160:163], v[12:15], v[68:71], v[160:163]
	v_mfma_f32_16x16x32_bf16 v[164:167], v[12:15], v[76:79], v[164:167]
	s_nop 6
	v_max_f32_e32 v160, 0, v160
	v_max_f32_e32 v164, 0, v164
	v_max_f32_e32 v161, 0, v161
	v_max_f32_e32 v165, 0, v165
	v_pk_fma_f32 v[142:143], v[152:153], v[160:161], v[142:143] op_sel_hi:[0,1,1]
	v_max_f32_e32 v160, 0, v162
	v_max_f32_e32 v162, 0, v166
	v_max_f32_e32 v161, 0, v163
	v_max_f32_e32 v163, 0, v167
	v_pk_fma_f32 v[144:145], v[152:153], v[160:161], v[144:145] op_sel_hi:[0,1,1]
	v_pk_fma_f32 v[110:111], v[150:151], v[162:163], v[110:111] op_sel_hi:[0,1,1]
	v_mfma_f32_16x16x32_bf16 v[160:163], v[16:19], v[64:67], 0
	v_fma_f32 v108, v150, v164, v108
	v_fma_f32 v109, v150, v165, v109
	v_mfma_f32_16x16x32_bf16 v[164:167], v[16:19], v[72:75], 0
	v_mfma_f32_16x16x32_bf16 v[160:163], v[20:23], v[68:71], v[160:163]
	v_mfma_f32_16x16x32_bf16 v[164:167], v[20:23], v[76:79], v[164:167]
	s_nop 6
	v_max_f32_e32 v160, 0, v160
	v_max_f32_e32 v164, 0, v164
	v_max_f32_e32 v161, 0, v161
	v_max_f32_e32 v165, 0, v165
	v_pk_fma_f32 v[138:139], v[152:153], v[160:161], v[138:139] op_sel_hi:[0,1,1]
	v_max_f32_e32 v160, 0, v162
	v_max_f32_e32 v162, 0, v166
	v_max_f32_e32 v161, 0, v163
	v_max_f32_e32 v163, 0, v167
	v_pk_fma_f32 v[140:141], v[152:153], v[160:161], v[140:141] op_sel_hi:[0,1,1]
	v_pk_fma_f32 v[106:107], v[150:151], v[162:163], v[106:107] op_sel_hi:[0,1,1]
	v_mfma_f32_16x16x32_bf16 v[160:163], v[24:27], v[64:67], 0
	v_fma_f32 v104, v150, v164, v104
	v_fma_f32 v105, v150, v165, v105
	v_mfma_f32_16x16x32_bf16 v[164:167], v[24:27], v[72:75], 0
	v_mfma_f32_16x16x32_bf16 v[160:163], v[28:31], v[68:71], v[160:163]
	v_mfma_f32_16x16x32_bf16 v[164:167], v[28:31], v[76:79], v[164:167]
	s_nop 6
	v_max_f32_e32 v160, 0, v160
	v_max_f32_e32 v164, 0, v164
	v_max_f32_e32 v161, 0, v161
	v_max_f32_e32 v165, 0, v165
	v_pk_fma_f32 v[132:133], v[152:153], v[160:161], v[132:133] op_sel_hi:[0,1,1]
	v_max_f32_e32 v160, 0, v162
	v_max_f32_e32 v162, 0, v166
	v_max_f32_e32 v161, 0, v163
	v_max_f32_e32 v163, 0, v167
	v_pk_fma_f32 v[134:135], v[152:153], v[160:161], v[134:135] op_sel_hi:[0,1,1]
	v_pk_fma_f32 v[102:103], v[150:151], v[162:163], v[102:103] op_sel_hi:[0,1,1]
	v_mfma_f32_16x16x32_bf16 v[160:163], v[32:35], v[64:67], 0
	v_fma_f32 v100, v150, v164, v100
	v_fma_f32 v101, v150, v165, v101
	v_mfma_f32_16x16x32_bf16 v[164:167], v[32:35], v[72:75], 0
	v_mfma_f32_16x16x32_bf16 v[160:163], v[36:39], v[68:71], v[160:163]
	v_mfma_f32_16x16x32_bf16 v[164:167], v[36:39], v[76:79], v[164:167]
	s_nop 6
	v_max_f32_e32 v160, 0, v160
	v_max_f32_e32 v164, 0, v164
	v_max_f32_e32 v161, 0, v161
	v_max_f32_e32 v165, 0, v165
	v_pk_fma_f32 v[128:129], v[152:153], v[160:161], v[128:129] op_sel_hi:[0,1,1]
	v_max_f32_e32 v160, 0, v162
	v_max_f32_e32 v162, 0, v166
	v_max_f32_e32 v161, 0, v163
	v_max_f32_e32 v163, 0, v167
	v_pk_fma_f32 v[130:131], v[152:153], v[160:161], v[130:131] op_sel_hi:[0,1,1]
	v_pk_fma_f32 v[98:99], v[150:151], v[162:163], v[98:99] op_sel_hi:[0,1,1]
	v_mfma_f32_16x16x32_bf16 v[160:163], v[40:43], v[64:67], 0
	v_fma_f32 v96, v150, v164, v96
	v_fma_f32 v97, v150, v165, v97
	v_mfma_f32_16x16x32_bf16 v[164:167], v[40:43], v[72:75], 0
	v_mfma_f32_16x16x32_bf16 v[160:163], v[44:47], v[68:71], v[160:163]
	v_mfma_f32_16x16x32_bf16 v[164:167], v[44:47], v[76:79], v[164:167]
	s_nop 6
	v_max_f32_e32 v160, 0, v160
	v_max_f32_e32 v164, 0, v164
	v_max_f32_e32 v161, 0, v161
	v_max_f32_e32 v165, 0, v165
	v_pk_fma_f32 v[124:125], v[152:153], v[160:161], v[124:125] op_sel_hi:[0,1,1]
	v_max_f32_e32 v160, 0, v162
	v_max_f32_e32 v162, 0, v166
	v_max_f32_e32 v161, 0, v163
	v_max_f32_e32 v163, 0, v167
	v_pk_fma_f32 v[126:127], v[152:153], v[160:161], v[126:127] op_sel_hi:[0,1,1]
	v_pk_fma_f32 v[94:95], v[150:151], v[162:163], v[94:95] op_sel_hi:[0,1,1]
	v_mfma_f32_16x16x32_bf16 v[160:163], v[48:51], v[64:67], 0
	v_fma_f32 v92, v150, v164, v92
	v_fma_f32 v93, v150, v165, v93
	v_mfma_f32_16x16x32_bf16 v[64:67], v[56:59], v[64:67], 0
; #define MFMA16(a, b, c) __builtin_amdgcn_mfma_f32_16x16x32_bf16((a), (b), (c), 0, 0, 0)
; DI void score_phase(const bf16_t* PROJ, unsigned short* SC, int c, char* smem, int bid, int nb) {
;     ...
;       for (int nj = 0; nj < 8; ++nj) {
;         f32x4 d = MFMA16(kf[nj][0], qa0, ((f32x4){0.f, 0.f, 0.f, 0.f}));
;         d = MFMA16(kf[nj][1], qa1, d);
;         f32x4 e = MFMA16(kf[nj][0], qb0f, ((f32x4){0.f, 0.f, 0.f, 0.f}));
;         e = MFMA16(kf[nj][1], qb1f, e);
; #pragma unroll
;         for (int r = 0; r < 4; ++r) { sc[0][nj][r] += w0 * fmaxf(d[r], 0.f); sc[1][nj][r] += w1 * fmaxf(e[r], 0.f); }
;       }
;     }
; #pragma unroll
;     for (int mi = 0; mi < 2; ++mi) {
;       const int t = q0 + mi * 16 + fr;
;       unsigned short* op = SC + (size_t)(t - c * 4096) * S + s0 + fq * 4;
; #pragma unroll
;       for (int nj = 0; nj < 8; ++nj) {
;         unsigned w0 = __builtin_bit_cast(unsigned, __builtin_amdgcn_cvt_pkrtz(sc[mi][nj][0], sc[mi][nj][1]));
;         unsigned w1 = __builtin_bit_cast(unsigned, __builtin_amdgcn_cvt_pkrtz(sc[mi][nj][2], sc[mi][nj][3]));
;         const unsigned m0 = ((w0 >> 15) & 0x00010001u) * 0xffffu, m1 = ((w1 >> 15) & 0x00010001u) * 0xffffu;
;         w0 ^= (m0 | 0x80008000u); w1 ^= (m1 | 0x80008000u);
;         uint2 st2; st2.x = w0; st2.y = w1;
;         *(uint2*)(op + nj * 16) = st2;
	v_mfma_f32_16x16x32_bf16 v[164:167], v[48:51], v[72:75], 0
	v_mfma_f32_16x16x32_bf16 v[160:163], v[52:55], v[68:71], v[160:163]
	v_mfma_f32_16x16x32_bf16 v[64:67], v[60:63], v[68:71], v[64:67]
	v_mfma_f32_16x16x32_bf16 v[68:71], v[56:59], v[72:75], 0
	s_nop 5
	v_max_f32_e32 v160, 0, v160
	v_mfma_f32_16x16x32_bf16 v[164:167], v[52:55], v[76:79], v[164:167]
	v_max_f32_e32 v64, 0, v64
	v_max_f32_e32 v65, 0, v65
	v_mfma_f32_16x16x32_bf16 v[68:71], v[60:63], v[76:79], v[68:71]
	v_fma_f32 v116, v152, v64, v116
	v_fma_f32 v117, v152, v65, v117
	s_nop 1
	s_nop 0
	v_max_f32_e32 v164, 0, v164
	v_max_f32_e32 v161, 0, v161
	v_max_f32_e32 v165, 0, v165
	v_pk_fma_f32 v[120:121], v[152:153], v[160:161], v[120:121] op_sel_hi:[0,1,1]
	v_max_f32_e32 v160, 0, v162
	v_max_f32_e32 v69, 0, v69
	v_max_f32_e32 v64, v66, v66
	v_max_f32_e32 v66, 0, v70
	v_max_f32_e32 v162, 0, v166
	v_max_f32_e32 v64, 0, v64
	v_max_f32_e32 v65, 0, v67
	v_max_f32_e32 v161, 0, v163
	v_max_f32_e32 v159, v167, v167
	v_pk_fma_f32 v[118:119], v[152:153], v[64:65], v[118:119] op_sel_hi:[0,1,1]
	v_max_f32_e32 v64, v71, v71
	v_max_f32_e32 v163, 0, v159
	v_max_f32_e32 v68, 0, v68
	v_max_f32_e32 v67, 0, v64
	v_pk_fma_f32 v[88:89], v[150:151], v[164:165], v[88:89] op_sel_hi:[0,1,1]
	v_pk_fma_f32 v[122:123], v[152:153], v[160:161], v[122:123] op_sel_hi:[0,1,1]
	v_pk_fma_f32 v[90:91], v[150:151], v[162:163], v[90:91] op_sel_hi:[0,1,1]
	v_pk_fma_f32 v[84:85], v[150:151], v[68:69], v[84:85] op_sel_hi:[0,1,1]
	v_pk_fma_f32 v[86:87], v[150:151], v[66:67], v[86:87] op_sel_hi:[0,1,1]
	s_setprio 0
	s_cbranch_scc0 .LBB0_1061
	v_add_u32_e32 v0, v155, v157
	v_ashrrev_i32_e32 v1, 31, v0
	v_lshlrev_b64 v[4:5], 15, v[0:1]
	v_cvt_pkrtz_f16_f32 v1, v146, v147
	v_cvt_pkrtz_f16_f32 v6, v148, v149
	v_lshrrev_b32_e32 v7, 15, v6
	v_lshrrev_b32_e32 v8, 15, v1
	v_and_b32_e32 v7, 0x10001, v7
	v_and_b32_e32 v8, 0x10001, v8
	s_ashr_i32 s5, s4, 31
	v_mul_u32_u24_e32 v8, 0xffff, v8
	v_mul_u32_u24_e32 v7, 0xffff, v7
	v_lshl_add_u64 v[2:3], s[4:5], 1, v[80:81]
	v_or_b32_e32 v7, 0x80008000, v7
	v_or_b32_e32 v8, 0x80008000, v8
	v_lshl_add_u64 v[4:5], v[2:3], 0, v[4:5]
	v_xor_b32_e32 v7, v7, v6
	v_xor_b32_e32 v6, v8, v1
	global_store_dwordx2 v[4:5], v[6:7], off
	v_cvt_pkrtz_f16_f32 v1, v142, v143
	v_cvt_pkrtz_f16_f32 v6, v144, v145
	v_lshrrev_b32_e32 v7, 15, v6
	v_lshrrev_b32_e32 v8, 15, v1
	v_and_b32_e32 v7, 0x10001, v7
	v_and_b32_e32 v8, 0x10001, v8
	v_mul_u32_u24_e32 v8, 0xffff, v8
	v_mul_u32_u24_e32 v7, 0xffff, v7
	v_or_b32_e32 v7, 0x80008000, v7
	v_or_b32_e32 v8, 0x80008000, v8
	v_xor_b32_e32 v7, v7, v6
	v_xor_b32_e32 v6, v8, v1
	global_store_dwordx2 v[4:5], v[6:7], off offset:32
	v_cvt_pkrtz_f16_f32 v1, v138, v139
	v_cvt_pkrtz_f16_f32 v6, v140, v141
	v_lshrrev_b32_e32 v7, 15, v6
	v_lshrrev_b32_e32 v8, 15, v1
	v_and_b32_e32 v7, 0x10001, v7
	v_and_b32_e32 v8, 0x10001, v8
	v_mul_u32_u24_e32 v8, 0xffff, v8
	v_mul_u32_u24_e32 v7, 0xffff, v7
	v_or_b32_e32 v7, 0x80008000, v7
	v_or_b32_e32 v8, 0x80008000, v8
	v_xor_b32_e32 v7, v7, v6
	v_xor_b32_e32 v6, v8, v1
	global_store_dwordx2 v[4:5], v[6:7], off offset:64
	v_cvt_pkrtz_f16_f32 v1, v132, v133
	v_cvt_pkrtz_f16_f32 v6, v134, v135
	v_lshrrev_b32_e32 v7, 15, v6
	v_lshrrev_b32_e32 v8, 15, v1
	v_and_b32_e32 v7, 0x10001, v7
	v_and_b32_e32 v8, 0x10001, v8
	v_mul_u32_u24_e32 v8, 0xffff, v8
	v_mul_u32_u24_e32 v7, 0xffff, v7
	v_or_b32_e32 v7, 0x80008000, v7
	v_or_b32_e32 v8, 0x80008000, v8
	v_xor_b32_e32 v7, v7, v6
	v_xor_b32_e32 v6, v8, v1
	global_store_dwordx2 v[4:5], v[6:7], off offset:96
	v_cvt_pkrtz_f16_f32 v1, v128, v129
	v_cvt_pkrtz_f16_f32 v6, v130, v131
	v_lshrrev_b32_e32 v7, 15, v6
	v_lshrrev_b32_e32 v8, 15, v1
	v_and_b32_e32 v7, 0x10001, v7
	v_and_b32_e32 v8, 0x10001, v8
	v_mul_u32_u24_e32 v8, 0xffff, v8
	v_mul_u32_u24_e32 v7, 0xffff, v7
	v_or_b32_e32 v7, 0x80008000, v7
	v_or_b32_e32 v8, 0x80008000, v8
	v_xor_b32_e32 v7, v7, v6
	v_xor_b32_e32 v6, v8, v1
	global_store_dwordx2 v[4:5], v[6:7], off offset:128
	v_cvt_pkrtz_f16_f32 v1, v124, v125
	v_cvt_pkrtz_f16_f32 v6, v126, v127
	v_lshrrev_b32_e32 v7, 15, v6
	v_lshrrev_b32_e32 v8, 15, v1
	v_and_b32_e32 v7, 0x10001, v7
	v_and_b32_e32 v8, 0x10001, v8
	v_mul_u32_u24_e32 v8, 0xffff, v8
	v_mul_u32_u24_e32 v7, 0xffff, v7
	v_or_b32_e32 v7, 0x80008000, v7
	v_or_b32_e32 v8, 0x80008000, v8
	v_xor_b32_e32 v7, v7, v6
	v_xor_b32_e32 v6, v8, v1
	global_store_dwordx2 v[4:5], v[6:7], off offset:160
	v_cvt_pkrtz_f16_f32 v1, v120, v121
	v_cvt_pkrtz_f16_f32 v6, v122, v123
	v_lshrrev_b32_e32 v7, 15, v6
; DI void score_phase(const bf16_t* PROJ, unsigned short* SC, int c, char* smem, int bid, int nb) {
;     ...
; #pragma unroll
;     for (int mi = 0; mi < 2; ++mi) {
;       const int t = q0 + mi * 16 + fr;
;       unsigned short* op = SC + (size_t)(t - c * 4096) * S + s0 + fq * 4;
; #pragma unroll
;       for (int nj = 0; nj < 8; ++nj) {
;         unsigned w0 = __builtin_bit_cast(unsigned, __builtin_amdgcn_cvt_pkrtz(sc[mi][nj][0], sc[mi][nj][1]));
;         unsigned w1 = __builtin_bit_cast(unsigned, __builtin_amdgcn_cvt_pkrtz(sc[mi][nj][2], sc[mi][nj][3]));
;         const unsigned m0 = ((w0 >> 15) & 0x00010001u) * 0xffffu, m1 = ((w1 >> 15) & 0x00010001u) * 0xffffu;
;         w0 ^= (m0 | 0x80008000u); w1 ^= (m1 | 0x80008000u);
;         uint2 st2; st2.x = w0; st2.y = w1;
;         *(uint2*)(op + nj * 16) = st2;
;       }
;     }
;   }
	v_lshrrev_b32_e32 v8, 15, v1
	v_and_b32_e32 v7, 0x10001, v7
	v_and_b32_e32 v8, 0x10001, v8
	v_mul_u32_u24_e32 v8, 0xffff, v8
	v_mul_u32_u24_e32 v7, 0xffff, v7
	v_or_b32_e32 v7, 0x80008000, v7
	v_or_b32_e32 v8, 0x80008000, v8
	v_xor_b32_e32 v7, v7, v6
	v_xor_b32_e32 v6, v8, v1
	global_store_dwordx2 v[4:5], v[6:7], off offset:192
	v_cvt_pkrtz_f16_f32 v1, v116, v117
	v_cvt_pkrtz_f16_f32 v6, v118, v119
	v_lshrrev_b32_e32 v7, 15, v6
	v_lshrrev_b32_e32 v8, 15, v1
	v_and_b32_e32 v7, 0x10001, v7
	v_and_b32_e32 v8, 0x10001, v8
	v_mul_u32_u24_e32 v8, 0xffff, v8
	v_mul_u32_u24_e32 v7, 0xffff, v7
	v_or_b32_e32 v7, 0x80008000, v7
	v_or_b32_e32 v8, 0x80008000, v8
	v_or_b32_e32 v0, 16, v0
	v_xor_b32_e32 v7, v7, v6
	v_xor_b32_e32 v6, v8, v1
	v_ashrrev_i32_e32 v1, 31, v0
	v_lshlrev_b64 v[0:1], 15, v[0:1]
	v_lshl_add_u64 v[0:1], v[2:3], 0, v[0:1]
	v_cvt_pkrtz_f16_f32 v2, v112, v113
	v_cvt_pkrtz_f16_f32 v3, v114, v115
	global_store_dwordx2 v[4:5], v[6:7], off offset:224
	v_lshrrev_b32_e32 v4, 15, v3
	v_lshrrev_b32_e32 v5, 15, v2
	v_and_b32_e32 v4, 0x10001, v4
	v_and_b32_e32 v5, 0x10001, v5
	v_mul_u32_u24_e32 v5, 0xffff, v5
	v_mul_u32_u24_e32 v4, 0xffff, v4
	v_or_b32_e32 v4, 0x80008000, v4
	v_or_b32_e32 v5, 0x80008000, v5
	v_xor_b32_e32 v3, v4, v3
	v_xor_b32_e32 v2, v5, v2
	global_store_dwordx2 v[0:1], v[2:3], off
	v_cvt_pkrtz_f16_f32 v2, v108, v109
	v_cvt_pkrtz_f16_f32 v3, v110, v111
	v_lshrrev_b32_e32 v4, 15, v3
	v_lshrrev_b32_e32 v5, 15, v2
	v_and_b32_e32 v4, 0x10001, v4
	v_and_b32_e32 v5, 0x10001, v5
	v_mul_u32_u24_e32 v5, 0xffff, v5
	v_mul_u32_u24_e32 v4, 0xffff, v4
	v_or_b32_e32 v4, 0x80008000, v4
	v_or_b32_e32 v5, 0x80008000, v5
	v_xor_b32_e32 v3, v4, v3
	v_xor_b32_e32 v2, v5, v2
	global_store_dwordx2 v[0:1], v[2:3], off offset:32
	v_cvt_pkrtz_f16_f32 v2, v104, v105
	v_cvt_pkrtz_f16_f32 v3, v106, v107
	v_lshrrev_b32_e32 v4, 15, v3
	v_lshrrev_b32_e32 v5, 15, v2
	v_and_b32_e32 v4, 0x10001, v4
	v_and_b32_e32 v5, 0x10001, v5
	v_mul_u32_u24_e32 v5, 0xffff, v5
	v_mul_u32_u24_e32 v4, 0xffff, v4
	v_or_b32_e32 v4, 0x80008000, v4
	v_or_b32_e32 v5, 0x80008000, v5
	v_xor_b32_e32 v3, v4, v3
	v_xor_b32_e32 v2, v5, v2
	global_store_dwordx2 v[0:1], v[2:3], off offset:64
	v_cvt_pkrtz_f16_f32 v2, v100, v101
	v_cvt_pkrtz_f16_f32 v3, v102, v103
	v_lshrrev_b32_e32 v4, 15, v3
	v_lshrrev_b32_e32 v5, 15, v2
	v_and_b32_e32 v4, 0x10001, v4
	v_and_b32_e32 v5, 0x10001, v5
	v_mul_u32_u24_e32 v5, 0xffff, v5
	v_mul_u32_u24_e32 v4, 0xffff, v4
	v_or_b32_e32 v4, 0x80008000, v4
	v_or_b32_e32 v5, 0x80008000, v5
	v_xor_b32_e32 v3, v4, v3
	v_xor_b32_e32 v2, v5, v2
	global_store_dwordx2 v[0:1], v[2:3], off offset:96
	v_cvt_pkrtz_f16_f32 v2, v96, v97
	v_cvt_pkrtz_f16_f32 v3, v98, v99
	v_lshrrev_b32_e32 v4, 15, v3
	v_lshrrev_b32_e32 v5, 15, v2
	v_and_b32_e32 v4, 0x10001, v4
	v_and_b32_e32 v5, 0x10001, v5
	v_mul_u32_u24_e32 v5, 0xffff, v5
	v_mul_u32_u24_e32 v4, 0xffff, v4
	v_or_b32_e32 v4, 0x80008000, v4
	v_or_b32_e32 v5, 0x80008000, v5
	v_xor_b32_e32 v3, v4, v3
	v_xor_b32_e32 v2, v5, v2
	global_store_dwordx2 v[0:1], v[2:3], off offset:128
	v_cvt_pkrtz_f16_f32 v2, v92, v93
	v_cvt_pkrtz_f16_f32 v3, v94, v95
	v_lshrrev_b32_e32 v4, 15, v3
	v_lshrrev_b32_e32 v5, 15, v2
	v_and_b32_e32 v4, 0x10001, v4
	v_and_b32_e32 v5, 0x10001, v5
	v_mul_u32_u24_e32 v5, 0xffff, v5
	v_mul_u32_u24_e32 v4, 0xffff, v4
	v_or_b32_e32 v4, 0x80008000, v4
	v_or_b32_e32 v5, 0x80008000, v5
	v_xor_b32_e32 v3, v4, v3
	v_xor_b32_e32 v2, v5, v2
	global_store_dwordx2 v[0:1], v[2:3], off offset:160
	v_cvt_pkrtz_f16_f32 v2, v88, v89
	v_cvt_pkrtz_f16_f32 v3, v90, v91
	v_lshrrev_b32_e32 v4, 15, v3
	v_lshrrev_b32_e32 v5, 15, v2
	v_and_b32_e32 v4, 0x10001, v4
	v_and_b32_e32 v5, 0x10001, v5
	v_mul_u32_u24_e32 v5, 0xffff, v5
	v_mul_u32_u24_e32 v4, 0xffff, v4
	v_or_b32_e32 v4, 0x80008000, v4
	v_or_b32_e32 v5, 0x80008000, v5
	v_xor_b32_e32 v3, v4, v3
	v_xor_b32_e32 v2, v5, v2
	global_store_dwordx2 v[0:1], v[2:3], off offset:192
	v_cvt_pkrtz_f16_f32 v2, v84, v85
	v_cvt_pkrtz_f16_f32 v3, v86, v87
	v_lshrrev_b32_e32 v4, 15, v3
	v_lshrrev_b32_e32 v5, 15, v2
	v_and_b32_e32 v4, 0x10001, v4
	v_and_b32_e32 v5, 0x10001, v5
	v_mul_u32_u24_e32 v5, 0xffff, v5
	v_mul_u32_u24_e32 v4, 0xffff, v4
	v_readlane_b32 s2, v249, 43
	v_or_b32_e32 v4, 0x80008000, v4
	v_or_b32_e32 v5, 0x80008000, v5
	s_add_i32 s12, s12, s2
	v_xor_b32_e32 v3, v4, v3
	v_xor_b32_e32 v2, v5, v2
	s_cmp_ge_i32 s12, s8
	v_readlane_b32 s3, v249, 44
	global_store_dwordx2 v[0:1], v[2:3], off offset:224
	s_cbranch_scc0 .LBB0_1055

; #define MFMA16(a, b, c) __builtin_amdgcn_mfma_f32_16x16x32_bf16((a), (b), (c), 0, 0, 0)
; DI void score_phase(const bf16_t* PROJ, unsigned short* SC, int c, char* smem, int bid, int nb) {
;     ...
;     for (int h = 0; h < 16; ++h) {
;       const bf16x8 qa0 = *(const bf16x8*)(rowp0 + C_IQ + h * 64 + fq * 8), qa1 = *(const bf16x8*)(rowp0 + C_IQ + h * 64 + 32 + fq * 8);
;       const bf16x8 qb0f = *(const bf16x8*)(rowp1 + C_IQ + h * 64 + fq * 8), qb1f = *(const bf16x8*)(rowp1 + C_IQ + h * 64 + 32 + fq * 8);
;       const float w0 = sW[fr * 17 + h], w1 = sW[(16 + fr) * 17 + h];
; #pragma unroll
;       for (int nj = 0; nj < 8; ++nj) {
;         f32x4 d = MFMA16(kf[nj][0], qa0, ((f32x4){0.f, 0.f, 0.f, 0.f}));
;         d = MFMA16(kf[nj][1], qa1, d);
;         f32x4 e = MFMA16(kf[nj][0], qb0f, ((f32x4){0.f, 0.f, 0.f, 0.f}));
;         e = MFMA16(kf[nj][1], qb1f, e);
; #pragma unroll
;         for (int r = 0; r < 4; ++r) { sc[0][nj][r] += w0 * fmaxf(d[r], 0.f); sc[1][nj][r] += w1 * fmaxf(e[r], 0.f); }
;       }
.LBB0_1343:
	v_lshl_add_u64 v[72:73], v[136:137], 0, s[6:7]
	v_add_co_u32_e32 v68, vcc, s2, v72
	s_add_u32 s6, s6, 0x80
	s_nop 0
	v_addc_co_u32_e32 v69, vcc, 0, v73, vcc
	v_add_co_u32_e32 v76, vcc, s3, v72
	global_load_dwordx4 v[64:67], v[68:69], off offset:128
	s_nop 0
	global_load_dwordx4 v[68:71], v[68:69], off offset:192
	v_addc_co_u32_e32 v77, vcc, 0, v73, vcc
	global_load_dwordx4 v[72:75], v[76:77], off offset:128
	s_nop 0
	global_load_dwordx4 v[76:79], v[76:77], off offset:192
	ds_read_b32 v152, v158
	ds_read_b32 v150, v158 offset:1088
	s_addc_u32 s7, s7, 0
	v_add_u32_e32 v158, 4, v158
	s_cmpk_eq_i32 s6, 0x800
	s_waitcnt vmcnt(3)
	s_setprio 1
	v_mfma_f32_16x16x32_bf16 v[160:163], v[0:3], v[64:67], 0
	s_waitcnt vmcnt(1)
	v_mfma_f32_16x16x32_bf16 v[164:167], v[0:3], v[72:75], 0
	v_mfma_f32_16x16x32_bf16 v[160:163], v[4:7], v[68:71], v[160:163]
	s_waitcnt vmcnt(0)
	v_mfma_f32_16x16x32_bf16 v[164:167], v[4:7], v[76:79], v[164:167]
	s_nop 5
	v_max_f32_e32 v160, 0, v160
	s_nop 0
	v_max_f32_e32 v164, 0, v164
	v_max_f32_e32 v161, 0, v161
	v_max_f32_e32 v165, 0, v165
	s_waitcnt lgkmcnt(1)
	v_pk_fma_f32 v[146:147], v[152:153], v[160:161], v[146:147] op_sel_hi:[0,1,1]
	v_max_f32_e32 v160, 0, v162
	v_max_f32_e32 v162, 0, v166
	v_max_f32_e32 v161, 0, v163
	v_max_f32_e32 v163, 0, v167
	v_pk_fma_f32 v[148:149], v[152:153], v[160:161], v[148:149] op_sel_hi:[0,1,1]
	s_waitcnt lgkmcnt(0)
	v_pk_fma_f32 v[114:115], v[150:151], v[162:163], v[114:115] op_sel_hi:[0,1,1]
	v_mfma_f32_16x16x32_bf16 v[160:163], v[8:11], v[64:67], 0
	v_fma_f32 v112, v150, v164, v112
	v_fma_f32 v113, v150, v165, v113
	v_mfma_f32_16x16x32_bf16 v[164:167], v[8:11], v[72:75], 0
	v_mfma_f32_16x16x32_bf16 v[160:163], v[12:15], v[68:71], v[160:163]
	v_mfma_f32_16x16x32_bf16 v[164:167], v[12:15], v[76:79], v[164:167]
	s_nop 6
	v_max_f32_e32 v160, 0, v160
	v_max_f32_e32 v164, 0, v164
	v_max_f32_e32 v161, 0, v161
	v_max_f32_e32 v165, 0, v165
	v_pk_fma_f32 v[142:143], v[152:153], v[160:161], v[142:143] op_sel_hi:[0,1,1]
	v_max_f32_e32 v160, 0, v162
	v_max_f32_e32 v162, 0, v166
	v_max_f32_e32 v161, 0, v163
	v_max_f32_e32 v163, 0, v167
	v_pk_fma_f32 v[144:145], v[152:153], v[160:161], v[144:145] op_sel_hi:[0,1,1]
	v_pk_fma_f32 v[110:111], v[150:151], v[162:163], v[110:111] op_sel_hi:[0,1,1]
	v_mfma_f32_16x16x32_bf16 v[160:163], v[16:19], v[64:67], 0
	v_fma_f32 v108, v150, v164, v108
	v_fma_f32 v109, v150, v165, v109
	v_mfma_f32_16x16x32_bf16 v[164:167], v[16:19], v[72:75], 0
	v_mfma_f32_16x16x32_bf16 v[160:163], v[20:23], v[68:71], v[160:163]
	v_mfma_f32_16x16x32_bf16 v[164:167], v[20:23], v[76:79], v[164:167]
	s_nop 6
	v_max_f32_e32 v160, 0, v160
	v_max_f32_e32 v164, 0, v164
	v_max_f32_e32 v161, 0, v161
	v_max_f32_e32 v165, 0, v165
	v_pk_fma_f32 v[138:139], v[152:153], v[160:161], v[138:139] op_sel_hi:[0,1,1]
	v_max_f32_e32 v160, 0, v162
	v_max_f32_e32 v162, 0, v166
	v_max_f32_e32 v161, 0, v163
	v_max_f32_e32 v163, 0, v167
	v_pk_fma_f32 v[140:141], v[152:153], v[160:161], v[140:141] op_sel_hi:[0,1,1]
	v_pk_fma_f32 v[106:107], v[150:151], v[162:163], v[106:107] op_sel_hi:[0,1,1]
	v_mfma_f32_16x16x32_bf16 v[160:163], v[24:27], v[64:67], 0
	v_fma_f32 v104, v150, v164, v104
	v_fma_f32 v105, v150, v165, v105
	v_mfma_f32_16x16x32_bf16 v[164:167], v[24:27], v[72:75], 0
	v_mfma_f32_16x16x32_bf16 v[160:163], v[28:31], v[68:71], v[160:163]
	v_mfma_f32_16x16x32_bf16 v[164:167], v[28:31], v[76:79], v[164:167]
	s_nop 6
	v_max_f32_e32 v160, 0, v160
	v_max_f32_e32 v164, 0, v164
	v_max_f32_e32 v161, 0, v161
	v_max_f32_e32 v165, 0, v165
	v_pk_fma_f32 v[132:133], v[152:153], v[160:161], v[132:133] op_sel_hi:[0,1,1]
	v_max_f32_e32 v160, 0, v162
	v_max_f32_e32 v162, 0, v166
	v_max_f32_e32 v161, 0, v163
	v_max_f32_e32 v163, 0, v167
	v_pk_fma_f32 v[134:135], v[152:153], v[160:161], v[134:135] op_sel_hi:[0,1,1]
	v_pk_fma_f32 v[102:103], v[150:151], v[162:163], v[102:103] op_sel_hi:[0,1,1]
	v_mfma_f32_16x16x32_bf16 v[160:163], v[32:35], v[64:67], 0
	v_fma_f32 v100, v150, v164, v100
	v_fma_f32 v101, v150, v165, v101
	v_mfma_f32_16x16x32_bf16 v[164:167], v[32:35], v[72:75], 0
	v_mfma_f32_16x16x32_bf16 v[160:163], v[36:39], v[68:71], v[160:163]
	v_mfma_f32_16x16x32_bf16 v[164:167], v[36:39], v[76:79], v[164:167]
	s_nop 6
	v_max_f32_e32 v160, 0, v160
	v_max_f32_e32 v164, 0, v164
	v_max_f32_e32 v161, 0, v161
	v_max_f32_e32 v165, 0, v165
	v_pk_fma_f32 v[128:129], v[152:153], v[160:161], v[128:129] op_sel_hi:[0,1,1]
	v_max_f32_e32 v160, 0, v162
	v_max_f32_e32 v162, 0, v166
	v_max_f32_e32 v161, 0, v163
	v_max_f32_e32 v163, 0, v167
	v_pk_fma_f32 v[130:131], v[152:153], v[160:161], v[130:131] op_sel_hi:[0,1,1]
	v_pk_fma_f32 v[98:99], v[150:151], v[162:163], v[98:99] op_sel_hi:[0,1,1]
	v_mfma_f32_16x16x32_bf16 v[160:163], v[40:43], v[64:67], 0
	v_fma_f32 v96, v150, v164, v96
	v_fma_f32 v97, v150, v165, v97
	v_mfma_f32_16x16x32_bf16 v[164:167], v[40:43], v[72:75], 0
	v_mfma_f32_16x16x32_bf16 v[160:163], v[44:47], v[68:71], v[160:163]
	v_mfma_f32_16x16x32_bf16 v[164:167], v[44:47], v[76:79], v[164:167]
	s_nop 6
	v_max_f32_e32 v160, 0, v160
	v_max_f32_e32 v164, 0, v164
	v_max_f32_e32 v161, 0, v161
	v_max_f32_e32 v165, 0, v165
	v_pk_fma_f32 v[124:125], v[152:153], v[160:161], v[124:125] op_sel_hi:[0,1,1]
	v_max_f32_e32 v160, 0, v162
	v_max_f32_e32 v162, 0, v166
	v_max_f32_e32 v161, 0, v163
	v_max_f32_e32 v163, 0, v167
	v_pk_fma_f32 v[126:127], v[152:153], v[160:161], v[126:127] op_sel_hi:[0,1,1]
	v_pk_fma_f32 v[94:95], v[150:151], v[162:163], v[94:95] op_sel_hi:[0,1,1]
	v_mfma_f32_16x16x32_bf16 v[160:163], v[48:51], v[64:67], 0
	v_fma_f32 v92, v150, v164, v92
	v_fma_f32 v93, v150, v165, v93
	v_mfma_f32_16x16x32_bf16 v[64:67], v[56:59], v[64:67], 0
; #define MFMA16(a, b, c) __builtin_amdgcn_mfma_f32_16x16x32_bf16((a), (b), (c), 0, 0, 0)
; DI void score_phase(const bf16_t* PROJ, unsigned short* SC, int c, char* smem, int bid, int nb) {
;     ...
;       for (int nj = 0; nj < 8; ++nj) {
;         f32x4 d = MFMA16(kf[nj][0], qa0, ((f32x4){0.f, 0.f, 0.f, 0.f}));
;         d = MFMA16(kf[nj][1], qa1, d);
;         f32x4 e = MFMA16(kf[nj][0], qb0f, ((f32x4){0.f, 0.f, 0.f, 0.f}));
;         e = MFMA16(kf[nj][1], qb1f, e);
; #pragma unroll
;         for (int r = 0; r < 4; ++r) { sc[0][nj][r] += w0 * fmaxf(d[r], 0.f); sc[1][nj][r] += w1 * fmaxf(e[r], 0.f); }
;       }
;     }
; #pragma unroll
;     for (int mi = 0; mi < 2; ++mi) {
;       const int t = q0 + mi * 16 + fr;
;       unsigned short* op = SC + (size_t)(t - c * 4096) * S + s0 + fq * 4;
; #pragma unroll
;       for (int nj = 0; nj < 8; ++nj) {
;         unsigned w0 = __builtin_bit_cast(unsigned, __builtin_amdgcn_cvt_pkrtz(sc[mi][nj][0], sc[mi][nj][1]));
;         unsigned w1 = __builtin_bit_cast(unsigned, __builtin_amdgcn_cvt_pkrtz(sc[mi][nj][2], sc[mi][nj][3]));
;         const unsigned m0 = ((w0 >> 15) & 0x00010001u) * 0xffffu, m1 = ((w1 >> 15) & 0x00010001u) * 0xffffu;
;         w0 ^= (m0 | 0x80008000u); w1 ^= (m1 | 0x80008000u);
;         uint2 st2; st2.x = w0; st2.y = w1;
;         *(uint2*)(op + nj * 16) = st2;
	v_mfma_f32_16x16x32_bf16 v[164:167], v[48:51], v[72:75], 0
	v_mfma_f32_16x16x32_bf16 v[160:163], v[52:55], v[68:71], v[160:163]
	v_mfma_f32_16x16x32_bf16 v[64:67], v[60:63], v[68:71], v[64:67]
	v_mfma_f32_16x16x32_bf16 v[68:71], v[56:59], v[72:75], 0
	s_nop 5
	v_max_f32_e32 v160, 0, v160
	v_mfma_f32_16x16x32_bf16 v[164:167], v[52:55], v[76:79], v[164:167]
	v_max_f32_e32 v64, 0, v64
	v_max_f32_e32 v65, 0, v65
	v_mfma_f32_16x16x32_bf16 v[68:71], v[60:63], v[76:79], v[68:71]
	v_fma_f32 v116, v152, v64, v116
	v_fma_f32 v117, v152, v65, v117
	s_nop 1
	s_nop 0
	v_max_f32_e32 v164, 0, v164
	v_max_f32_e32 v161, 0, v161
	v_max_f32_e32 v165, 0, v165
	v_pk_fma_f32 v[120:121], v[152:153], v[160:161], v[120:121] op_sel_hi:[0,1,1]
	v_max_f32_e32 v160, 0, v162
	v_max_f32_e32 v69, 0, v69
	v_max_f32_e32 v64, v66, v66
	v_max_f32_e32 v66, 0, v70
	v_max_f32_e32 v162, 0, v166
	v_max_f32_e32 v64, 0, v64
	v_max_f32_e32 v65, 0, v67
	v_max_f32_e32 v161, 0, v163
	v_max_f32_e32 v159, v167, v167
	v_pk_fma_f32 v[118:119], v[152:153], v[64:65], v[118:119] op_sel_hi:[0,1,1]
	v_max_f32_e32 v64, v71, v71
	v_max_f32_e32 v163, 0, v159
	v_max_f32_e32 v68, 0, v68
	v_max_f32_e32 v67, 0, v64
	v_pk_fma_f32 v[88:89], v[150:151], v[164:165], v[88:89] op_sel_hi:[0,1,1]
	v_pk_fma_f32 v[122:123], v[152:153], v[160:161], v[122:123] op_sel_hi:[0,1,1]
	v_pk_fma_f32 v[90:91], v[150:151], v[162:163], v[90:91] op_sel_hi:[0,1,1]
	v_pk_fma_f32 v[84:85], v[150:151], v[68:69], v[84:85] op_sel_hi:[0,1,1]
	v_pk_fma_f32 v[86:87], v[150:151], v[66:67], v[86:87] op_sel_hi:[0,1,1]
	s_setprio 0
	s_cbranch_scc0 .LBB0_1343
	v_add_u32_e32 v0, v157, v155
	v_ashrrev_i32_e32 v1, 31, v0
	v_lshlrev_b64 v[4:5], 15, v[0:1]
	v_cvt_pkrtz_f16_f32 v1, v146, v147
	v_cvt_pkrtz_f16_f32 v6, v148, v149
	v_lshrrev_b32_e32 v7, 15, v6
	v_lshrrev_b32_e32 v8, 15, v1
	v_and_b32_e32 v7, 0x10001, v7
	v_and_b32_e32 v8, 0x10001, v8
	s_ashr_i32 s5, s4, 31
	v_mul_u32_u24_e32 v8, 0xffff, v8
	v_mul_u32_u24_e32 v7, 0xffff, v7
	v_lshl_add_u64 v[2:3], s[4:5], 1, v[80:81]
	v_or_b32_e32 v7, 0x80008000, v7
	v_or_b32_e32 v8, 0x80008000, v8
	v_lshl_add_u64 v[4:5], v[2:3], 0, v[4:5]
	v_xor_b32_e32 v7, v7, v6
	v_xor_b32_e32 v6, v8, v1
	global_store_dwordx2 v[4:5], v[6:7], off
	v_cvt_pkrtz_f16_f32 v1, v142, v143
	v_cvt_pkrtz_f16_f32 v6, v144, v145
	v_lshrrev_b32_e32 v7, 15, v6
	v_lshrrev_b32_e32 v8, 15, v1
	v_and_b32_e32 v7, 0x10001, v7
	v_and_b32_e32 v8, 0x10001, v8
	v_mul_u32_u24_e32 v8, 0xffff, v8
	v_mul_u32_u24_e32 v7, 0xffff, v7
	v_or_b32_e32 v7, 0x80008000, v7
	v_or_b32_e32 v8, 0x80008000, v8
	v_xor_b32_e32 v7, v7, v6
	v_xor_b32_e32 v6, v8, v1
	global_store_dwordx2 v[4:5], v[6:7], off offset:32
	v_cvt_pkrtz_f16_f32 v1, v138, v139
	v_cvt_pkrtz_f16_f32 v6, v140, v141
	v_lshrrev_b32_e32 v7, 15, v6
	v_lshrrev_b32_e32 v8, 15, v1
	v_and_b32_e32 v7, 0x10001, v7
	v_and_b32_e32 v8, 0x10001, v8
	v_mul_u32_u24_e32 v8, 0xffff, v8
	v_mul_u32_u24_e32 v7, 0xffff, v7
	v_or_b32_e32 v7, 0x80008000, v7
	v_or_b32_e32 v8, 0x80008000, v8
	v_xor_b32_e32 v7, v7, v6
	v_xor_b32_e32 v6, v8, v1
	global_store_dwordx2 v[4:5], v[6:7], off offset:64
	v_cvt_pkrtz_f16_f32 v1, v132, v133
	v_cvt_pkrtz_f16_f32 v6, v134, v135
	v_lshrrev_b32_e32 v7, 15, v6
	v_lshrrev_b32_e32 v8, 15, v1
	v_and_b32_e32 v7, 0x10001, v7
	v_and_b32_e32 v8, 0x10001, v8
	v_mul_u32_u24_e32 v8, 0xffff, v8
	v_mul_u32_u24_e32 v7, 0xffff, v7
	v_or_b32_e32 v7, 0x80008000, v7
	v_or_b32_e32 v8, 0x80008000, v8
	v_xor_b32_e32 v7, v7, v6
	v_xor_b32_e32 v6, v8, v1
	global_store_dwordx2 v[4:5], v[6:7], off offset:96
	v_cvt_pkrtz_f16_f32 v1, v128, v129
	v_cvt_pkrtz_f16_f32 v6, v130, v131
	v_lshrrev_b32_e32 v7, 15, v6
	v_lshrrev_b32_e32 v8, 15, v1
	v_and_b32_e32 v7, 0x10001, v7
	v_and_b32_e32 v8, 0x10001, v8
	v_mul_u32_u24_e32 v8, 0xffff, v8
	v_mul_u32_u24_e32 v7, 0xffff, v7
	v_or_b32_e32 v7, 0x80008000, v7
	v_or_b32_e32 v8, 0x80008000, v8
	v_xor_b32_e32 v7, v7, v6
	v_xor_b32_e32 v6, v8, v1
	global_store_dwordx2 v[4:5], v[6:7], off offset:128
	v_cvt_pkrtz_f16_f32 v1, v124, v125
	v_cvt_pkrtz_f16_f32 v6, v126, v127
	v_lshrrev_b32_e32 v7, 15, v6
	v_lshrrev_b32_e32 v8, 15, v1
	v_and_b32_e32 v7, 0x10001, v7
	v_and_b32_e32 v8, 0x10001, v8
	v_mul_u32_u24_e32 v8, 0xffff, v8
	v_mul_u32_u24_e32 v7, 0xffff, v7
	v_or_b32_e32 v7, 0x80008000, v7
	v_or_b32_e32 v8, 0x80008000, v8
	v_xor_b32_e32 v7, v7, v6
	v_xor_b32_e32 v6, v8, v1
	global_store_dwordx2 v[4:5], v[6:7], off offset:160
	v_cvt_pkrtz_f16_f32 v1, v120, v121
	v_cvt_pkrtz_f16_f32 v6, v122, v123
	v_lshrrev_b32_e32 v7, 15, v6
; DI void score_phase(const bf16_t* PROJ, unsigned short* SC, int c, char* smem, int bid, int nb) {
;     ...
; #pragma unroll
;     for (int mi = 0; mi < 2; ++mi) {
;       const int t = q0 + mi * 16 + fr;
;       unsigned short* op = SC + (size_t)(t - c * 4096) * S + s0 + fq * 4;
; #pragma unroll
;       for (int nj = 0; nj < 8; ++nj) {
;         unsigned w0 = __builtin_bit_cast(unsigned, __builtin_amdgcn_cvt_pkrtz(sc[mi][nj][0], sc[mi][nj][1]));
;         unsigned w1 = __builtin_bit_cast(unsigned, __builtin_amdgcn_cvt_pkrtz(sc[mi][nj][2], sc[mi][nj][3]));
;         const unsigned m0 = ((w0 >> 15) & 0x00010001u) * 0xffffu, m1 = ((w1 >> 15) & 0x00010001u) * 0xffffu;
;         w0 ^= (m0 | 0x80008000u); w1 ^= (m1 | 0x80008000u);
;         uint2 st2; st2.x = w0; st2.y = w1;
;         *(uint2*)(op + nj * 16) = st2;
;       }
;     }
;   }
	v_lshrrev_b32_e32 v8, 15, v1
	v_and_b32_e32 v7, 0x10001, v7
	v_and_b32_e32 v8, 0x10001, v8
	v_mul_u32_u24_e32 v8, 0xffff, v8
	v_mul_u32_u24_e32 v7, 0xffff, v7
	v_or_b32_e32 v7, 0x80008000, v7
	v_or_b32_e32 v8, 0x80008000, v8
	v_xor_b32_e32 v7, v7, v6
	v_xor_b32_e32 v6, v8, v1
	global_store_dwordx2 v[4:5], v[6:7], off offset:192
	v_cvt_pkrtz_f16_f32 v1, v116, v117
	v_cvt_pkrtz_f16_f32 v6, v118, v119
	v_lshrrev_b32_e32 v7, 15, v6
	v_lshrrev_b32_e32 v8, 15, v1
	v_and_b32_e32 v7, 0x10001, v7
	v_and_b32_e32 v8, 0x10001, v8
	v_mul_u32_u24_e32 v8, 0xffff, v8
	v_mul_u32_u24_e32 v7, 0xffff, v7
	v_or_b32_e32 v7, 0x80008000, v7
	v_or_b32_e32 v8, 0x80008000, v8
	v_or_b32_e32 v0, 16, v0
	v_xor_b32_e32 v7, v7, v6
	v_xor_b32_e32 v6, v8, v1
	v_ashrrev_i32_e32 v1, 31, v0
	v_lshlrev_b64 v[0:1], 15, v[0:1]
	v_lshl_add_u64 v[0:1], v[2:3], 0, v[0:1]
	v_cvt_pkrtz_f16_f32 v2, v112, v113
	v_cvt_pkrtz_f16_f32 v3, v114, v115
	global_store_dwordx2 v[4:5], v[6:7], off offset:224
	v_lshrrev_b32_e32 v4, 15, v3
	v_lshrrev_b32_e32 v5, 15, v2
	v_and_b32_e32 v4, 0x10001, v4
	v_and_b32_e32 v5, 0x10001, v5
	v_mul_u32_u24_e32 v5, 0xffff, v5
	v_mul_u32_u24_e32 v4, 0xffff, v4
	v_or_b32_e32 v4, 0x80008000, v4
	v_or_b32_e32 v5, 0x80008000, v5
	v_xor_b32_e32 v3, v4, v3
	v_xor_b32_e32 v2, v5, v2
	global_store_dwordx2 v[0:1], v[2:3], off
	v_cvt_pkrtz_f16_f32 v2, v108, v109
	v_cvt_pkrtz_f16_f32 v3, v110, v111
	v_lshrrev_b32_e32 v4, 15, v3
	v_lshrrev_b32_e32 v5, 15, v2
	v_and_b32_e32 v4, 0x10001, v4
	v_and_b32_e32 v5, 0x10001, v5
	v_mul_u32_u24_e32 v5, 0xffff, v5
	v_mul_u32_u24_e32 v4, 0xffff, v4
	v_or_b32_e32 v4, 0x80008000, v4
	v_or_b32_e32 v5, 0x80008000, v5
	v_xor_b32_e32 v3, v4, v3
	v_xor_b32_e32 v2, v5, v2
	global_store_dwordx2 v[0:1], v[2:3], off offset:32
	v_cvt_pkrtz_f16_f32 v2, v104, v105
	v_cvt_pkrtz_f16_f32 v3, v106, v107
	v_lshrrev_b32_e32 v4, 15, v3
	v_lshrrev_b32_e32 v5, 15, v2
	v_and_b32_e32 v4, 0x10001, v4
	v_and_b32_e32 v5, 0x10001, v5
	v_mul_u32_u24_e32 v5, 0xffff, v5
	v_mul_u32_u24_e32 v4, 0xffff, v4
	v_or_b32_e32 v4, 0x80008000, v4
	v_or_b32_e32 v5, 0x80008000, v5
	v_xor_b32_e32 v3, v4, v3
	v_xor_b32_e32 v2, v5, v2
	global_store_dwordx2 v[0:1], v[2:3], off offset:64
	v_cvt_pkrtz_f16_f32 v2, v100, v101
	v_cvt_pkrtz_f16_f32 v3, v102, v103
	v_lshrrev_b32_e32 v4, 15, v3
	v_lshrrev_b32_e32 v5, 15, v2
	v_and_b32_e32 v4, 0x10001, v4
	v_and_b32_e32 v5, 0x10001, v5
	v_mul_u32_u24_e32 v5, 0xffff, v5
	v_mul_u32_u24_e32 v4, 0xffff, v4
	v_or_b32_e32 v4, 0x80008000, v4
	v_or_b32_e32 v5, 0x80008000, v5
	v_xor_b32_e32 v3, v4, v3
	v_xor_b32_e32 v2, v5, v2
	global_store_dwordx2 v[0:1], v[2:3], off offset:96
	v_cvt_pkrtz_f16_f32 v2, v96, v97
	v_cvt_pkrtz_f16_f32 v3, v98, v99
	v_lshrrev_b32_e32 v4, 15, v3
	v_lshrrev_b32_e32 v5, 15, v2
	v_and_b32_e32 v4, 0x10001, v4
	v_and_b32_e32 v5, 0x10001, v5
	v_mul_u32_u24_e32 v5, 0xffff, v5
	v_mul_u32_u24_e32 v4, 0xffff, v4
	v_or_b32_e32 v4, 0x80008000, v4
	v_or_b32_e32 v5, 0x80008000, v5
	v_xor_b32_e32 v3, v4, v3
	v_xor_b32_e32 v2, v5, v2
	global_store_dwordx2 v[0:1], v[2:3], off offset:128
	v_cvt_pkrtz_f16_f32 v2, v92, v93
	v_cvt_pkrtz_f16_f32 v3, v94, v95
	v_lshrrev_b32_e32 v4, 15, v3
	v_lshrrev_b32_e32 v5, 15, v2
	v_and_b32_e32 v4, 0x10001, v4
	v_and_b32_e32 v5, 0x10001, v5
	v_mul_u32_u24_e32 v5, 0xffff, v5
	v_mul_u32_u24_e32 v4, 0xffff, v4
	v_or_b32_e32 v4, 0x80008000, v4
	v_or_b32_e32 v5, 0x80008000, v5
	v_xor_b32_e32 v3, v4, v3
	v_xor_b32_e32 v2, v5, v2
	global_store_dwordx2 v[0:1], v[2:3], off offset:160
	v_cvt_pkrtz_f16_f32 v2, v88, v89
	v_cvt_pkrtz_f16_f32 v3, v90, v91
	v_lshrrev_b32_e32 v4, 15, v3
	v_lshrrev_b32_e32 v5, 15, v2
	v_and_b32_e32 v4, 0x10001, v4
	v_and_b32_e32 v5, 0x10001, v5
	v_mul_u32_u24_e32 v5, 0xffff, v5
	v_mul_u32_u24_e32 v4, 0xffff, v4
	v_or_b32_e32 v4, 0x80008000, v4
	v_or_b32_e32 v5, 0x80008000, v5
	v_xor_b32_e32 v3, v4, v3
	v_xor_b32_e32 v2, v5, v2
	global_store_dwordx2 v[0:1], v[2:3], off offset:192
	v_cvt_pkrtz_f16_f32 v2, v84, v85
	v_cvt_pkrtz_f16_f32 v3, v86, v87
	v_lshrrev_b32_e32 v4, 15, v3
	v_lshrrev_b32_e32 v5, 15, v2
	v_and_b32_e32 v4, 0x10001, v4
	v_and_b32_e32 v5, 0x10001, v5
	v_mul_u32_u24_e32 v5, 0xffff, v5
	v_mul_u32_u24_e32 v4, 0xffff, v4
	v_readlane_b32 s2, v249, 43
	v_or_b32_e32 v4, 0x80008000, v4
	v_or_b32_e32 v5, 0x80008000, v5
	s_add_i32 s8, s8, s2
	v_xor_b32_e32 v3, v4, v3
	v_xor_b32_e32 v2, v5, v2
	s_cmpk_gt_i32 s8, 0x60f
	v_readlane_b32 s3, v249, 44
	global_store_dwordx2 v[0:1], v[2:3], off offset:224
	s_cbranch_scc0 .LBB0_1336

; template <int DQK>
; DI void attn_phase(const bf16_t* Q, int ldq, const bf16_t* K1, int ldk1, const bf16_t* K2, int ldk2, const bf16_t* VT, int ldvt,
;                    bf16_t* O, int ldo, int nheads, int nq, int nkeys, bool causal, float scale, char* smem, int bid, int nb) {
;     ...
;     for (int kt = 0; kt < ntiles; ++kt) {
;       const int s0 = kt * 64;
;       int tl = tid; asm volatile("" : "+v"(tl));
;       __syncthreads();
;       if (CPR / 4 == 6) asm volatile("s_waitcnt vmcnt(0)" : "+v"(kr[0]), "+v"(kr[1]), "+v"(kr[2]), "+v"(kr[3]), "+v"(kr[CPR / 4 - 2]), "+v"(kr[CPR / 4 - 1]), "+v"(vr[0]), "+v"(vr[1]), "+v"(vr[2]), "+v"(vr[3]) :: "memory");
;       else asm volatile("s_waitcnt vmcnt(0)" : "+v"(kr[0]), "+v"(kr[1]), "+v"(kr[2]), "+v"(kr[3]), "+v"(vr[0]), "+v"(vr[1]), "+v"(vr[2]), "+v"(vr[3]) :: "memory");
; #pragma unroll
;       for (int j = 0; j < CPR / 4; ++j) {
;         const int c = tl + 256 * j, row = c / CPR, ch = c % CPR;
;         *(u32x4v*)(Ks + row * LK * 2 + (((ch & ~7) | ((ch ^ (row >> 1)) & 7)) * 16)) = kr[j];
;       }
; #pragma unroll
;       for (int j = 0; j < 4; ++j) { const int c = tl + 256 * j, d = c >> 3, ch = c & 7; *(u32x4v*)(Vs + (d * LDT + ch * 8) * 2) = vr[j]; }
;       {
;         const int s1 = (kt + 1 < ntiles ? kt + 1 : kt) * 64;
; #pragma unroll
;         for (int j = 0; j < CPR / 4; ++j) {
;           const int c = tl + 256 * j, row = c / CPR, ch = c % CPR;
;           gld(kr[j], ch < 16 ? K1 + (size_t)(s1 + row) * ldk1 + h * 128 + ch * 8 : K2 + (size_t)(s1 + row) * ldk2 + (ch - 16) * 8);
;         }
; #pragma unroll
;         for (int j = 0; j < 4; ++j) { const int c = tl + 256 * j, d = c >> 3, ch = c & 7; gld(vr[j], VT + (size_t)(h * 128 + d) * ldvt + s1 + ch * 8); }
;       }
;       __syncthreads();
;       if (causal && s0 > qw + 31) continue;
;       f32x4 st[2][4];
; #pragma unroll
;       for (int mi = 0; mi < 2; ++mi)
; #pragma unroll
;         for (int nj = 0; nj < 4; ++nj) st[mi][nj] = (f32x4){0.f, 0.f, 0.f, 0.f};
;       asm volatile("" ::: "memory");
; #pragma unroll
;       for (int ks = 0; ks < NKS; ++ks) {
;         bf16x8 kf[4];
; #pragma unroll
;         for (int nj = 0; nj < 4; ++nj) kf[nj] = *(const bf16x8*)(Ks + (nj * 16 + fr) * LK * 2 + ((((ks * 4) & ~7) | (((ks * 4 + fq) ^ (fr >> 1)) & 7)) * 16));
;         bf16x8 qq[2];
; #pragma unroll
;         for (int mi = 0; mi < 2; ++mi) {
.LBB0_1540:
	v_mov_b32_e32 v153, v226
	v_lshrrev_b32_e32 v154, 4, v153
	v_and_b32_e32 v156, 15, v153
	v_lshrrev_b32_e32 v155, 1, v154
	v_xor_b32_e32 v155, v155, v156
	v_and_b32_e32 v155, 7, v155
	v_and_or_b32 v155, v156, 8, v155
	v_mul_u32_u24_e32 v154, 0x180, v154
	v_lshl_add_u32 v155, v155, 4, v154
	v_lshrrev_b32_e32 v157, 3, v153
	v_and_b32_e32 v158, 7, v153
	v_lshrrev_b32_e32 v159, 1, v157
	v_xor_b32_e32 v159, v159, v158
	v_and_b32_e32 v159, 7, v159
	v_lshlrev_b32_e32 v159, 4, v159
	v_mul_u32_u24_e32 v157, 0x180, v157
	v_add_u32_e32 v159, 0x100, v159
	v_add_u32_e32 v159, v157, v159
	s_waitcnt vmcnt(63) expcnt(7) lgkmcnt(15)
	s_barrier
	s_waitcnt vmcnt(0)
	ds_write_b128 v155, v[0:3]
	ds_write_b128 v155, v[52:55] offset:6144
	ds_write_b128 v155, v[56:59] offset:12288
	ds_write_b128 v155, v[60:63] offset:18432
	ds_write_b128 v159, v[64:67]
	ds_write_b128 v159, v[68:71] offset:12288
	v_add_u32_e32 v0, 0x100, v153
	v_add_u32_e32 v1, 0x200, v153
	v_add_u32_e32 v2, 0x300, v153
	v_lshrrev_b32_e32 v156, 3, v153
	v_and_b32_e32 v157, 7, v153
	v_mul_u32_u24_e32 v3, 0x90, v156
	v_lshl_add_u32 v3, v157, 4, v3
	s_mov_b32 s0, s14
	s_add_i32 s14, s14, 1
	ds_write_b128 v3, v[72:75] offset:24576
	ds_write_b128 v3, v[76:79] offset:29184
	s_cmp_lt_u32 s14, s3
	s_cselect_b32 s0, s14, s0
	v_readlane_b32 s5, v247, 48
	ds_write_b128 v3, v[80:83] offset:33792
	s_mov_b32 s1, s5
	s_lshl_b32 s0, s0, 6
	v_writelane_b32 v247, s0, 47
	ds_write_b128 v3, v[84:87] offset:38400
	v_writelane_b32 v247, s1, 48
	v_mov_b32_e32 v158, v226
	v_lshrrev_b32_e32 v159, 4, v158
	v_and_b32_e32 v160, 15, v158
	v_lshlrev_b32_e32 v160, 4, v160
	v_lshl_or_b32 v159, v159, 11, v160
	v_lshrrev_b32_e32 v161, 3, v158
	v_and_b32_e32 v162, 7, v158
	v_mul_u32_u24_e32 v161, 0x4200, v161
	v_lshl_add_u32 v161, v162, 4, v161
	s_lshl_b32 s4, s0, 11
	s_add_u32 s4, s10, s4
	s_addc_u32 s5, s11, 0
	global_load_dwordx4 v[0:3], v159, s[4:5]
	s_add_u32 s4, s4, 0x8000
	s_addc_u32 s5, s5, 0
	global_load_dwordx4 v[52:55], v159, s[4:5]
	s_add_u32 s4, s4, 0x8000
	s_addc_u32 s5, s5, 0
	global_load_dwordx4 v[56:59], v159, s[4:5]
	s_add_u32 s4, s4, 0x8000
	s_addc_u32 s5, s5, 0
	global_load_dwordx4 v[60:63], v159, s[4:5]
	v_readlane_b32 s4, v249, 1
	v_readlane_b32 s5, v249, 2
	s_mul_i32 s1, s0, 0x4200
	s_add_u32 s4, s4, s1
	s_addc_u32 s5, s5, 0
	global_load_dwordx4 v[64:67], v161, s[4:5]
	s_add_u32 s4, s4, 0x84000
	s_addc_u32 s5, s5, 0
	global_load_dwordx4 v[68:71], v161, s[4:5]
	v_readlane_b32 s4, v249, 3
	v_readlane_b32 s5, v249, 4
	s_lshl_b32 s1, s0, 1
	s_add_u32 s4, s4, s1
	s_addc_u32 s5, s5, 0
	s_lshl_b32 s1, s8, 15
	s_add_u32 s4, s4, s1
	s_addc_u32 s5, s5, 0
	v_lshlrev_b32_e32 v163, 4, v157
	v_lshl_or_b32 v163, v156, 15, v163
	global_load_dwordx4 v[72:75], v163, s[4:5]
	s_add_u32 s4, s4, 0x100000
	s_addc_u32 s5, s5, 0
	global_load_dwordx4 v[76:79], v163, s[4:5]
	s_add_u32 s4, s4, 0x100000
	s_addc_u32 s5, s5, 0
	global_load_dwordx4 v[80:83], v163, s[4:5]
	s_add_u32 s4, s4, 0x100000
	s_addc_u32 s5, s5, 0
	global_load_dwordx4 v[84:87], v163, s[4:5]
	s_sub_i32 s0, s9, 63
	v_cmp_le_i32_e32 vcc, s0, v237
	s_waitcnt lgkmcnt(0)
	s_barrier
	s_and_saveexec_b64 s[12:13], vcc
	s_cbranch_execz .LBB0_1539
	ds_read_b128 v[154:157], v231
	ds_read_b128 v[158:161], v231 offset:6144
	ds_read_b128 v[162:165], v231 offset:12288
	ds_read_b128 v[166:169], v231 offset:18432
	ds_read_b128 v[198:201], v232
	ds_read_b128 v[202:205], v232 offset:6144
	ds_read_b128 v[206:209], v232 offset:12288
	ds_read_b128 v[210:213], v232 offset:18432
	s_waitcnt lgkmcnt(7)
	v_mfma_f32_16x16x32_bf16 v[170:173], v[154:157], v[4:7], 0
	v_add_u32_e32 v153, s9, v230
	v_subrev_u32_e32 v182, 63, v153
	v_cmp_gt_i32_e32 vcc, s9, v234
	s_waitcnt lgkmcnt(6)
	v_mfma_f32_16x16x32_bf16 v[186:189], v[158:161], v[4:7], 0
	v_cmp_ge_i32_e64 s[4:5], v182, v235
	s_and_b64 s[4:5], vcc, s[4:5]
	v_cmp_gt_i32_e64 s[0:1], v182, v235
	s_waitcnt lgkmcnt(5)
	v_mfma_f32_16x16x32_bf16 v[190:193], v[162:165], v[4:7], 0
	s_and_b64 s[0:1], vcc, s[0:1]
	s_mov_b32 s17, 0xf149f2ca
	s_movk_i32 s16, 0x7fff
	s_waitcnt lgkmcnt(4)
	v_mfma_f32_16x16x32_bf16 v[194:197], v[166:169], v[4:7], 0
	s_mov_b32 s15, 0xffff0000
	v_add_u32_e32 v244, 0x6800, v233
	v_add_u32_e32 v245, 0x7000, v233
	s_nop 0
	v_mfma_f32_16x16x32_bf16 v[154:157], v[154:157], v[28:31], 0
	v_add_u32_e32 v221, 0x7800, v233
	v_add_u32_e32 v215, 0x8000, v233
	v_add_u32_e32 v216, 0x8800, v233
	v_mfma_f32_16x16x32_bf16 v[158:161], v[158:161], v[28:31], 0
	v_add_u32_e32 v224, 0x9000, v233
	v_add_u32_e32 v225, 0x9800, v233
	v_mfma_f32_16x16x32_bf16 v[162:165], v[162:165], v[28:31], 0
	v_mfma_f32_16x16x32_bf16 v[166:169], v[166:169], v[28:31], 0
	s_waitcnt lgkmcnt(3)
	v_mfma_f32_16x16x32_bf16 v[170:173], v[198:201], v[8:11], v[170:173]
	s_waitcnt lgkmcnt(2)
	v_mfma_f32_16x16x32_bf16 v[186:189], v[202:205], v[8:11], v[186:189]
	s_waitcnt lgkmcnt(1)
	v_mfma_f32_16x16x32_bf16 v[190:193], v[206:209], v[8:11], v[190:193]
	s_waitcnt lgkmcnt(0)
	v_mfma_f32_16x16x32_bf16 v[194:197], v[210:213], v[8:11], v[194:197]
	s_nop 0
	v_mfma_f32_16x16x32_bf16 v[154:157], v[198:201], v[32:35], v[154:157]
	v_mfma_f32_16x16x32_bf16 v[158:161], v[202:205], v[32:35], v[158:161]
	v_mfma_f32_16x16x32_bf16 v[162:165], v[206:209], v[32:35], v[162:165]
	v_mfma_f32_16x16x32_bf16 v[166:169], v[210:213], v[32:35], v[166:169]
	ds_read_b128 v[198:201], v231 offset:128
	ds_read_b128 v[202:205], v231 offset:6272
	ds_read_b128 v[206:209], v231 offset:12416
	ds_read_b128 v[210:213], v231 offset:18560
	s_waitcnt lgkmcnt(3)
	v_mfma_f32_16x16x32_bf16 v[170:173], v[198:201], v[12:15], v[170:173]
	s_waitcnt lgkmcnt(2)
	v_mfma_f32_16x16x32_bf16 v[186:189], v[202:205], v[12:15], v[186:189]
	s_waitcnt lgkmcnt(1)
; #define MFMA16(a, b, c) __builtin_amdgcn_mfma_f32_16x16x32_bf16((a), (b), (c), 0, 0, 0)
; template <int DQK>
; DI void attn_phase(const bf16_t* Q, int ldq, const bf16_t* K1, int ldk1, const bf16_t* K2, int ldk2, const bf16_t* VT, int ldvt,
;                    bf16_t* O, int ldo, int nheads, int nq, int nkeys, bool causal, float scale, char* smem, int bid, int nb) {
;     ...
;       for (int ks = 0; ks < NKS; ++ks) {
;         bf16x8 kf[4];
; #pragma unroll
;         for (int nj = 0; nj < 4; ++nj) kf[nj] = *(const bf16x8*)(Ks + (nj * 16 + fr) * LK * 2 + ((((ks * 4) & ~7) | (((ks * 4 + fq) ^ (fr >> 1)) & 7)) * 16));
;         bf16x8 qq[2];
; #pragma unroll
;         for (int mi = 0; mi < 2; ++mi) {
;           if (ks < NKH) qq[mi] = qf[mi][ks < NKH ? ks : 0];
;           else qq[mi] = *(const bf16x8*)(Q + (size_t)(qw + mi * 16 + fr) * ldq + h * DQK + ks * 32 + fq * 8);
;         }
; #pragma unroll
;         for (int mi = 0; mi < 2; ++mi)
; #pragma unroll
;           for (int nj = 0; nj < 4; ++nj) st[mi][nj] = MFMA16(kf[nj], qq[mi], st[mi][nj]);
;       }
;       const bool diag = causal && (s0 + 63 > qw);
;       bf16x8 pf[2][2];
; #pragma unroll
;       for (int mi = 0; mi < 2; ++mi) {
;         const int qi = qw + mi * 16 + fr;
;         float mx = -1e30f;
; #pragma unroll
;         for (int nj = 0; nj < 4; ++nj)
; #pragma unroll
;           for (int r = 0; r < 4; ++r) {
;             float v = st[mi][nj][r] * sc2;
;             if (diag && (s0 + nj * 16 + fq * 4 + r > qi)) v = -1e30f;
;             st[mi][nj][r] = v; mx = fmaxf(mx, v);
;           }
	v_mfma_f32_16x16x32_bf16 v[190:193], v[206:209], v[12:15], v[190:193]
	s_waitcnt lgkmcnt(0)
	v_mfma_f32_16x16x32_bf16 v[194:197], v[210:213], v[12:15], v[194:197]
	s_nop 0
	v_mfma_f32_16x16x32_bf16 v[154:157], v[198:201], v[36:39], v[154:157]
	v_mfma_f32_16x16x32_bf16 v[158:161], v[202:205], v[36:39], v[158:161]
	v_mfma_f32_16x16x32_bf16 v[162:165], v[206:209], v[36:39], v[162:165]
	v_mfma_f32_16x16x32_bf16 v[166:169], v[210:213], v[36:39], v[166:169]
	ds_read_b128 v[198:201], v232 offset:128
	ds_read_b128 v[202:205], v232 offset:6272
	ds_read_b128 v[206:209], v232 offset:12416
	ds_read_b128 v[210:213], v232 offset:18560
	s_waitcnt lgkmcnt(3)
	v_mfma_f32_16x16x32_bf16 v[170:173], v[198:201], v[16:19], v[170:173]
	s_waitcnt lgkmcnt(2)
	v_mfma_f32_16x16x32_bf16 v[186:189], v[202:205], v[16:19], v[186:189]
	s_waitcnt lgkmcnt(1)
	v_mfma_f32_16x16x32_bf16 v[190:193], v[206:209], v[16:19], v[190:193]
	s_waitcnt lgkmcnt(0)
	v_mfma_f32_16x16x32_bf16 v[194:197], v[210:213], v[16:19], v[194:197]
	s_nop 0
	v_mfma_f32_16x16x32_bf16 v[154:157], v[198:201], v[40:43], v[154:157]
	v_mfma_f32_16x16x32_bf16 v[158:161], v[202:205], v[40:43], v[158:161]
	v_mfma_f32_16x16x32_bf16 v[162:165], v[206:209], v[40:43], v[162:165]
	v_mfma_f32_16x16x32_bf16 v[166:169], v[210:213], v[40:43], v[166:169]
	ds_read_b128 v[198:201], v231 offset:256
	ds_read_b128 v[202:205], v231 offset:6400
	ds_read_b128 v[206:209], v231 offset:12544
	ds_read_b128 v[210:213], v231 offset:18688
	s_waitcnt lgkmcnt(3)
	v_mfma_f32_16x16x32_bf16 v[170:173], v[198:201], v[20:23], v[170:173]
	s_waitcnt lgkmcnt(2)
	v_mfma_f32_16x16x32_bf16 v[186:189], v[202:205], v[20:23], v[186:189]
	s_waitcnt lgkmcnt(1)
	v_mfma_f32_16x16x32_bf16 v[190:193], v[206:209], v[20:23], v[190:193]
	s_waitcnt lgkmcnt(0)
	v_mfma_f32_16x16x32_bf16 v[194:197], v[210:213], v[20:23], v[194:197]
	s_nop 0
	v_mfma_f32_16x16x32_bf16 v[154:157], v[198:201], v[44:47], v[154:157]
	v_mfma_f32_16x16x32_bf16 v[158:161], v[202:205], v[44:47], v[158:161]
	v_mfma_f32_16x16x32_bf16 v[162:165], v[206:209], v[44:47], v[162:165]
	v_mfma_f32_16x16x32_bf16 v[198:201], v[210:213], v[44:47], v[166:169]
	s_nop 2
	ds_read_b128 v[166:169], v232 offset:256
	ds_read_b128 v[202:205], v232 offset:6400
	ds_read_b128 v[206:209], v232 offset:12544
	ds_read_b128 v[210:213], v232 offset:18688
	s_waitcnt lgkmcnt(3)
	v_mfma_f32_16x16x32_bf16 v[238:241], v[166:169], v[24:27], v[170:173]
	s_nop 0
	v_mfma_f32_16x16x32_bf16 v[172:175], v[166:169], v[48:51], v[154:157]
	s_waitcnt lgkmcnt(2)
	v_mfma_f32_16x16x32_bf16 v[168:171], v[202:205], v[48:51], v[158:161]
	s_nop 3
	v_mul_f32_e32 v155, 0x3dd53b94, v239
	v_cndmask_b32_e64 v155, v155, v223, s[4:5]
	v_mul_f32_e32 v157, 0x3dd53b94, v240
	s_waitcnt lgkmcnt(1)
	v_mfma_f32_16x16x32_bf16 v[164:167], v[206:209], v[48:51], v[162:165]
	v_mul_f32_e32 v158, 0x3dd53b94, v241
	v_subrev_u32_e32 v159, 47, v153
	v_mul_f32_e32 v154, 0x3dd53b94, v238
	s_waitcnt lgkmcnt(0)
	v_mfma_f32_16x16x32_bf16 v[160:163], v[210:213], v[48:51], v[198:201]
	v_cndmask_b32_e64 v154, v154, v223, s[0:1]
	v_max3_f32 v156, v154, s17, v155
	v_add_u32_e32 v240, -12, v153
	v_subrev_u32_e32 v198, 61, v153
	v_cmp_gt_i32_e64 s[4:5], v198, v235
	v_mfma_f32_16x16x32_bf16 v[186:189], v[202:205], v[24:27], v[186:189]
	s_and_b64 s[4:5], vcc, s[4:5]
	v_subrev_u32_e32 v200, 60, v153
	v_cndmask_b32_e64 v157, v157, v223, s[4:5]
	v_cmp_gt_i32_e64 s[4:5], v200, v235
	s_and_b64 s[4:5], vcc, s[4:5]
	s_nop 2
	v_mul_f32_e32 v181, 0x3dd53b94, v186
	v_cndmask_b32_e64 v158, v158, v223, s[4:5]
	v_cmp_gt_i32_e64 s[4:5], v159, v235
	s_and_b64 s[4:5], vcc, s[4:5]
	v_subrev_u32_e32 v186, 46, v153
	v_cndmask_b32_e64 v159, v181, v223, s[4:5]
	v_cmp_gt_i32_e64 s[4:5], v186, v235
	v_mul_f32_e32 v181, 0x3dd53b94, v187
	s_and_b64 s[4:5], vcc, s[4:5]
	v_cndmask_b32_e64 v183, v181, v223, s[4:5]
	v_mul_f32_e32 v181, 0x3dd53b94, v188
	v_subrev_u32_e32 v188, 45, v153
	v_cmp_gt_i32_e64 s[4:5], v188, v235
	v_mfma_f32_16x16x32_bf16 v[190:193], v[206:209], v[24:27], v[190:193]
	s_and_b64 s[4:5], vcc, s[4:5]
	v_subrev_u32_e32 v202, 44, v153
	v_cndmask_b32_e64 v184, v181, v223, s[4:5]
	v_cmp_gt_i32_e64 s[4:5], v202, v235
	v_mul_f32_e32 v181, 0x3dd53b94, v189
	s_and_b64 s[4:5], vcc, s[4:5]
	v_subrev_u32_e32 v204, 31, v153
	v_cndmask_b32_e64 v201, v181, v223, s[4:5]
	v_cmp_gt_i32_e64 s[4:5], v204, v235
	v_mul_f32_e32 v181, 0x3dd53b94, v190
	s_and_b64 s[4:5], vcc, s[4:5]
	v_subrev_u32_e32 v206, 30, v153
	v_cndmask_b32_e64 v190, v181, v223, s[4:5]
	v_cmp_gt_i32_e64 s[4:5], v206, v235
	v_mul_f32_e32 v181, 0x3dd53b94, v191
	s_and_b64 s[4:5], vcc, s[4:5]
	v_cndmask_b32_e64 v191, v181, v223, s[4:5]
	v_mul_f32_e32 v181, 0x3dd53b94, v192
	v_subrev_u32_e32 v192, 29, v153
	v_cmp_gt_i32_e64 s[4:5], v192, v235
	v_mfma_f32_16x16x32_bf16 v[194:197], v[210:213], v[24:27], v[194:197]
	s_and_b64 s[4:5], vcc, s[4:5]
	v_subrev_u32_e32 v208, 28, v153
	v_cndmask_b32_e64 v203, v181, v223, s[4:5]
	v_cmp_gt_i32_e64 s[4:5], v208, v235
	v_mul_f32_e32 v181, 0x3dd53b94, v193
	s_and_b64 s[4:5], vcc, s[4:5]
	v_add_u32_e32 v210, -15, v153
	v_cndmask_b32_e64 v209, v181, v223, s[4:5]
	v_cmp_gt_i32_e64 s[4:5], v210, v235
	v_mul_f32_e32 v181, 0x3dd53b94, v194
	s_and_b64 s[4:5], vcc, s[4:5]
	v_add_u32_e32 v212, -14, v153
	v_cndmask_b32_e64 v194, v181, v223, s[4:5]
	v_cmp_gt_i32_e64 s[4:5], v212, v235
	v_mul_f32_e32 v181, 0x3dd53b94, v195
	s_and_b64 s[4:5], vcc, s[4:5]
	v_max3_f32 v156, v156, v157, v158
	v_cndmask_b32_e64 v211, v181, v223, s[4:5]
	v_mul_f32_e32 v181, 0x3dd53b94, v196
	v_add_u32_e32 v196, -13, v153
	v_max3_f32 v156, v156, v159, v183
	v_cmp_gt_i32_e64 s[4:5], v196, v235
	v_max3_f32 v156, v156, v184, v201
; DI unsigned pack2(float a, float b) { return (unsigned)f2bf(a) | ((unsigned)f2bf(b) << 16); }
; template <int DQK>
; DI void attn_phase(const bf16_t* Q, int ldq, const bf16_t* K1, int ldk1, const bf16_t* K2, int ldk2, const bf16_t* VT, int ldvt,
;                    bf16_t* O, int ldo, int nheads, int nq, int nkeys, bool causal, float scale, char* smem, int bid, int nb) {
;     ...
;       for (int mi = 0; mi < 2; ++mi) {
;         const int qi = qw + mi * 16 + fr;
;         float mx = -1e30f;
; #pragma unroll
;         for (int nj = 0; nj < 4; ++nj)
; #pragma unroll
;           for (int r = 0; r < 4; ++r) {
;             float v = st[mi][nj][r] * sc2;
;             if (diag && (s0 + nj * 16 + fq * 4 + r > qi)) v = -1e30f;
;             st[mi][nj][r] = v; mx = fmaxf(mx, v);
;           }
;         mx = rows4_max(mx);
;         const float mn = fmaxf(mrow[mi], mx), al = __builtin_amdgcn_exp2f(mrow[mi] - mn);
;         mrow[mi] = mn;
;         float ps = 0.f;
; #pragma unroll
;         for (int nj = 0; nj < 4; ++nj)
; #pragma unroll
;           for (int r = 0; r < 4; ++r) { const float pv = __builtin_amdgcn_exp2f(st[mi][nj][r] - mn); st[mi][nj][r] = pv; ps += pv; }
;         lrow[mi] = lrow[mi] * al + ps;
; #pragma unroll
;         for (int dj = 0; dj < 8; ++dj) ot[mi][dj] *= al;
; #pragma unroll
;         for (int s = 0; s < 2; ++s) {
;           uint4 w;
;           w.x = pack2(st[mi][2 * s][0], st[mi][2 * s][1]); w.y = pack2(st[mi][2 * s][2], st[mi][2 * s][3]);
;           w.z = pack2(st[mi][2 * s + 1][0], st[mi][2 * s + 1][1]); w.w = pack2(st[mi][2 * s + 1][2], st[mi][2 * s + 1][3]);
;           pf[mi][s] = __builtin_bit_cast(bf16x8, w);
;         }
	s_and_b64 s[4:5], vcc, s[4:5]
	v_max3_f32 v156, v156, v190, v191
	v_cndmask_b32_e64 v239, v181, v223, s[4:5]
	v_cmp_gt_i32_e64 s[4:5], v240, v235
	v_max3_f32 v156, v156, v203, v209
	v_mul_f32_e32 v181, 0x3dd53b94, v197
	s_and_b64 s[4:5], vcc, s[4:5]
	v_max3_f32 v156, v156, v194, v211
	v_cndmask_b32_e64 v153, v181, v223, s[4:5]
	v_max3_f32 v156, v156, v239, v153
	v_mov_b32_e32 v181, v156
	s_nop 1
	v_permlane32_swap_b32_e32 v156, v181
	v_max_f32_e32 v181, v181, v181
	v_max_f32_e32 v156, v156, v156
	v_max_f32_e32 v156, v156, v181
	v_mov_b32_e32 v181, v156
	s_nop 1
	v_permlane16_swap_b32_e32 v156, v181
	v_max3_f32 v238, v152, v156, v181
	v_sub_f32_e32 v154, v154, v238
	v_exp_f32_e32 v181, v154
	v_sub_f32_e32 v154, v155, v238
	v_exp_f32_e32 v189, v154
	v_sub_f32_e32 v154, v157, v238
	v_exp_f32_e32 v187, v154
	v_sub_f32_e32 v154, v158, v238
	v_exp_f32_e32 v199, v154
	v_sub_f32_e32 v154, v159, v238
	v_mul_f32_e32 v168, 0x3dd53b94, v168
	v_exp_f32_e32 v193, v154
	v_sub_f32_e32 v154, v183, v238
	v_cndmask_b32_e64 v168, v168, v223, s[0:1]
	v_cmp_gt_i32_e64 s[0:1], v186, v236
	v_exp_f32_e32 v207, v154
	v_sub_f32_e32 v154, v184, v238
	v_mul_f32_e32 v169, 0x3dd53b94, v169
	s_and_b64 s[0:1], vcc, s[0:1]
	v_exp_f32_e32 v205, v154
	v_sub_f32_e32 v154, v201, v238
	v_cndmask_b32_e64 v169, v169, v223, s[0:1]
	v_cmp_gt_i32_e64 s[0:1], v188, v236
	v_exp_f32_e32 v213, v154
	v_sub_f32_e32 v154, v190, v238
	v_mul_f32_e32 v170, 0x3dd53b94, v170
	s_and_b64 s[0:1], vcc, s[0:1]
	v_sub_f32_e32 v152, v152, v238
	v_exp_f32_e32 v183, v154
	v_sub_f32_e32 v154, v191, v238
	v_cndmask_b32_e64 v170, v170, v223, s[0:1]
	v_cmp_gt_i32_e64 s[0:1], v202, v236
	v_exp_f32_e32 v197, v154
	v_sub_f32_e32 v154, v203, v238
	v_exp_f32_e32 v184, v152
	v_mul_f32_e32 v171, 0x3dd53b94, v171
	s_and_b64 s[0:1], vcc, s[0:1]
	v_exp_f32_e32 v191, v154
	v_sub_f32_e32 v154, v209, v238
	v_cndmask_b32_e64 v171, v171, v223, s[0:1]
	v_cmp_gt_i32_e64 s[0:1], v204, v236
	v_exp_f32_e32 v203, v154
	v_sub_f32_e32 v154, v194, v238
	v_mul_f32_e32 v164, 0x3dd53b94, v164
	s_and_b64 s[0:1], vcc, s[0:1]
	v_exp_f32_e32 v195, v154
	v_sub_f32_e32 v154, v211, v238
	v_cmp_gt_i32_e64 s[4:5], v182, v236
	v_cndmask_b32_e64 v164, v164, v223, s[0:1]
	v_cmp_gt_i32_e64 s[0:1], v206, v236
	v_exp_f32_e32 v209, v154
	v_sub_f32_e32 v154, v239, v238
	v_sub_f32_e32 v153, v153, v238
	v_pk_mul_f32 v[158:159], v[150:151], v[184:185] op_sel_hi:[1,0]
	v_pk_mul_f32 v[150:151], v[142:143], v[184:185] op_sel_hi:[1,0]
	v_pk_mul_f32 v[142:143], v[130:131], v[184:185] op_sel_hi:[1,0]
	s_nop 0
	s_nop 0
	v_mul_f32_e32 v172, 0x3dd53b94, v172
	s_and_b64 s[4:5], vcc, s[4:5]
	v_mul_f32_e32 v165, 0x3dd53b94, v165
	s_and_b64 s[0:1], vcc, s[0:1]
	v_exp_f32_e32 v201, v154
	v_exp_f32_e32 v211, v153
	v_pk_mul_f32 v[154:155], v[146:147], v[184:185] op_sel_hi:[1,0]
	v_pk_mul_f32 v[152:153], v[144:145], v[184:185] op_sel_hi:[1,0]
	v_pk_mul_f32 v[146:147], v[138:139], v[184:185] op_sel_hi:[1,0]
	v_pk_mul_f32 v[144:145], v[136:137], v[184:185] op_sel_hi:[1,0]
	v_pk_mul_f32 v[138:139], v[126:127], v[184:185] op_sel_hi:[1,0]
	v_pk_mul_f32 v[136:137], v[124:125], v[184:185] op_sel_hi:[1,0]
	v_pk_mul_f32 v[126:127], v[122:123], v[184:185] op_sel_hi:[1,0]
	v_pk_mul_f32 v[124:125], v[120:121], v[184:185] op_sel_hi:[1,0]
	v_pk_mul_f32 v[122:123], v[134:135], v[184:185] op_sel_hi:[1,0]
	v_pk_mul_f32 v[120:121], v[132:133], v[184:185] op_sel_hi:[1,0]
	s_nop 0
	s_nop 0
	s_nop 0
	s_nop 0
	s_nop 0
	s_nop 0
	v_cndmask_b32_e64 v172, v172, v223, s[4:5]
	v_cmp_ge_i32_e64 s[4:5], v182, v236
	v_cndmask_b32_e64 v165, v165, v223, s[0:1]
	v_cmp_gt_i32_e64 s[0:1], v192, v236
	v_pk_mul_f32 v[156:157], v[148:149], v[184:185] op_sel_hi:[1,0]
	v_pk_mul_f32 v[148:149], v[140:141], v[184:185] op_sel_hi:[1,0]
	v_pk_mul_f32 v[140:141], v[128:129], v[184:185] op_sel_hi:[1,0]
	s_nop 0
	s_nop 0
	s_nop 0
	s_nop 0
	s_nop 0
	s_nop 0
	v_mul_f32_e32 v173, 0x3dd53b94, v173
	s_and_b64 s[4:5], vcc, s[4:5]
	v_mul_f32_e32 v166, 0x3dd53b94, v166
	s_and_b64 s[0:1], vcc, s[0:1]
	s_nop 0
	s_nop 0
	s_nop 0
	s_nop 0
	s_nop 0
	s_nop 0
	s_nop 0
	s_nop 0
	v_cndmask_b32_e64 v173, v173, v223, s[4:5]
	v_cmp_gt_i32_e64 s[4:5], v198, v236
	v_cndmask_b32_e64 v166, v166, v223, s[0:1]
	v_cmp_gt_i32_e64 s[0:1], v208, v236
	v_cvt_pk_bf16_f32 v131, v205, v213
	v_cvt_pk_bf16_f32 v130, v193, v207
	v_cvt_pk_bf16_f32 v129, v187, v199
	v_cvt_pk_bf16_f32 v128, v181, v189
	s_nop 0
	s_nop 0
	s_nop 0
	s_nop 0
	s_nop 0
	v_mul_f32_e32 v174, 0x3dd53b94, v174
	s_and_b64 s[4:5], vcc, s[4:5]
	v_mul_f32_e32 v167, 0x3dd53b94, v167
	s_and_b64 s[0:1], vcc, s[0:1]
	s_nop 0
	s_nop 0
	s_nop 0
	s_nop 0
	v_cndmask_b32_e64 v174, v174, v223, s[4:5]
	v_cmp_gt_i32_e64 s[4:5], v200, v236
	v_cndmask_b32_e64 v167, v167, v223, s[0:1]
	v_cmp_gt_i32_e64 s[0:1], v210, v236
	s_nop 0
	s_nop 0
	s_nop 0
	s_nop 0
	v_mul_f32_e32 v175, 0x3dd53b94, v175
	s_and_b64 s[4:5], vcc, s[4:5]
	v_mul_f32_e32 v160, 0x3dd53b94, v160
	s_and_b64 s[0:1], vcc, s[0:1]
	v_cvt_pk_bf16_f32 v134, v195, v209
	v_cvt_pk_bf16_f32 v133, v191, v203
	v_max3_f32 v182, v172, s17, v173
	v_cndmask_b32_e64 v175, v175, v223, s[4:5]
	v_cndmask_b32_e64 v194, v160, v223, s[0:1]
	v_cmp_gt_i32_e64 s[0:1], v212, v236
	v_max3_f32 v182, v182, v174, v175
	v_mul_f32_e32 v160, 0x3dd53b94, v161
	s_and_b64 s[0:1], vcc, s[0:1]
	v_max3_f32 v182, v182, v168, v169
	v_cndmask_b32_e64 v200, v160, v223, s[0:1]
	v_cmp_gt_i32_e64 s[0:1], v196, v236
	v_max3_f32 v182, v182, v170, v171
	v_mul_f32_e32 v161, 0x3dd53b94, v162
	s_and_b64 s[0:1], vcc, s[0:1]
	v_max3_f32 v182, v182, v164, v165
	v_cndmask_b32_e64 v162, v161, v223, s[0:1]
	v_cmp_gt_i32_e64 s[0:1], v240, v236
	v_max3_f32 v182, v182, v166, v167
; DI unsigned pack2(float a, float b) { return (unsigned)f2bf(a) | ((unsigned)f2bf(b) << 16); }
; template <int DQK>
; DI void attn_phase(const bf16_t* Q, int ldq, const bf16_t* K1, int ldk1, const bf16_t* K2, int ldk2, const bf16_t* VT, int ldvt,
;                    bf16_t* O, int ldo, int nheads, int nq, int nkeys, bool causal, float scale, char* smem, int bid, int nb) {
;     ...
;       for (int mi = 0; mi < 2; ++mi) {
;         const int qi = qw + mi * 16 + fr;
;         float mx = -1e30f;
; #pragma unroll
;         for (int nj = 0; nj < 4; ++nj)
; #pragma unroll
;           for (int r = 0; r < 4; ++r) {
;             float v = st[mi][nj][r] * sc2;
;             if (diag && (s0 + nj * 16 + fq * 4 + r > qi)) v = -1e30f;
;             st[mi][nj][r] = v; mx = fmaxf(mx, v);
;           }
;         mx = rows4_max(mx);
;         const float mn = fmaxf(mrow[mi], mx), al = __builtin_amdgcn_exp2f(mrow[mi] - mn);
;         mrow[mi] = mn;
;         float ps = 0.f;
; #pragma unroll
;         for (int nj = 0; nj < 4; ++nj)
; #pragma unroll
;           for (int r = 0; r < 4; ++r) { const float pv = __builtin_amdgcn_exp2f(st[mi][nj][r] - mn); st[mi][nj][r] = pv; ps += pv; }
;         lrow[mi] = lrow[mi] * al + ps;
; #pragma unroll
;         for (int dj = 0; dj < 8; ++dj) ot[mi][dj] *= al;
; #pragma unroll
;         for (int s = 0; s < 2; ++s) {
;           uint4 w;
;           w.x = pack2(st[mi][2 * s][0], st[mi][2 * s][1]); w.y = pack2(st[mi][2 * s][2], st[mi][2 * s][3]);
;           w.z = pack2(st[mi][2 * s + 1][0], st[mi][2 * s + 1][1]); w.w = pack2(st[mi][2 * s + 1][2], st[mi][2 * s + 1][3]);
;           pf[mi][s] = __builtin_bit_cast(bf16x8, w);
;         }
	v_mul_f32_e32 v161, 0x3dd53b94, v163
	s_and_b64 vcc, vcc, s[0:1]
	v_max3_f32 v160, v182, v194, v200
	v_cndmask_b32_e32 v163, v161, v223, vcc
	v_max3_f32 v160, v160, v162, v163
	v_mov_b32_e32 v161, v160
	s_nop 1
	v_permlane32_swap_b32_e32 v160, v161
	v_max_f32_e32 v161, v161, v161
	v_max_f32_e32 v160, v160, v160
	v_max_f32_e32 v160, v160, v161
	v_mov_b32_e32 v161, v160
	s_nop 1
	v_permlane16_swap_b32_e32 v160, v161
	v_max3_f32 v239, v180, v160, v161
	v_sub_f32_e32 v160, v172, v239
	v_sub_f32_e32 v240, v180, v239
	v_exp_f32_e32 v180, v160
	v_sub_f32_e32 v160, v173, v239
	v_exp_f32_e32 v188, v160
	v_sub_f32_e32 v160, v174, v239
	v_exp_f32_e32 v186, v160
	v_sub_f32_e32 v160, v175, v239
	v_exp_f32_e32 v198, v160
	v_sub_f32_e32 v160, v168, v239
	v_exp_f32_e32 v192, v160
	v_sub_f32_e32 v160, v169, v239
	v_exp_f32_e32 v206, v160
	v_sub_f32_e32 v160, v170, v239
	v_exp_f32_e32 v204, v160
	v_sub_f32_e32 v160, v171, v239
	v_exp_f32_e32 v212, v160
	v_pk_add_f32 v[160:161], v[180:181], 0 op_sel_hi:[1,0]
	s_nop 0
	v_pk_add_f32 v[160:161], v[188:189], v[160:161]
	v_sub_f32_e32 v164, v164, v239
	v_pk_add_f32 v[160:161], v[186:187], v[160:161]
	s_nop 0
	v_pk_add_f32 v[160:161], v[198:199], v[160:161]
	s_nop 0
	v_pk_add_f32 v[160:161], v[192:193], v[160:161]
	v_exp_f32_e32 v182, v164
	v_sub_f32_e32 v164, v165, v239
	s_nop 0
	s_nop 0
	v_pk_add_f32 v[160:161], v[206:207], v[160:161]
	v_exp_f32_e32 v196, v164
	v_sub_f32_e32 v164, v166, v239
	v_cvt_pk_bf16_f32 v135, v201, v211
	v_cvt_pk_bf16_f32 v132, v183, v197
	v_pk_add_f32 v[160:161], v[204:205], v[160:161]
	v_exp_f32_e32 v190, v164
	v_sub_f32_e32 v164, v167, v239
	v_pk_add_f32 v[160:161], v[212:213], v[160:161]
	v_exp_f32_e32 v202, v164
	v_sub_f32_e32 v164, v194, v239
	v_exp_f32_e32 v194, v164
	v_sub_f32_e32 v164, v200, v239
	v_sub_f32_e32 v162, v162, v239
	v_pk_add_f32 v[160:161], v[182:183], v[160:161]
	v_exp_f32_e32 v208, v164
	v_exp_f32_e32 v200, v162
	v_sub_f32_e32 v162, v163, v239
	v_pk_add_f32 v[160:161], v[196:197], v[160:161]
	v_exp_f32_e32 v210, v162
	v_exp_f32_e32 v162, v240
	v_pk_add_f32 v[160:161], v[190:191], v[160:161]
	v_mov_b32_e32 v163, v184
	v_pk_add_f32 v[160:161], v[202:203], v[160:161]
	v_pk_mul_f32 v[170:171], v[118:119], v[162:163] op_sel_hi:[1,0]
	v_pk_add_f32 v[160:161], v[194:195], v[160:161]
	v_pk_mul_f32 v[168:169], v[116:117], v[162:163] op_sel_hi:[1,0]
	v_pk_add_f32 v[160:161], v[208:209], v[160:161]
	v_pk_mul_f32 v[118:119], v[110:111], v[162:163] op_sel_hi:[1,0]
	v_pk_add_f32 v[160:161], v[200:201], v[160:161]
	v_pk_mul_f32 v[116:117], v[108:109], v[162:163] op_sel_hi:[1,0]
	s_nop 0
	s_nop 0
	s_nop 0
	v_pk_add_f32 v[160:161], v[210:211], v[160:161]
	v_pk_mul_f32 v[166:167], v[114:115], v[162:163] op_sel_hi:[1,0]
	v_pk_mul_f32 v[164:165], v[112:113], v[162:163] op_sel_hi:[1,0]
	v_pk_mul_f32 v[114:115], v[102:103], v[162:163] op_sel_hi:[1,0]
	v_pk_mul_f32 v[112:113], v[100:101], v[162:163] op_sel_hi:[1,0]
	v_pk_mul_f32 v[102:103], v[98:99], v[162:163] op_sel_hi:[1,0]
	v_pk_mul_f32 v[100:101], v[96:97], v[162:163] op_sel_hi:[1,0]
	v_pk_mul_f32 v[98:99], v[90:91], v[162:163] op_sel_hi:[1,0]
	v_pk_mul_f32 v[96:97], v[88:89], v[162:163] op_sel_hi:[1,0]
	v_pk_mul_f32 v[90:91], v[106:107], v[162:163] op_sel_hi:[1,0]
	v_pk_mul_f32 v[88:89], v[104:105], v[162:163] op_sel_hi:[1,0]
	s_nop 0
	s_nop 0
	s_nop 0
	s_nop 0
	s_nop 0
	s_nop 0
	s_nop 0
	v_pk_fma_f32 v[178:179], v[178:179], v[162:163], v[160:161]
	s_nop 0
	s_nop 0
	s_nop 0
	s_nop 0
	s_nop 0
	s_nop 0
	s_nop 0
	s_nop 0
	v_cvt_pk_bf16_f32 v111, v204, v212
	v_cvt_pk_bf16_f32 v109, v186, v198
	v_cvt_pk_bf16_f32 v108, v180, v188
	s_nop 0
	s_nop 0
	s_nop 0
	s_nop 0
	s_nop 0
	s_nop 0
	s_nop 0
	v_add_u32_e32 v184, 0x6000, v233
	v_cvt_pk_bf16_f32 v105, v190, v202
	ds_read2_b64 v[172:175], v184 offset1:4
	s_nop 0
	v_pk_mul_f32 v[94:95], v[94:95], v[162:163] op_sel_hi:[1,0]
	v_pk_mul_f32 v[92:93], v[92:93], v[162:163] op_sel_hi:[1,0]
	s_nop 0
	s_nop 0
	s_nop 0
	s_nop 0
	v_cvt_pk_bf16_f32 v110, v192, v206
	s_nop 0
	s_nop 0
	s_nop 0
	s_nop 0
	s_nop 0
	s_nop 0
	s_nop 0
	s_nop 0
	s_nop 0
	s_nop 0
	v_cvt_pk_bf16_f32 v107, v200, v210
	v_cvt_pk_bf16_f32 v106, v194, v208
	v_cvt_pk_bf16_f32 v104, v182, v196
	s_waitcnt lgkmcnt(0)
; #define MFMA16(a, b, c) __builtin_amdgcn_mfma_f32_16x16x32_bf16((a), (b), (c), 0, 0, 0)
; template <int DQK>
; DI void attn_phase(const bf16_t* Q, int ldq, const bf16_t* K1, int ldk1, const bf16_t* K2, int ldk2, const bf16_t* VT, int ldvt,
;                    bf16_t* O, int ldo, int nheads, int nq, int nkeys, bool causal, float scale, char* smem, int bid, int nb) {
;     ...
; #pragma unroll
;       for (int s = 0; s < 2; ++s)
; #pragma unroll
;         for (int dj = 0; dj < 8; ++dj) {
;           const char* vp = Vs + ((dj * 16 + fr) * LDT + 32 * s + fq * 4) * 2;
;           const s16x4 lo = *(const s16x4*)vp, hi = *(const s16x4*)(vp + 32);
;           const bf16x8 vf = __builtin_shufflevector(lo, hi, 0, 1, 2, 3, 4, 5, 6, 7);
; #pragma unroll
;           for (int mi = 0; mi < 2; ++mi) ot[mi][dj] = MFMA16(vf, pf[mi][s], ot[mi][dj]);
;         }
	v_mfma_f32_16x16x32_bf16 v[160:163], v[172:175], v[128:131], v[156:159]
	v_mfma_f32_16x16x32_bf16 v[156:159], v[172:175], v[108:111], v[168:171]
	ds_read2_b64 v[172:175], v245 offset0:64 offset1:68
	s_nop 1
	ds_read2_b64 v[168:171], v244 offset0:32 offset1:36
	s_waitcnt lgkmcnt(0)
	v_mfma_f32_16x16x32_bf16 v[152:155], v[168:171], v[128:131], v[152:155]
	v_mfma_f32_16x16x32_bf16 v[164:167], v[168:171], v[108:111], v[164:167]
	v_mfma_f32_16x16x32_bf16 v[168:171], v[172:175], v[128:131], v[148:151]
	v_mfma_f32_16x16x32_bf16 v[172:175], v[172:175], v[108:111], v[116:119]
	s_nop 2
	ds_read2_b64 v[116:119], v221 offset0:96 offset1:100
	s_waitcnt lgkmcnt(0)
	v_mfma_f32_16x16x32_bf16 v[186:189], v[116:119], v[108:111], v[112:115]
	s_nop 2
	ds_read2_b64 v[112:115], v215 offset0:128 offset1:132
	s_waitcnt lgkmcnt(0)
	v_mfma_f32_16x16x32_bf16 v[194:197], v[112:115], v[108:111], v[100:103]
	s_nop 2
	ds_read2_b64 v[100:103], v216 offset0:160 offset1:164
	s_waitcnt lgkmcnt(0)
	v_mfma_f32_16x16x32_bf16 v[202:205], v[100:103], v[108:111], v[96:99]
	s_nop 2
	ds_read2_b64 v[96:99], v224 offset0:192 offset1:196
	s_waitcnt lgkmcnt(0)
	v_mfma_f32_16x16x32_bf16 v[206:209], v[96:99], v[128:131], v[124:127]
	v_mfma_f32_16x16x32_bf16 v[92:95], v[96:99], v[108:111], v[92:95]
	ds_read2_b64 v[96:99], v225 offset0:224 offset1:228
	s_waitcnt lgkmcnt(0)
	v_mfma_f32_16x16x32_bf16 v[240:243], v[96:99], v[108:111], v[88:91]
	s_nop 2
	ds_read2_b64 v[88:91], v184 offset0:8 offset1:12
	v_mfma_f32_16x16x32_bf16 v[180:183], v[116:119], v[128:131], v[144:147]
	s_waitcnt lgkmcnt(0)
	v_mfma_f32_16x16x32_bf16 v[148:151], v[88:91], v[132:135], v[160:163]
	v_mfma_f32_16x16x32_bf16 v[116:119], v[88:91], v[104:107], v[156:159]
	ds_read2_b64 v[88:91], v244 offset0:40 offset1:44
	v_mfma_f32_16x16x32_bf16 v[190:193], v[112:115], v[128:131], v[140:143]
	s_waitcnt lgkmcnt(0)
	v_mfma_f32_16x16x32_bf16 v[144:147], v[88:91], v[132:135], v[152:155]
	s_nop 2
	ds_read2_b64 v[152:155], v224 offset0:200 offset1:204
	v_mfma_f32_16x16x32_bf16 v[112:115], v[88:91], v[104:107], v[164:167]
	ds_read2_b64 v[88:91], v245 offset0:72 offset1:76
	s_waitcnt lgkmcnt(0)
	v_mfma_f32_16x16x32_bf16 v[140:143], v[88:91], v[132:135], v[168:171]
	v_mfma_f32_16x16x32_bf16 v[108:111], v[88:91], v[104:107], v[172:175]
	ds_read2_b64 v[88:91], v221 offset0:104 offset1:108
	v_mfma_f32_16x16x32_bf16 v[198:201], v[100:103], v[128:131], v[136:139]
	s_waitcnt lgkmcnt(0)
	v_mfma_f32_16x16x32_bf16 v[136:139], v[88:91], v[132:135], v[180:183]
	s_nop 2
	v_mov_b32_e32 v180, v239
	v_mfma_f32_16x16x32_bf16 v[100:103], v[88:91], v[104:107], v[186:189]
	ds_read2_b64 v[88:91], v215 offset0:136 offset1:140
	v_mfma_f32_16x16x32_bf16 v[210:213], v[96:99], v[128:131], v[120:123]
	s_waitcnt lgkmcnt(0)
	v_mfma_f32_16x16x32_bf16 v[128:131], v[88:91], v[132:135], v[190:193]
	v_mfma_f32_16x16x32_bf16 v[96:99], v[88:91], v[104:107], v[194:197]
	ds_read2_b64 v[88:91], v216 offset0:168 offset1:172
	v_mfma_f32_16x16x32_bf16 v[120:123], v[152:155], v[132:135], v[206:209]
	v_mfma_f32_16x16x32_bf16 v[92:95], v[152:155], v[104:107], v[92:95]
	ds_read2_b64 v[152:155], v225 offset0:232 offset1:236
	s_waitcnt lgkmcnt(1)
	v_mfma_f32_16x16x32_bf16 v[124:127], v[88:91], v[132:135], v[198:201]
	v_mfma_f32_16x16x32_bf16 v[88:91], v[88:91], v[104:107], v[202:205]
	s_waitcnt lgkmcnt(0)
	v_mfma_f32_16x16x32_bf16 v[132:135], v[152:155], v[132:135], v[210:213]
	v_mfma_f32_16x16x32_bf16 v[104:107], v[152:155], v[104:107], v[240:243]
	v_mov_b32_e32 v152, v238
	s_branch .LBB0_1539

; #define MFMA16(a, b, c) __builtin_amdgcn_mfma_f32_16x16x32_bf16((a), (b), (c), 0, 0, 0)
; DI void score_phase(const bf16_t* PROJ, unsigned short* SC, int c, char* smem, int bid, int nb) {
;     ...
;     for (int h = 0; h < 16; ++h) {
;       const bf16x8 qa0 = *(const bf16x8*)(rowp0 + C_IQ + h * 64 + fq * 8), qa1 = *(const bf16x8*)(rowp0 + C_IQ + h * 64 + 32 + fq * 8);
;       const bf16x8 qb0f = *(const bf16x8*)(rowp1 + C_IQ + h * 64 + fq * 8), qb1f = *(const bf16x8*)(rowp1 + C_IQ + h * 64 + 32 + fq * 8);
;       const float w0 = sW[fr * 17 + h], w1 = sW[(16 + fr) * 17 + h];
; #pragma unroll
;       for (int nj = 0; nj < 8; ++nj) {
;         f32x4 d = MFMA16(kf[nj][0], qa0, ((f32x4){0.f, 0.f, 0.f, 0.f}));
;         d = MFMA16(kf[nj][1], qa1, d);
;         f32x4 e = MFMA16(kf[nj][0], qb0f, ((f32x4){0.f, 0.f, 0.f, 0.f}));
;         e = MFMA16(kf[nj][1], qb1f, e);
; #pragma unroll
;         for (int r = 0; r < 4; ++r) { sc[0][nj][r] += w0 * fmaxf(d[r], 0.f); sc[1][nj][r] += w1 * fmaxf(e[r], 0.f); }
;       }
.LBB0_1574:
	v_lshl_add_u64 v[72:73], v[138:139], 0, s[6:7]
	v_add_co_u32_e32 v68, vcc, s2, v72
	s_add_u32 s6, s6, 0x80
	s_nop 0
	v_addc_co_u32_e32 v69, vcc, 0, v73, vcc
	global_load_dwordx4 v[64:67], v[68:69], off offset:128
	s_nop 0
	global_load_dwordx4 v[68:71], v[68:69], off offset:192
	v_add_co_u32_e32 v76, vcc, s3, v72
	s_addc_u32 s7, s7, 0
	s_nop 0
	v_addc_co_u32_e32 v77, vcc, 0, v73, vcc
	global_load_dwordx4 v[72:75], v[76:77], off offset:128
	s_nop 0
	global_load_dwordx4 v[76:79], v[76:77], off offset:192
	ds_read_b32 v154, v157
	ds_read_b32 v152, v157 offset:1088
	v_add_u32_e32 v157, 4, v157
	s_cmpk_eq_i32 s6, 0x800
	s_waitcnt vmcnt(3)
	s_setprio 1
	v_mfma_f32_16x16x32_bf16 v[158:161], v[0:3], v[64:67], 0
	s_waitcnt vmcnt(1)
	v_mfma_f32_16x16x32_bf16 v[162:165], v[0:3], v[72:75], 0
	v_mfma_f32_16x16x32_bf16 v[158:161], v[4:7], v[68:71], v[158:161]
	s_waitcnt vmcnt(0)
	v_mfma_f32_16x16x32_bf16 v[162:165], v[4:7], v[76:79], v[162:165]
	s_nop 5
	v_max_f32_e32 v158, 0, v158
	v_max_f32_e32 v159, 0, v159
	s_waitcnt lgkmcnt(1)
	v_pk_fma_f32 v[148:149], v[154:155], v[158:159], v[148:149] op_sel_hi:[0,1,1]
	v_max_f32_e32 v163, 0, v163
	v_max_f32_e32 v158, v160, v160
	v_max_f32_e32 v160, 0, v164
	v_max_f32_e32 v158, 0, v158
	v_max_f32_e32 v159, 0, v161
	v_pk_fma_f32 v[150:151], v[154:155], v[158:159], v[150:151] op_sel_hi:[0,1,1]
	v_max_f32_e32 v161, 0, v165
	s_waitcnt lgkmcnt(0)
	v_pk_fma_f32 v[116:117], v[152:153], v[160:161], v[116:117] op_sel_hi:[0,1,1]
	v_mfma_f32_16x16x32_bf16 v[158:161], v[8:11], v[64:67], 0
	v_max_f32_e32 v162, 0, v162
	v_pk_fma_f32 v[114:115], v[152:153], v[162:163], v[114:115] op_sel_hi:[0,1,1]
	v_mfma_f32_16x16x32_bf16 v[162:165], v[8:11], v[72:75], 0
	v_mfma_f32_16x16x32_bf16 v[158:161], v[12:15], v[68:71], v[158:161]
	v_mfma_f32_16x16x32_bf16 v[162:165], v[12:15], v[76:79], v[162:165]
	s_nop 6
	v_max_f32_e32 v158, 0, v158
	v_max_f32_e32 v159, 0, v159
	v_pk_fma_f32 v[144:145], v[154:155], v[158:159], v[144:145] op_sel_hi:[0,1,1]
	v_max_f32_e32 v163, 0, v163
	v_max_f32_e32 v158, v160, v160
	v_max_f32_e32 v160, 0, v164
	v_max_f32_e32 v158, 0, v158
	v_max_f32_e32 v159, 0, v161
	v_pk_fma_f32 v[146:147], v[154:155], v[158:159], v[146:147] op_sel_hi:[0,1,1]
	v_max_f32_e32 v161, 0, v165
	v_pk_fma_f32 v[112:113], v[152:153], v[160:161], v[112:113] op_sel_hi:[0,1,1]
	v_mfma_f32_16x16x32_bf16 v[158:161], v[16:19], v[64:67], 0
	v_max_f32_e32 v162, 0, v162
	v_pk_fma_f32 v[110:111], v[152:153], v[162:163], v[110:111] op_sel_hi:[0,1,1]
	v_mfma_f32_16x16x32_bf16 v[162:165], v[16:19], v[72:75], 0
	v_mfma_f32_16x16x32_bf16 v[158:161], v[20:23], v[68:71], v[158:161]
	v_mfma_f32_16x16x32_bf16 v[162:165], v[20:23], v[76:79], v[162:165]
	s_nop 6
	v_max_f32_e32 v158, 0, v158
	v_max_f32_e32 v159, 0, v159
	v_pk_fma_f32 v[140:141], v[154:155], v[158:159], v[140:141] op_sel_hi:[0,1,1]
	v_max_f32_e32 v163, 0, v163
	v_max_f32_e32 v158, v160, v160
	v_max_f32_e32 v160, 0, v164
	v_max_f32_e32 v158, 0, v158
	v_max_f32_e32 v159, 0, v161
	v_pk_fma_f32 v[142:143], v[154:155], v[158:159], v[142:143] op_sel_hi:[0,1,1]
	v_max_f32_e32 v161, 0, v165
	v_pk_fma_f32 v[108:109], v[152:153], v[160:161], v[108:109] op_sel_hi:[0,1,1]
	v_mfma_f32_16x16x32_bf16 v[158:161], v[24:27], v[64:67], 0
	v_max_f32_e32 v162, 0, v162
	v_pk_fma_f32 v[106:107], v[152:153], v[162:163], v[106:107] op_sel_hi:[0,1,1]
	v_mfma_f32_16x16x32_bf16 v[162:165], v[24:27], v[72:75], 0
	v_mfma_f32_16x16x32_bf16 v[158:161], v[28:31], v[68:71], v[158:161]
	v_mfma_f32_16x16x32_bf16 v[162:165], v[28:31], v[76:79], v[162:165]
	s_nop 6
	v_max_f32_e32 v158, 0, v158
	v_max_f32_e32 v159, 0, v159
	v_pk_fma_f32 v[134:135], v[154:155], v[158:159], v[134:135] op_sel_hi:[0,1,1]
	v_max_f32_e32 v163, 0, v163
	v_max_f32_e32 v158, v160, v160
	v_max_f32_e32 v160, 0, v164
	v_max_f32_e32 v158, 0, v158
	v_max_f32_e32 v159, 0, v161
	v_pk_fma_f32 v[136:137], v[154:155], v[158:159], v[136:137] op_sel_hi:[0,1,1]
	v_max_f32_e32 v161, 0, v165
	v_pk_fma_f32 v[104:105], v[152:153], v[160:161], v[104:105] op_sel_hi:[0,1,1]
	v_mfma_f32_16x16x32_bf16 v[158:161], v[32:35], v[64:67], 0
	v_max_f32_e32 v162, 0, v162
	v_pk_fma_f32 v[102:103], v[152:153], v[162:163], v[102:103] op_sel_hi:[0,1,1]
	v_mfma_f32_16x16x32_bf16 v[162:165], v[32:35], v[72:75], 0
	v_mfma_f32_16x16x32_bf16 v[158:161], v[36:39], v[68:71], v[158:161]
	v_mfma_f32_16x16x32_bf16 v[162:165], v[36:39], v[76:79], v[162:165]
	s_nop 6
	v_max_f32_e32 v158, 0, v158
	v_max_f32_e32 v159, 0, v159
	v_pk_fma_f32 v[130:131], v[154:155], v[158:159], v[130:131] op_sel_hi:[0,1,1]
	v_max_f32_e32 v163, 0, v163
	v_max_f32_e32 v158, v160, v160
	v_max_f32_e32 v160, 0, v164
	v_max_f32_e32 v158, 0, v158
	v_max_f32_e32 v159, 0, v161
	v_pk_fma_f32 v[132:133], v[154:155], v[158:159], v[132:133] op_sel_hi:[0,1,1]
	v_max_f32_e32 v161, 0, v165
	v_pk_fma_f32 v[100:101], v[152:153], v[160:161], v[100:101] op_sel_hi:[0,1,1]
	v_mfma_f32_16x16x32_bf16 v[158:161], v[40:43], v[64:67], 0
	v_max_f32_e32 v162, 0, v162
	v_pk_fma_f32 v[98:99], v[152:153], v[162:163], v[98:99] op_sel_hi:[0,1,1]
	v_mfma_f32_16x16x32_bf16 v[162:165], v[40:43], v[72:75], 0
	v_mfma_f32_16x16x32_bf16 v[158:161], v[44:47], v[68:71], v[158:161]
	v_mfma_f32_16x16x32_bf16 v[162:165], v[44:47], v[76:79], v[162:165]
	s_nop 6
	v_max_f32_e32 v158, 0, v158
	v_max_f32_e32 v159, 0, v159
	v_pk_fma_f32 v[126:127], v[154:155], v[158:159], v[126:127] op_sel_hi:[0,1,1]
	v_max_f32_e32 v163, 0, v163
	v_max_f32_e32 v158, v160, v160
	v_max_f32_e32 v160, 0, v164
	v_max_f32_e32 v158, 0, v158
	v_max_f32_e32 v159, 0, v161
	v_pk_fma_f32 v[128:129], v[154:155], v[158:159], v[128:129] op_sel_hi:[0,1,1]
	v_max_f32_e32 v161, 0, v165
; DI void score_phase(const bf16_t* PROJ, unsigned short* SC, int c, char* smem, int bid, int nb) {
;     ...
;         for (int r = 0; r < 4; ++r) { sc[0][nj][r] += w0 * fmaxf(d[r], 0.f); sc[1][nj][r] += w1 * fmaxf(e[r], 0.f); }
;       }
;     }
; #pragma unroll
;     for (int mi = 0; mi < 2; ++mi) {
;       const int t = q0 + mi * 16 + fr;
;       unsigned short* op = SC + (size_t)(t - c * 4096) * S + s0 + fq * 4;
; #pragma unroll
;       for (int nj = 0; nj < 8; ++nj) {
;         unsigned w0 = __builtin_bit_cast(unsigned, __builtin_amdgcn_cvt_pkrtz(sc[mi][nj][0], sc[mi][nj][1]));
;         unsigned w1 = __builtin_bit_cast(unsigned, __builtin_amdgcn_cvt_pkrtz(sc[mi][nj][2], sc[mi][nj][3]));
;         const unsigned m0 = ((w0 >> 15) & 0x00010001u) * 0xffffu, m1 = ((w1 >> 15) & 0x00010001u) * 0xffffu;
;         w0 ^= (m0 | 0x80008000u); w1 ^= (m1 | 0x80008000u);
;         uint2 st2; st2.x = w0; st2.y = w1;
;         *(uint2*)(op + nj * 16) = st2;
;       }
	v_pk_fma_f32 v[96:97], v[152:153], v[160:161], v[96:97] op_sel_hi:[0,1,1]
	v_mfma_f32_16x16x32_bf16 v[158:161], v[48:51], v[64:67], 0
	v_max_f32_e32 v162, 0, v162
	v_pk_fma_f32 v[94:95], v[152:153], v[162:163], v[94:95] op_sel_hi:[0,1,1]
	v_mfma_f32_16x16x32_bf16 v[64:67], v[56:59], v[64:67], 0
	v_mfma_f32_16x16x32_bf16 v[158:161], v[52:55], v[68:71], v[158:161]
	v_mfma_f32_16x16x32_bf16 v[162:165], v[48:51], v[72:75], 0
	v_mfma_f32_16x16x32_bf16 v[64:67], v[60:63], v[68:71], v[64:67]
	s_nop 5
	v_max_f32_e32 v158, 0, v158
	v_mfma_f32_16x16x32_bf16 v[68:71], v[56:59], v[72:75], 0
	v_max_f32_e32 v159, 0, v159
	v_mfma_f32_16x16x32_bf16 v[162:165], v[52:55], v[76:79], v[162:165]
	v_max_f32_e32 v64, 0, v64
	v_max_f32_e32 v65, 0, v65
	v_pk_fma_f32 v[122:123], v[154:155], v[158:159], v[122:123] op_sel_hi:[0,1,1]
	v_mfma_f32_16x16x32_bf16 v[68:71], v[60:63], v[76:79], v[68:71]
	v_fma_f32 v118, v154, v64, v118
	v_fma_f32 v119, v154, v65, v119
	s_nop 1
	v_max_f32_e32 v163, 0, v163
	v_max_f32_e32 v158, v160, v160
	v_max_f32_e32 v160, 0, v164
	s_nop 0
	v_max_f32_e32 v69, 0, v69
	v_max_f32_e32 v64, v66, v66
	v_max_f32_e32 v66, 0, v70
	v_max_f32_e32 v158, 0, v158
	v_max_f32_e32 v159, 0, v161
	v_max_f32_e32 v64, 0, v64
	v_max_f32_e32 v65, 0, v67
	v_pk_fma_f32 v[124:125], v[154:155], v[158:159], v[124:125] op_sel_hi:[0,1,1]
	v_max_f32_e32 v158, v165, v165
	v_pk_fma_f32 v[120:121], v[154:155], v[64:65], v[120:121] op_sel_hi:[0,1,1]
	v_max_f32_e32 v64, v71, v71
	v_max_f32_e32 v162, 0, v162
	v_max_f32_e32 v161, 0, v158
	v_max_f32_e32 v68, 0, v68
	v_max_f32_e32 v67, 0, v64
	v_pk_fma_f32 v[90:91], v[152:153], v[162:163], v[90:91] op_sel_hi:[0,1,1]
	v_pk_fma_f32 v[92:93], v[152:153], v[160:161], v[92:93] op_sel_hi:[0,1,1]
	v_pk_fma_f32 v[86:87], v[152:153], v[68:69], v[86:87] op_sel_hi:[0,1,1]
	v_pk_fma_f32 v[88:89], v[152:153], v[66:67], v[88:89] op_sel_hi:[0,1,1]
	s_setprio 0
	s_cbranch_scc0 .LBB0_1574
	v_cvt_pkrtz_f16_f32 v4, v148, v149
	v_cvt_pkrtz_f16_f32 v5, v150, v151
	v_lshrrev_b32_e32 v6, 15, v5
	v_lshrrev_b32_e32 v7, 15, v4
	v_and_b32_e32 v6, 0x10001, v6
	v_and_b32_e32 v7, 0x10001, v7
	s_ashr_i32 s5, s4, 31
	v_mul_u32_u24_e32 v7, 0xffff, v7
	v_mul_u32_u24_e32 v6, 0xffff, v6
	v_lshl_add_u64 v[0:1], s[4:5], 1, v[80:81]
	v_lshlrev_b64 v[2:3], 15, v[84:85]
	v_or_b32_e32 v6, 0x80008000, v6
	v_or_b32_e32 v7, 0x80008000, v7
	v_lshl_add_u64 v[2:3], v[0:1], 0, v[2:3]
	v_xor_b32_e32 v5, v6, v5
	v_xor_b32_e32 v4, v7, v4
	global_store_dwordx2 v[2:3], v[4:5], off
	v_cvt_pkrtz_f16_f32 v4, v144, v145
	v_cvt_pkrtz_f16_f32 v5, v146, v147
	v_lshrrev_b32_e32 v6, 15, v5
	v_lshrrev_b32_e32 v7, 15, v4
	v_and_b32_e32 v6, 0x10001, v6
	v_and_b32_e32 v7, 0x10001, v7
	v_mul_u32_u24_e32 v7, 0xffff, v7
	v_mul_u32_u24_e32 v6, 0xffff, v6
	v_or_b32_e32 v6, 0x80008000, v6
	v_or_b32_e32 v7, 0x80008000, v7
	v_xor_b32_e32 v5, v6, v5
	v_xor_b32_e32 v4, v7, v4
	global_store_dwordx2 v[2:3], v[4:5], off offset:32
	v_cvt_pkrtz_f16_f32 v4, v140, v141
	v_cvt_pkrtz_f16_f32 v5, v142, v143
	v_lshrrev_b32_e32 v6, 15, v5
	v_lshrrev_b32_e32 v7, 15, v4
	v_and_b32_e32 v6, 0x10001, v6
	v_and_b32_e32 v7, 0x10001, v7
	v_mul_u32_u24_e32 v7, 0xffff, v7
	v_mul_u32_u24_e32 v6, 0xffff, v6
	v_or_b32_e32 v6, 0x80008000, v6
	v_or_b32_e32 v7, 0x80008000, v7
	v_xor_b32_e32 v5, v6, v5
	v_xor_b32_e32 v4, v7, v4
	global_store_dwordx2 v[2:3], v[4:5], off offset:64
	v_cvt_pkrtz_f16_f32 v4, v134, v135
	v_cvt_pkrtz_f16_f32 v5, v136, v137
	v_lshrrev_b32_e32 v6, 15, v5
	v_lshrrev_b32_e32 v7, 15, v4
	v_and_b32_e32 v6, 0x10001, v6
	v_and_b32_e32 v7, 0x10001, v7
	v_mul_u32_u24_e32 v7, 0xffff, v7
	v_mul_u32_u24_e32 v6, 0xffff, v6
	v_or_b32_e32 v6, 0x80008000, v6
	v_or_b32_e32 v7, 0x80008000, v7
	v_xor_b32_e32 v5, v6, v5
	v_xor_b32_e32 v4, v7, v4
	global_store_dwordx2 v[2:3], v[4:5], off offset:96
	v_cvt_pkrtz_f16_f32 v4, v130, v131
	v_cvt_pkrtz_f16_f32 v5, v132, v133
	v_lshrrev_b32_e32 v6, 15, v5
	v_lshrrev_b32_e32 v7, 15, v4
	v_and_b32_e32 v6, 0x10001, v6
	v_and_b32_e32 v7, 0x10001, v7
	v_mul_u32_u24_e32 v7, 0xffff, v7
	v_mul_u32_u24_e32 v6, 0xffff, v6
	v_or_b32_e32 v6, 0x80008000, v6
	v_or_b32_e32 v7, 0x80008000, v7
	v_xor_b32_e32 v5, v6, v5
	v_xor_b32_e32 v4, v7, v4
	global_store_dwordx2 v[2:3], v[4:5], off offset:128
	v_cvt_pkrtz_f16_f32 v4, v126, v127
	v_cvt_pkrtz_f16_f32 v5, v128, v129
	v_lshrrev_b32_e32 v6, 15, v5
	v_lshrrev_b32_e32 v7, 15, v4
	v_and_b32_e32 v6, 0x10001, v6
	v_and_b32_e32 v7, 0x10001, v7
	v_mul_u32_u24_e32 v7, 0xffff, v7
	v_mul_u32_u24_e32 v6, 0xffff, v6
	v_or_b32_e32 v6, 0x80008000, v6
	v_or_b32_e32 v7, 0x80008000, v7
	v_xor_b32_e32 v5, v6, v5
	v_xor_b32_e32 v4, v7, v4
; DI void score_phase(const bf16_t* PROJ, unsigned short* SC, int c, char* smem, int bid, int nb) {
;     ...
; #pragma unroll
;     for (int mi = 0; mi < 2; ++mi) {
;       const int t = q0 + mi * 16 + fr;
;       unsigned short* op = SC + (size_t)(t - c * 4096) * S + s0 + fq * 4;
; #pragma unroll
;       for (int nj = 0; nj < 8; ++nj) {
;         unsigned w0 = __builtin_bit_cast(unsigned, __builtin_amdgcn_cvt_pkrtz(sc[mi][nj][0], sc[mi][nj][1]));
;         unsigned w1 = __builtin_bit_cast(unsigned, __builtin_amdgcn_cvt_pkrtz(sc[mi][nj][2], sc[mi][nj][3]));
;         const unsigned m0 = ((w0 >> 15) & 0x00010001u) * 0xffffu, m1 = ((w1 >> 15) & 0x00010001u) * 0xffffu;
;         w0 ^= (m0 | 0x80008000u); w1 ^= (m1 | 0x80008000u);
;         uint2 st2; st2.x = w0; st2.y = w1;
;         *(uint2*)(op + nj * 16) = st2;
;       }
;     }
;   }
	global_store_dwordx2 v[2:3], v[4:5], off offset:160
	v_cvt_pkrtz_f16_f32 v4, v122, v123
	v_cvt_pkrtz_f16_f32 v5, v124, v125
	v_lshrrev_b32_e32 v6, 15, v5
	v_lshrrev_b32_e32 v7, 15, v4
	v_and_b32_e32 v6, 0x10001, v6
	v_and_b32_e32 v7, 0x10001, v7
	v_mul_u32_u24_e32 v7, 0xffff, v7
	v_mul_u32_u24_e32 v6, 0xffff, v6
	v_or_b32_e32 v6, 0x80008000, v6
	v_or_b32_e32 v7, 0x80008000, v7
	v_xor_b32_e32 v5, v6, v5
	v_xor_b32_e32 v4, v7, v4
	global_store_dwordx2 v[2:3], v[4:5], off offset:192
	v_cvt_pkrtz_f16_f32 v4, v118, v119
	v_cvt_pkrtz_f16_f32 v5, v120, v121
	v_lshrrev_b32_e32 v6, 15, v5
	v_lshrrev_b32_e32 v7, 15, v4
	v_and_b32_e32 v6, 0x10001, v6
	v_and_b32_e32 v7, 0x10001, v7
	v_mul_u32_u24_e32 v7, 0xffff, v7
	v_mul_u32_u24_e32 v6, 0xffff, v6
	v_or_b32_e32 v6, 0x80008000, v6
	v_or_b32_e32 v7, 0x80008000, v7
	v_xor_b32_e32 v5, v6, v5
	v_xor_b32_e32 v4, v7, v4
	global_store_dwordx2 v[2:3], v[4:5], off offset:224
	v_or_b32_e32 v2, 16, v84
	v_ashrrev_i32_e32 v3, 31, v2
	v_lshlrev_b64 v[2:3], 15, v[2:3]
	v_lshl_add_u64 v[0:1], v[0:1], 0, v[2:3]
	v_cvt_pkrtz_f16_f32 v2, v114, v115
	v_cvt_pkrtz_f16_f32 v3, v116, v117
	v_lshrrev_b32_e32 v4, 15, v3
	v_lshrrev_b32_e32 v5, 15, v2
	v_and_b32_e32 v4, 0x10001, v4
	v_and_b32_e32 v5, 0x10001, v5
	v_mul_u32_u24_e32 v5, 0xffff, v5
	v_mul_u32_u24_e32 v4, 0xffff, v4
	v_or_b32_e32 v4, 0x80008000, v4
	v_or_b32_e32 v5, 0x80008000, v5
	v_xor_b32_e32 v3, v4, v3
	v_xor_b32_e32 v2, v5, v2
	global_store_dwordx2 v[0:1], v[2:3], off
	v_cvt_pkrtz_f16_f32 v2, v110, v111
	v_cvt_pkrtz_f16_f32 v3, v112, v113
	v_lshrrev_b32_e32 v4, 15, v3
	v_lshrrev_b32_e32 v5, 15, v2
	v_and_b32_e32 v4, 0x10001, v4
	v_and_b32_e32 v5, 0x10001, v5
	v_mul_u32_u24_e32 v5, 0xffff, v5
	v_mul_u32_u24_e32 v4, 0xffff, v4
	v_or_b32_e32 v4, 0x80008000, v4
	v_or_b32_e32 v5, 0x80008000, v5
	v_xor_b32_e32 v3, v4, v3
	v_xor_b32_e32 v2, v5, v2
	global_store_dwordx2 v[0:1], v[2:3], off offset:32
	v_cvt_pkrtz_f16_f32 v2, v106, v107
	v_cvt_pkrtz_f16_f32 v3, v108, v109
	v_lshrrev_b32_e32 v4, 15, v3
	v_lshrrev_b32_e32 v5, 15, v2
	v_and_b32_e32 v4, 0x10001, v4
	v_and_b32_e32 v5, 0x10001, v5
	v_mul_u32_u24_e32 v5, 0xffff, v5
	v_mul_u32_u24_e32 v4, 0xffff, v4
	v_or_b32_e32 v4, 0x80008000, v4
	v_or_b32_e32 v5, 0x80008000, v5
	v_xor_b32_e32 v3, v4, v3
	v_xor_b32_e32 v2, v5, v2
	global_store_dwordx2 v[0:1], v[2:3], off offset:64
	v_cvt_pkrtz_f16_f32 v2, v102, v103
	v_cvt_pkrtz_f16_f32 v3, v104, v105
	v_lshrrev_b32_e32 v4, 15, v3
	v_lshrrev_b32_e32 v5, 15, v2
	v_and_b32_e32 v4, 0x10001, v4
	v_and_b32_e32 v5, 0x10001, v5
	v_mul_u32_u24_e32 v5, 0xffff, v5
	v_mul_u32_u24_e32 v4, 0xffff, v4
	v_or_b32_e32 v4, 0x80008000, v4
	v_or_b32_e32 v5, 0x80008000, v5
	v_xor_b32_e32 v3, v4, v3
	v_xor_b32_e32 v2, v5, v2
	global_store_dwordx2 v[0:1], v[2:3], off offset:96
	v_cvt_pkrtz_f16_f32 v2, v98, v99
	v_cvt_pkrtz_f16_f32 v3, v100, v101
	v_lshrrev_b32_e32 v4, 15, v3
	v_lshrrev_b32_e32 v5, 15, v2
	v_and_b32_e32 v4, 0x10001, v4
	v_and_b32_e32 v5, 0x10001, v5
	v_mul_u32_u24_e32 v5, 0xffff, v5
	v_mul_u32_u24_e32 v4, 0xffff, v4
	v_or_b32_e32 v4, 0x80008000, v4
	v_or_b32_e32 v5, 0x80008000, v5
	v_xor_b32_e32 v3, v4, v3
	v_xor_b32_e32 v2, v5, v2
	global_store_dwordx2 v[0:1], v[2:3], off offset:128
	v_cvt_pkrtz_f16_f32 v2, v94, v95
	v_cvt_pkrtz_f16_f32 v3, v96, v97
	v_lshrrev_b32_e32 v4, 15, v3
	v_lshrrev_b32_e32 v5, 15, v2
	v_and_b32_e32 v4, 0x10001, v4
	v_and_b32_e32 v5, 0x10001, v5
	v_mul_u32_u24_e32 v5, 0xffff, v5
	v_mul_u32_u24_e32 v4, 0xffff, v4
	v_or_b32_e32 v4, 0x80008000, v4
	v_or_b32_e32 v5, 0x80008000, v5
	v_xor_b32_e32 v3, v4, v3
	v_xor_b32_e32 v2, v5, v2
	global_store_dwordx2 v[0:1], v[2:3], off offset:160
	v_cvt_pkrtz_f16_f32 v2, v90, v91
	v_cvt_pkrtz_f16_f32 v3, v92, v93
	v_lshrrev_b32_e32 v4, 15, v3
	v_lshrrev_b32_e32 v5, 15, v2
	v_and_b32_e32 v4, 0x10001, v4
	v_and_b32_e32 v5, 0x10001, v5
	v_mul_u32_u24_e32 v5, 0xffff, v5
	v_mul_u32_u24_e32 v4, 0xffff, v4
	v_or_b32_e32 v4, 0x80008000, v4
	v_or_b32_e32 v5, 0x80008000, v5
	v_xor_b32_e32 v3, v4, v3
	v_xor_b32_e32 v2, v5, v2
	global_store_dwordx2 v[0:1], v[2:3], off offset:192
	v_cvt_pkrtz_f16_f32 v2, v86, v87
	v_cvt_pkrtz_f16_f32 v3, v88, v89
	v_lshrrev_b32_e32 v4, 15, v3
	v_lshrrev_b32_e32 v5, 15, v2
	v_and_b32_e32 v4, 0x10001, v4
	v_and_b32_e32 v5, 0x10001, v5
	v_mul_u32_u24_e32 v5, 0xffff, v5
	v_mul_u32_u24_e32 v4, 0xffff, v4
	v_readlane_b32 s2, v249, 43
	v_or_b32_e32 v4, 0x80008000, v4
	v_or_b32_e32 v5, 0x80008000, v5
	s_add_i32 s8, s8, s2
	v_xor_b32_e32 v3, v4, v3
	v_xor_b32_e32 v2, v5, v2
	s_cmpk_gt_i32 s8, 0x20f
	v_readlane_b32 s3, v249, 44
	global_store_dwordx2 v[0:1], v[2:3], off offset:224
	s_cbranch_scc0 .LBB0_1568
	s_branch .LBB0_1577

; #define MFMA16(a, b, c) __builtin_amdgcn_mfma_f32_16x16x32_bf16((a), (b), (c), 0, 0, 0)
; DI void gld(u32x4v& r, const void* p) { asm volatile("global_load_dwordx4 %0, %1, off" : "=v"(r) : "v"(p) : "memory"); }
; #define WAIT_SET(N, a, b) asm volatile("s_waitcnt vmcnt(" #N ")" : "+v"(a[0]), "+v"(a[1]), "+v"(a[2]), "+v"(a[3]), "+v"(b[0]), "+v"(b[1]), "+v"(b[2]), "+v"(b[3]) :: "memory")
; DI void gemm_half(f32x4 (&acc)[4][4], const char* sa, const char* sb, int o0, int o1, u32x4v (&ra)[4], u32x4v (&rb)[4],
;                   char* stw, const bf16_t* Agn, const bf16_t* Bgn, int lda, int ldb) {
;   bf16x8 af0[4], bf0[4], af1[4], bf1[4];
; #pragma unroll
;   for (int i = 0; i < 4; ++i) { af0[i] = *(const bf16x8*)(sa + i * 16 * 128 + o0); bf0[i] = *(const bf16x8*)(sb + i * 16 * 128 + o0); }
;   __builtin_amdgcn_sched_barrier(0);
;   WAIT_SET(8, ra, rb);
; #pragma unroll
;   for (int g = 0; g < 8; ++g) {
; #pragma unroll
;     for (int ni = 0; ni < 4; ++ni) {
;       if (g < 4) acc[g][ni] = MFMA16(bf0[ni], af0[g], acc[g][ni]);
;       else acc[g - 4][ni] = MFMA16(bf1[ni], af1[g - 4], acc[g - 4][ni]);
;     }
;     if (g < 4) { af1[g] = *(const bf16x8*)(sa + g * 16 * 128 + o1); bf1[g] = *(const bf16x8*)(sb + g * 16 * 128 + o1);
;                  *(u32x4v*)(stw + g * 32 * 128) = ra[g]; gld(ra[g], Agn + (size_t)g * 32 * lda); }
;     else { *(u32x4v*)(stw + TILE_B + (g - 4) * 32 * 128) = rb[g - 4]; gld(rb[g - 4], Bgn + (size_t)(g - 4) * 32 * ldb); }
;     __builtin_amdgcn_sched_barrier(0);
;   }
; DI void gemm_kloop(f32x4 (&acc)[4][4], const bf16_t* Ag, const bf16_t* Bg, int lda, int ldb, int K, char* smem,
;                    u32x4v (&ra)[4], u32x4v (&rb)[4], u32x4v (&rc)[4], u32x4v (&rd)[4], bool pre,
;                    const bf16_t* Agn, const bf16_t* Bgn, bool hasnext) {
;     ...
;   for (int kt = 0; kt < nk; kt += 2) {
;     const bool last = kt + 2 >= nk;
;     const bf16_t* pa1 = last ? (hasnext ? Agn + 64 : Alast) : Ag + (size_t)(kt + 3) * 64;
;     const bf16_t* pb1 = last ? (hasnext ? Bgn + 64 : Blast) : Bg + (size_t)(kt + 3) * 64;
;     gemm_half(acc, sa0, sb0, o0, o1, rc, rd, st + 2 * TILE_B, pa1, pb1, lda, ldb);
;     __syncthreads();
.LBB0_1589:
	s_add_i32 s2, s2, 2
	s_cmp_gt_u32 s2, 5
	v_lshl_add_u64 v[182:183], v[150:151], 0, v[136:137]
	s_cselect_b64 vcc, -1, 0
	v_lshl_add_u64 v[162:163], v[182:183], 0, s[26:27]
	v_lshl_add_u64 v[212:213], v[152:153], 0, v[136:137]
	s_mov_b64 s[4:5], 0x2100180
	v_cndmask_b32_e32 v211, v163, v133, vcc
	v_cndmask_b32_e32 v210, v162, v146, vcc
	v_lshl_add_u64 v[162:163], v[212:213], 0, s[4:5]
	v_add_u32_e32 v184, v158, v160
	v_add_u32_e32 v228, v159, v160
	v_cndmask_b32_e32 v227, v163, v147, vcc
	v_cndmask_b32_e32 v226, v162, v148, vcc
	ds_read_b128 v[162:165], v184
	ds_read_b128 v[166:169], v228 offset:16384
	ds_read_b128 v[170:173], v184 offset:2048
	ds_read_b128 v[174:177], v228 offset:18432
	ds_read_b128 v[178:181], v184 offset:4096
	ds_read_b128 v[186:189], v228 offset:20480
	ds_read_b128 v[190:193], v184 offset:6144
	ds_read_b128 v[194:197], v228 offset:22528
	s_waitcnt vmcnt(8)
	s_setprio 1
	v_add_u32_e32 v229, v158, v161
	v_add_u32_e32 v230, v159, v161
	v_add_u32_e32 v231, v149, v157
	s_waitcnt lgkmcnt(6)
	v_mfma_f32_16x16x32_bf16 v[124:127], v[166:169], v[162:165], v[124:127]
	ds_read_b128 v[198:201], v230 offset:16384
	s_waitcnt lgkmcnt(5)
	v_mfma_f32_16x16x32_bf16 v[116:119], v[174:177], v[162:165], v[116:119]
	s_waitcnt lgkmcnt(3)
	v_mfma_f32_16x16x32_bf16 v[120:123], v[186:189], v[162:165], v[120:123]
	s_waitcnt lgkmcnt(1)
	v_mfma_f32_16x16x32_bf16 v[112:115], v[194:197], v[162:165], v[112:115]
	ds_read_b128 v[162:165], v229
	ds_write_b128 v231, v[12:15] offset:32768
	global_load_dwordx4 v[12:15], v[210:211], off
	v_mfma_f32_16x16x32_bf16 v[108:111], v[166:169], v[170:173], v[108:111]
	v_mfma_f32_16x16x32_bf16 v[100:103], v[174:177], v[170:173], v[100:103]
	v_mfma_f32_16x16x32_bf16 v[104:107], v[186:189], v[170:173], v[104:107]
	v_mfma_f32_16x16x32_bf16 v[96:99], v[194:197], v[170:173], v[96:99]
	ds_read_b128 v[170:173], v229 offset:2048
	ds_read_b128 v[202:205], v230 offset:18432
	ds_write_b128 v231, v[24:27] offset:36864
	v_lshl_add_u64 v[24:25], v[210:211], 0, s[18:19]
	global_load_dwordx4 v[24:27], v[24:25], off
	s_setprio 2
	v_mfma_f32_16x16x32_bf16 v[92:95], v[166:169], v[178:181], v[92:95]
	v_mfma_f32_16x16x32_bf16 v[84:87], v[174:177], v[178:181], v[84:87]
	v_mfma_f32_16x16x32_bf16 v[88:91], v[186:189], v[178:181], v[88:91]
	v_mfma_f32_16x16x32_bf16 v[80:83], v[194:197], v[178:181], v[80:83]
	ds_read_b128 v[178:181], v229 offset:4096
	ds_read_b128 v[206:209], v230 offset:20480
	ds_write_b128 v231, v[40:43] offset:40960
	v_lshl_add_u64 v[40:41], v[210:211], 0, s[20:21]
	global_load_dwordx4 v[40:43], v[40:41], off
	v_mfma_f32_16x16x32_bf16 v[76:79], v[166:169], v[190:193], v[76:79]
	v_mfma_f32_16x16x32_bf16 v[68:71], v[174:177], v[190:193], v[68:71]
	ds_read_b128 v[166:169], v229 offset:6144
	ds_read_b128 v[174:177], v230 offset:22528
	ds_write_b128 v231, v[48:51] offset:45056
	v_lshl_add_u64 v[48:49], v[210:211], 0, s[22:23]
	v_mfma_f32_16x16x32_bf16 v[72:75], v[186:189], v[190:193], v[72:75]
	global_load_dwordx4 v[48:51], v[48:49], off
	v_mfma_f32_16x16x32_bf16 v[64:67], v[194:197], v[190:193], v[64:67]
	s_waitcnt lgkmcnt(10)
	v_mfma_f32_16x16x32_bf16 v[124:127], v[198:201], v[162:165], v[124:127]
	ds_write_b128 v231, v[16:19] offset:49152
	global_load_dwordx4 v[16:19], v[226:227], off
	s_waitcnt lgkmcnt(8)
	v_mfma_f32_16x16x32_bf16 v[116:119], v[202:205], v[162:165], v[116:119]
	s_waitcnt lgkmcnt(5)
	v_mfma_f32_16x16x32_bf16 v[120:123], v[206:209], v[162:165], v[120:123]
	s_waitcnt lgkmcnt(2)
	v_mfma_f32_16x16x32_bf16 v[112:115], v[174:177], v[162:165], v[112:115]
	s_setprio 3
	v_mfma_f32_16x16x32_bf16 v[108:111], v[198:201], v[170:173], v[108:111]
	ds_write_b128 v231, v[28:31] offset:53248
	v_lshl_add_u64 v[28:29], v[226:227], 0, s[18:19]
	global_load_dwordx4 v[28:31], v[28:29], off
	v_mfma_f32_16x16x32_bf16 v[100:103], v[202:205], v[170:173], v[100:103]
	v_mfma_f32_16x16x32_bf16 v[104:107], v[206:209], v[170:173], v[104:107]
	v_mfma_f32_16x16x32_bf16 v[96:99], v[174:177], v[170:173], v[96:99]
	v_mfma_f32_16x16x32_bf16 v[92:95], v[198:201], v[178:181], v[92:95]
	ds_write_b128 v231, v[44:47] offset:57344
	v_lshl_add_u64 v[44:45], v[226:227], 0, s[20:21]
	global_load_dwordx4 v[44:47], v[44:45], off
	v_mfma_f32_16x16x32_bf16 v[84:87], v[202:205], v[178:181], v[84:87]
	v_mfma_f32_16x16x32_bf16 v[88:91], v[206:209], v[178:181], v[88:91]
	v_mfma_f32_16x16x32_bf16 v[80:83], v[174:177], v[178:181], v[80:83]
	v_mfma_f32_16x16x32_bf16 v[76:79], v[198:201], v[166:169], v[76:79]
	ds_write_b128 v231, v[52:55] offset:61440
	v_lshl_add_u64 v[52:53], v[226:227], 0, s[22:23]
	global_load_dwordx4 v[52:55], v[52:53], off
	v_mfma_f32_16x16x32_bf16 v[68:71], v[202:205], v[166:169], v[68:71]
	v_mfma_f32_16x16x32_bf16 v[72:75], v[206:209], v[166:169], v[72:75]
	v_mfma_f32_16x16x32_bf16 v[64:67], v[174:177], v[166:169], v[64:67]
	s_cmp_lt_u32 s2, 4
	s_cselect_b64 s[4:5], -1, 0
	s_and_b64 s[6:7], s[0:1], vcc
	v_lshl_add_u64 v[162:163], v[182:183], 0, s[28:29]
	v_cndmask_b32_e64 v164, v142, v138, s[6:7]
	v_cndmask_b32_e64 v165, v143, v139, s[6:7]
	s_mov_b64 s[16:17], 0x2100200
	v_cndmask_b32_e64 v183, v165, v163, s[4:5]
	v_cndmask_b32_e64 v182, v164, v162, s[4:5]
	v_lshl_add_u64 v[162:163], v[212:213], 0, s[16:17]
	v_cndmask_b32_e64 v164, v144, v140, s[6:7]
	v_cndmask_b32_e64 v165, v145, v141, s[6:7]
	s_setprio 0
	s_waitcnt lgkmcnt(0)
	s_barrier
; #define MFMA16(a, b, c) __builtin_amdgcn_mfma_f32_16x16x32_bf16((a), (b), (c), 0, 0, 0)
; DI void gld(u32x4v& r, const void* p) { asm volatile("global_load_dwordx4 %0, %1, off" : "=v"(r) : "v"(p) : "memory"); }
; #define WAIT_SET(N, a, b) asm volatile("s_waitcnt vmcnt(" #N ")" : "+v"(a[0]), "+v"(a[1]), "+v"(a[2]), "+v"(a[3]), "+v"(b[0]), "+v"(b[1]), "+v"(b[2]), "+v"(b[3]) :: "memory")
; DI void gemm_half(f32x4 (&acc)[4][4], const char* sa, const char* sb, int o0, int o1, u32x4v (&ra)[4], u32x4v (&rb)[4],
;                   char* stw, const bf16_t* Agn, const bf16_t* Bgn, int lda, int ldb) {
;   bf16x8 af0[4], bf0[4], af1[4], bf1[4];
; #pragma unroll
;   for (int i = 0; i < 4; ++i) { af0[i] = *(const bf16x8*)(sa + i * 16 * 128 + o0); bf0[i] = *(const bf16x8*)(sb + i * 16 * 128 + o0); }
;   __builtin_amdgcn_sched_barrier(0);
;   WAIT_SET(8, ra, rb);
; #pragma unroll
;   for (int g = 0; g < 8; ++g) {
; #pragma unroll
;     for (int ni = 0; ni < 4; ++ni) {
;       if (g < 4) acc[g][ni] = MFMA16(bf0[ni], af0[g], acc[g][ni]);
;       else acc[g - 4][ni] = MFMA16(bf1[ni], af1[g - 4], acc[g - 4][ni]);
;     }
;     if (g < 4) { af1[g] = *(const bf16x8*)(sa + g * 16 * 128 + o1); bf1[g] = *(const bf16x8*)(sb + g * 16 * 128 + o1);
;                  *(u32x4v*)(stw + g * 32 * 128) = ra[g]; gld(ra[g], Agn + (size_t)g * 32 * lda); }
;     else { *(u32x4v*)(stw + TILE_B + (g - 4) * 32 * 128) = rb[g - 4]; gld(rb[g - 4], Bgn + (size_t)(g - 4) * 32 * ldb); }
;     __builtin_amdgcn_sched_barrier(0);
;   }
; DI void gemm_kloop(f32x4 (&acc)[4][4], const bf16_t* Ag, const bf16_t* Bg, int lda, int ldb, int K, char* smem,
;                    u32x4v (&ra)[4], u32x4v (&rb)[4], u32x4v (&rc)[4], u32x4v (&rd)[4], bool pre,
;                    const bf16_t* Agn, const bf16_t* Bgn, bool hasnext) {
;     ...
;     const bf16_t* pa0 = kt + 4 < nk ? Ag + (size_t)(kt + 4) * 64 : ((last && hasnext) ? Agn : Alast);
;     const bf16_t* pb0 = kt + 4 < nk ? Bg + (size_t)(kt + 4) * 64 : ((last && hasnext) ? Bgn : Blast);
;     gemm_half(acc, sa0 + 2 * TILE_B, sb0 + 2 * TILE_B, o0, o1, ra, rb, st, pa0, pb0, lda, ldb);
;     __syncthreads();
;   }
;   if (!hasnext) { WAIT_SET(0, ra, rb); WAIT_SET(0, rc, rd); }
	v_cndmask_b32_e64 v211, v165, v163, s[4:5]
	v_cndmask_b32_e64 v210, v164, v162, s[4:5]
	ds_read_b128 v[162:165], v184 offset:32768
	ds_read_b128 v[166:169], v228 offset:49152
	ds_read_b128 v[170:173], v184 offset:34816
	ds_read_b128 v[174:177], v228 offset:51200
	ds_read_b128 v[178:181], v184 offset:36864
	ds_read_b128 v[186:189], v228 offset:53248
	ds_read_b128 v[190:193], v184 offset:38912
	ds_read_b128 v[194:197], v228 offset:55296
	s_waitcnt vmcnt(8)
	s_setprio 1
	s_waitcnt lgkmcnt(6)
	v_mfma_f32_16x16x32_bf16 v[124:127], v[166:169], v[162:165], v[124:127]
	s_waitcnt lgkmcnt(4)
	v_mfma_f32_16x16x32_bf16 v[116:119], v[174:177], v[162:165], v[116:119]
	s_waitcnt lgkmcnt(2)
	v_mfma_f32_16x16x32_bf16 v[120:123], v[186:189], v[162:165], v[120:123]
	s_waitcnt lgkmcnt(0)
	v_mfma_f32_16x16x32_bf16 v[112:115], v[194:197], v[162:165], v[112:115]
	ds_read_b128 v[162:165], v229 offset:32768
	ds_read_b128 v[198:201], v230 offset:49152
	ds_write_b128 v231, v[0:3]
	global_load_dwordx4 v[0:3], v[182:183], off
	v_mfma_f32_16x16x32_bf16 v[108:111], v[166:169], v[170:173], v[108:111]
	v_mfma_f32_16x16x32_bf16 v[100:103], v[174:177], v[170:173], v[100:103]
	v_mfma_f32_16x16x32_bf16 v[104:107], v[186:189], v[170:173], v[104:107]
	v_mfma_f32_16x16x32_bf16 v[96:99], v[194:197], v[170:173], v[96:99]
	ds_read_b128 v[170:173], v229 offset:34816
	ds_read_b128 v[202:205], v230 offset:51200
	ds_write_b128 v231, v[8:11] offset:4096
	v_lshl_add_u64 v[8:9], v[182:183], 0, s[18:19]
	global_load_dwordx4 v[8:11], v[8:9], off
	s_setprio 2
	v_mfma_f32_16x16x32_bf16 v[92:95], v[166:169], v[178:181], v[92:95]
	v_mfma_f32_16x16x32_bf16 v[84:87], v[174:177], v[178:181], v[84:87]
	v_mfma_f32_16x16x32_bf16 v[88:91], v[186:189], v[178:181], v[88:91]
	v_mfma_f32_16x16x32_bf16 v[80:83], v[194:197], v[178:181], v[80:83]
	ds_read_b128 v[178:181], v229 offset:36864
	ds_read_b128 v[206:209], v230 offset:53248
	ds_write_b128 v231, v[32:35] offset:8192
	v_lshl_add_u64 v[32:33], v[182:183], 0, s[20:21]
	global_load_dwordx4 v[32:35], v[32:33], off
	v_mfma_f32_16x16x32_bf16 v[76:79], v[166:169], v[190:193], v[76:79]
	v_mfma_f32_16x16x32_bf16 v[68:71], v[174:177], v[190:193], v[68:71]
	ds_read_b128 v[166:169], v229 offset:38912
	ds_read_b128 v[174:177], v230 offset:55296
	ds_write_b128 v231, v[56:59] offset:12288
	v_lshl_add_u64 v[56:57], v[182:183], 0, s[22:23]
	v_mfma_f32_16x16x32_bf16 v[72:75], v[186:189], v[190:193], v[72:75]
	global_load_dwordx4 v[56:59], v[56:57], off
	v_mfma_f32_16x16x32_bf16 v[64:67], v[194:197], v[190:193], v[64:67]
	s_waitcnt lgkmcnt(10)
	v_mfma_f32_16x16x32_bf16 v[124:127], v[198:201], v[162:165], v[124:127]
	ds_write_b128 v231, v[4:7] offset:16384
	global_load_dwordx4 v[4:7], v[210:211], off
	s_waitcnt lgkmcnt(8)
	v_mfma_f32_16x16x32_bf16 v[116:119], v[202:205], v[162:165], v[116:119]
	s_waitcnt lgkmcnt(5)
	v_mfma_f32_16x16x32_bf16 v[120:123], v[206:209], v[162:165], v[120:123]
	s_waitcnt lgkmcnt(2)
	v_mfma_f32_16x16x32_bf16 v[112:115], v[174:177], v[162:165], v[112:115]
	s_setprio 3
	v_mfma_f32_16x16x32_bf16 v[108:111], v[198:201], v[170:173], v[108:111]
	ds_write_b128 v231, v[20:23] offset:20480
	v_lshl_add_u64 v[20:21], v[210:211], 0, s[18:19]
	global_load_dwordx4 v[20:23], v[20:21], off
	v_mfma_f32_16x16x32_bf16 v[100:103], v[202:205], v[170:173], v[100:103]
	v_mfma_f32_16x16x32_bf16 v[104:107], v[206:209], v[170:173], v[104:107]
	v_mfma_f32_16x16x32_bf16 v[96:99], v[174:177], v[170:173], v[96:99]
	v_mfma_f32_16x16x32_bf16 v[92:95], v[198:201], v[178:181], v[92:95]
	ds_write_b128 v231, v[36:39] offset:24576
	v_lshl_add_u64 v[36:37], v[210:211], 0, s[20:21]
	global_load_dwordx4 v[36:39], v[36:37], off
	v_mfma_f32_16x16x32_bf16 v[84:87], v[202:205], v[178:181], v[84:87]
	v_mfma_f32_16x16x32_bf16 v[88:91], v[206:209], v[178:181], v[88:91]
	v_mfma_f32_16x16x32_bf16 v[80:83], v[174:177], v[178:181], v[80:83]
	v_mfma_f32_16x16x32_bf16 v[76:79], v[198:201], v[166:169], v[76:79]
	ds_write_b128 v231, v[60:63] offset:28672
	v_lshl_add_u64 v[60:61], v[210:211], 0, s[22:23]
	global_load_dwordx4 v[60:63], v[60:61], off
	v_mfma_f32_16x16x32_bf16 v[68:71], v[202:205], v[166:169], v[68:71]
	v_mfma_f32_16x16x32_bf16 v[72:75], v[206:209], v[166:169], v[72:75]
	v_mfma_f32_16x16x32_bf16 v[64:67], v[174:177], v[166:169], v[64:67]
	v_lshl_add_u64 v[150:151], v[150:151], 0, s[24:25]
	v_lshl_add_u64 v[152:153], v[152:153], 0, s[24:25]
	s_and_b64 vcc, exec, vcc
	s_setprio 0
	s_waitcnt lgkmcnt(0)
	s_barrier
	s_cbranch_vccz .LBB0_1589
	s_and_b64 vcc, exec, s[8:9]
	s_cbranch_vccz .LBB0_1592
	s_waitcnt vmcnt(0)
	s_waitcnt vmcnt(0)

; #define MFMA16(a, b, c) __builtin_amdgcn_mfma_f32_16x16x32_bf16((a), (b), (c), 0, 0, 0)
; DI void gld(u32x4v& r, const void* p) { asm volatile("global_load_dwordx4 %0, %1, off" : "=v"(r) : "v"(p) : "memory"); }
; #define WAIT_SET(N, a, b) asm volatile("s_waitcnt vmcnt(" #N ")" : "+v"(a[0]), "+v"(a[1]), "+v"(a[2]), "+v"(a[3]), "+v"(b[0]), "+v"(b[1]), "+v"(b[2]), "+v"(b[3]) :: "memory")
; DI void gemm_half(f32x4 (&acc)[4][4], const char* sa, const char* sb, int o0, int o1, u32x4v (&ra)[4], u32x4v (&rb)[4],
;                   char* stw, const bf16_t* Agn, const bf16_t* Bgn, int lda, int ldb) {
;   bf16x8 af0[4], bf0[4], af1[4], bf1[4];
; #pragma unroll
;   for (int i = 0; i < 4; ++i) { af0[i] = *(const bf16x8*)(sa + i * 16 * 128 + o0); bf0[i] = *(const bf16x8*)(sb + i * 16 * 128 + o0); }
;   __builtin_amdgcn_sched_barrier(0);
;   WAIT_SET(8, ra, rb);
; #pragma unroll
;   for (int g = 0; g < 8; ++g) {
; #pragma unroll
;     for (int ni = 0; ni < 4; ++ni) {
;       if (g < 4) acc[g][ni] = MFMA16(bf0[ni], af0[g], acc[g][ni]);
;       else acc[g - 4][ni] = MFMA16(bf1[ni], af1[g - 4], acc[g - 4][ni]);
;     }
;     if (g < 4) { af1[g] = *(const bf16x8*)(sa + g * 16 * 128 + o1); bf1[g] = *(const bf16x8*)(sb + g * 16 * 128 + o1);
;                  *(u32x4v*)(stw + g * 32 * 128) = ra[g]; gld(ra[g], Agn + (size_t)g * 32 * lda); }
;     else { *(u32x4v*)(stw + TILE_B + (g - 4) * 32 * 128) = rb[g - 4]; gld(rb[g - 4], Bgn + (size_t)(g - 4) * 32 * ldb); }
;     __builtin_amdgcn_sched_barrier(0);
;   }
; DI void gemm_kloop(f32x4 (&acc)[4][4], const bf16_t* Ag, const bf16_t* Bg, int lda, int ldb, int K, char* smem,
;                    u32x4v (&ra)[4], u32x4v (&rb)[4], u32x4v (&rc)[4], u32x4v (&rd)[4], bool pre,
;                    const bf16_t* Agn, const bf16_t* Bgn, bool hasnext) {
;     ...
;   for (int kt = 0; kt < nk; kt += 2) {
;     const bool last = kt + 2 >= nk;
;     const bf16_t* pa1 = last ? (hasnext ? Agn + 64 : Alast) : Ag + (size_t)(kt + 3) * 64;
;     const bf16_t* pb1 = last ? (hasnext ? Bgn + 64 : Blast) : Bg + (size_t)(kt + 3) * 64;
;     gemm_half(acc, sa0, sb0, o0, o1, rc, rd, st + 2 * TILE_B, pa1, pb1, lda, ldb);
;     __syncthreads();
.LBB0_1609:
	s_add_i32 s15, s15, 2
	s_cmp_gt_u32 s15, 5
	v_lshl_add_u64 v[210:211], v[148:149], 0, v[134:135]
	s_cselect_b64 vcc, -1, 0
	v_lshl_add_u64 v[164:165], v[210:211], 0, s[26:27]
	v_lshl_add_u64 v[226:227], v[150:151], 0, v[134:135]
	s_mov_b64 s[0:1], 0x2280180
	v_cndmask_b32_e32 v213, v165, v145, vcc
	v_cndmask_b32_e32 v212, v164, v144, vcc
	v_lshl_add_u64 v[164:165], v[226:227], 0, s[0:1]
	v_add_u32_e32 v163, v159, v161
	v_add_u32_e32 v230, v160, v161
	v_cndmask_b32_e32 v229, v165, v147, vcc
	v_cndmask_b32_e32 v228, v164, v146, vcc
	ds_read_b128 v[164:167], v163
	ds_read_b128 v[168:171], v230 offset:16384
	ds_read_b128 v[172:175], v163 offset:2048
	ds_read_b128 v[176:179], v230 offset:18432
	ds_read_b128 v[180:183], v163 offset:4096
	ds_read_b128 v[186:189], v230 offset:20480
	ds_read_b128 v[190:193], v163 offset:6144
	ds_read_b128 v[194:197], v230 offset:22528
	s_waitcnt vmcnt(8)
	s_setprio 1
	v_add_u32_e32 v231, v159, v162
	v_add_u32_e32 v232, v160, v162
	v_add_u32_e32 v233, v157, v158
	s_waitcnt lgkmcnt(6)
	v_mfma_f32_16x16x32_bf16 v[124:127], v[168:171], v[164:167], v[124:127]
	ds_read_b128 v[198:201], v232 offset:16384
	s_waitcnt lgkmcnt(5)
	v_mfma_f32_16x16x32_bf16 v[120:123], v[176:179], v[164:167], v[120:123]
	s_waitcnt lgkmcnt(3)
	v_mfma_f32_16x16x32_bf16 v[116:119], v[186:189], v[164:167], v[116:119]
	s_waitcnt lgkmcnt(1)
	v_mfma_f32_16x16x32_bf16 v[112:115], v[194:197], v[164:167], v[112:115]
	ds_read_b128 v[164:167], v231
	ds_write_b128 v233, v[12:15] offset:32768
	global_load_dwordx4 v[12:15], v[212:213], off
	v_mfma_f32_16x16x32_bf16 v[108:111], v[168:171], v[172:175], v[108:111]
	v_mfma_f32_16x16x32_bf16 v[104:107], v[176:179], v[172:175], v[104:107]
	v_mfma_f32_16x16x32_bf16 v[100:103], v[186:189], v[172:175], v[100:103]
	v_mfma_f32_16x16x32_bf16 v[96:99], v[194:197], v[172:175], v[96:99]
	ds_read_b128 v[172:175], v231 offset:2048
	ds_read_b128 v[202:205], v232 offset:18432
	ds_write_b128 v233, v[24:27] offset:36864
	v_lshl_add_u64 v[24:25], v[212:213], 0, s[18:19]
	global_load_dwordx4 v[24:27], v[24:25], off
	s_setprio 2
	v_mfma_f32_16x16x32_bf16 v[92:95], v[168:171], v[180:183], v[92:95]
	v_mfma_f32_16x16x32_bf16 v[88:91], v[176:179], v[180:183], v[88:91]
	v_mfma_f32_16x16x32_bf16 v[84:87], v[186:189], v[180:183], v[84:87]
	v_mfma_f32_16x16x32_bf16 v[80:83], v[194:197], v[180:183], v[80:83]
	ds_read_b128 v[180:183], v231 offset:4096
	ds_read_b128 v[206:209], v232 offset:20480
	ds_write_b128 v233, v[40:43] offset:40960
	v_lshl_add_u64 v[40:41], v[212:213], 0, s[20:21]
	global_load_dwordx4 v[40:43], v[40:41], off
	v_mfma_f32_16x16x32_bf16 v[76:79], v[168:171], v[190:193], v[76:79]
	v_mfma_f32_16x16x32_bf16 v[72:75], v[176:179], v[190:193], v[72:75]
	ds_read_b128 v[168:171], v231 offset:6144
	ds_read_b128 v[176:179], v232 offset:22528
	ds_write_b128 v233, v[48:51] offset:45056
	v_lshl_add_u64 v[48:49], v[212:213], 0, s[22:23]
	v_mfma_f32_16x16x32_bf16 v[68:71], v[186:189], v[190:193], v[68:71]
	global_load_dwordx4 v[48:51], v[48:49], off
	v_mfma_f32_16x16x32_bf16 v[64:67], v[194:197], v[190:193], v[64:67]
	s_waitcnt lgkmcnt(10)
	v_mfma_f32_16x16x32_bf16 v[124:127], v[198:201], v[164:167], v[124:127]
	ds_write_b128 v233, v[16:19] offset:49152
	global_load_dwordx4 v[16:19], v[228:229], off
	s_waitcnt lgkmcnt(8)
	v_mfma_f32_16x16x32_bf16 v[120:123], v[202:205], v[164:167], v[120:123]
	s_waitcnt lgkmcnt(5)
	v_mfma_f32_16x16x32_bf16 v[116:119], v[206:209], v[164:167], v[116:119]
	s_waitcnt lgkmcnt(2)
	v_mfma_f32_16x16x32_bf16 v[112:115], v[176:179], v[164:167], v[112:115]
	s_setprio 3
	v_mfma_f32_16x16x32_bf16 v[108:111], v[198:201], v[172:175], v[108:111]
	ds_write_b128 v233, v[28:31] offset:53248
	v_lshl_add_u64 v[28:29], v[228:229], 0, s[18:19]
	global_load_dwordx4 v[28:31], v[28:29], off
	v_mfma_f32_16x16x32_bf16 v[104:107], v[202:205], v[172:175], v[104:107]
	v_mfma_f32_16x16x32_bf16 v[100:103], v[206:209], v[172:175], v[100:103]
	v_mfma_f32_16x16x32_bf16 v[96:99], v[176:179], v[172:175], v[96:99]
	v_mfma_f32_16x16x32_bf16 v[92:95], v[198:201], v[180:183], v[92:95]
	ds_write_b128 v233, v[44:47] offset:57344
	v_lshl_add_u64 v[44:45], v[228:229], 0, s[20:21]
	global_load_dwordx4 v[44:47], v[44:45], off
	v_mfma_f32_16x16x32_bf16 v[88:91], v[202:205], v[180:183], v[88:91]
	v_mfma_f32_16x16x32_bf16 v[84:87], v[206:209], v[180:183], v[84:87]
	v_mfma_f32_16x16x32_bf16 v[80:83], v[176:179], v[180:183], v[80:83]
	v_mfma_f32_16x16x32_bf16 v[76:79], v[198:201], v[168:171], v[76:79]
	ds_write_b128 v233, v[52:55] offset:61440
	v_lshl_add_u64 v[52:53], v[228:229], 0, s[22:23]
	global_load_dwordx4 v[52:55], v[52:53], off
	v_mfma_f32_16x16x32_bf16 v[72:75], v[202:205], v[168:171], v[72:75]
	v_mfma_f32_16x16x32_bf16 v[68:71], v[206:209], v[168:171], v[68:71]
	v_mfma_f32_16x16x32_bf16 v[64:67], v[176:179], v[168:171], v[64:67]
	s_cmp_lt_u32 s15, 4
	s_cselect_b64 s[0:1], -1, 0
	s_and_b64 s[4:5], s[8:9], vcc
	v_lshl_add_u64 v[164:165], v[210:211], 0, s[28:29]
	v_cndmask_b32_e64 v166, v140, v136, s[4:5]
	v_cndmask_b32_e64 v167, v141, v137, s[4:5]
	s_mov_b64 s[16:17], 0x2280200
	v_cndmask_b32_e64 v211, v167, v165, s[0:1]
	v_cndmask_b32_e64 v210, v166, v164, s[0:1]
	v_lshl_add_u64 v[164:165], v[226:227], 0, s[16:17]
	v_cndmask_b32_e64 v166, v142, v138, s[4:5]
	v_cndmask_b32_e64 v167, v143, v139, s[4:5]
	s_setprio 0
	s_waitcnt lgkmcnt(0)
	s_barrier
; #define MFMA16(a, b, c) __builtin_amdgcn_mfma_f32_16x16x32_bf16((a), (b), (c), 0, 0, 0)
; DI void gld(u32x4v& r, const void* p) { asm volatile("global_load_dwordx4 %0, %1, off" : "=v"(r) : "v"(p) : "memory"); }
; #define WAIT_SET(N, a, b) asm volatile("s_waitcnt vmcnt(" #N ")" : "+v"(a[0]), "+v"(a[1]), "+v"(a[2]), "+v"(a[3]), "+v"(b[0]), "+v"(b[1]), "+v"(b[2]), "+v"(b[3]) :: "memory")
; DI void gemm_half(f32x4 (&acc)[4][4], const char* sa, const char* sb, int o0, int o1, u32x4v (&ra)[4], u32x4v (&rb)[4],
;                   char* stw, const bf16_t* Agn, const bf16_t* Bgn, int lda, int ldb) {
;   bf16x8 af0[4], bf0[4], af1[4], bf1[4];
; #pragma unroll
;   for (int i = 0; i < 4; ++i) { af0[i] = *(const bf16x8*)(sa + i * 16 * 128 + o0); bf0[i] = *(const bf16x8*)(sb + i * 16 * 128 + o0); }
;   __builtin_amdgcn_sched_barrier(0);
;   WAIT_SET(8, ra, rb);
; #pragma unroll
;   for (int g = 0; g < 8; ++g) {
; #pragma unroll
;     for (int ni = 0; ni < 4; ++ni) {
;       if (g < 4) acc[g][ni] = MFMA16(bf0[ni], af0[g], acc[g][ni]);
;       else acc[g - 4][ni] = MFMA16(bf1[ni], af1[g - 4], acc[g - 4][ni]);
;     }
;     if (g < 4) { af1[g] = *(const bf16x8*)(sa + g * 16 * 128 + o1); bf1[g] = *(const bf16x8*)(sb + g * 16 * 128 + o1);
;                  *(u32x4v*)(stw + g * 32 * 128) = ra[g]; gld(ra[g], Agn + (size_t)g * 32 * lda); }
;     else { *(u32x4v*)(stw + TILE_B + (g - 4) * 32 * 128) = rb[g - 4]; gld(rb[g - 4], Bgn + (size_t)(g - 4) * 32 * ldb); }
;     __builtin_amdgcn_sched_barrier(0);
;   }
; DI void gemm_kloop(f32x4 (&acc)[4][4], const bf16_t* Ag, const bf16_t* Bg, int lda, int ldb, int K, char* smem,
;                    u32x4v (&ra)[4], u32x4v (&rb)[4], u32x4v (&rc)[4], u32x4v (&rd)[4], bool pre,
;                    const bf16_t* Agn, const bf16_t* Bgn, bool hasnext) {
;     ...
;     const bf16_t* pa0 = kt + 4 < nk ? Ag + (size_t)(kt + 4) * 64 : ((last && hasnext) ? Agn : Alast);
;     const bf16_t* pb0 = kt + 4 < nk ? Bg + (size_t)(kt + 4) * 64 : ((last && hasnext) ? Bgn : Blast);
;     gemm_half(acc, sa0 + 2 * TILE_B, sb0 + 2 * TILE_B, o0, o1, ra, rb, st, pa0, pb0, lda, ldb);
;     __syncthreads();
;   }
;   if (!hasnext) { WAIT_SET(0, ra, rb); WAIT_SET(0, rc, rd); }
	v_cndmask_b32_e64 v213, v167, v165, s[0:1]
	v_cndmask_b32_e64 v212, v166, v164, s[0:1]
	ds_read_b128 v[164:167], v163 offset:32768
	ds_read_b128 v[168:171], v230 offset:49152
	ds_read_b128 v[172:175], v163 offset:34816
	ds_read_b128 v[176:179], v230 offset:51200
	ds_read_b128 v[180:183], v163 offset:36864
	ds_read_b128 v[186:189], v230 offset:53248
	ds_read_b128 v[190:193], v163 offset:38912
	ds_read_b128 v[194:197], v230 offset:55296
	s_waitcnt vmcnt(8)
	s_setprio 1
	s_waitcnt lgkmcnt(6)
	v_mfma_f32_16x16x32_bf16 v[124:127], v[168:171], v[164:167], v[124:127]
	s_waitcnt lgkmcnt(4)
	v_mfma_f32_16x16x32_bf16 v[120:123], v[176:179], v[164:167], v[120:123]
	s_waitcnt lgkmcnt(2)
	v_mfma_f32_16x16x32_bf16 v[116:119], v[186:189], v[164:167], v[116:119]
	s_waitcnt lgkmcnt(0)
	v_mfma_f32_16x16x32_bf16 v[112:115], v[194:197], v[164:167], v[112:115]
	ds_read_b128 v[164:167], v231 offset:32768
	ds_read_b128 v[198:201], v232 offset:49152
	ds_write_b128 v233, v[0:3]
	global_load_dwordx4 v[0:3], v[210:211], off
	v_mfma_f32_16x16x32_bf16 v[108:111], v[168:171], v[172:175], v[108:111]
	v_mfma_f32_16x16x32_bf16 v[104:107], v[176:179], v[172:175], v[104:107]
	v_mfma_f32_16x16x32_bf16 v[100:103], v[186:189], v[172:175], v[100:103]
	v_mfma_f32_16x16x32_bf16 v[96:99], v[194:197], v[172:175], v[96:99]
	ds_read_b128 v[172:175], v231 offset:34816
	ds_read_b128 v[202:205], v232 offset:51200
	ds_write_b128 v233, v[8:11] offset:4096
	v_lshl_add_u64 v[8:9], v[210:211], 0, s[18:19]
	global_load_dwordx4 v[8:11], v[8:9], off
	s_setprio 2
	v_mfma_f32_16x16x32_bf16 v[92:95], v[168:171], v[180:183], v[92:95]
	v_mfma_f32_16x16x32_bf16 v[88:91], v[176:179], v[180:183], v[88:91]
	v_mfma_f32_16x16x32_bf16 v[84:87], v[186:189], v[180:183], v[84:87]
	v_mfma_f32_16x16x32_bf16 v[80:83], v[194:197], v[180:183], v[80:83]
	ds_read_b128 v[180:183], v231 offset:36864
	ds_read_b128 v[206:209], v232 offset:53248
	ds_write_b128 v233, v[32:35] offset:8192
	v_lshl_add_u64 v[32:33], v[210:211], 0, s[20:21]
	global_load_dwordx4 v[32:35], v[32:33], off
	v_mfma_f32_16x16x32_bf16 v[76:79], v[168:171], v[190:193], v[76:79]
	v_mfma_f32_16x16x32_bf16 v[72:75], v[176:179], v[190:193], v[72:75]
	ds_read_b128 v[168:171], v231 offset:38912
	ds_read_b128 v[176:179], v232 offset:55296
	ds_write_b128 v233, v[56:59] offset:12288
	v_lshl_add_u64 v[56:57], v[210:211], 0, s[22:23]
	v_mfma_f32_16x16x32_bf16 v[68:71], v[186:189], v[190:193], v[68:71]
	global_load_dwordx4 v[56:59], v[56:57], off
	v_mfma_f32_16x16x32_bf16 v[64:67], v[194:197], v[190:193], v[64:67]
	s_waitcnt lgkmcnt(10)
	v_mfma_f32_16x16x32_bf16 v[124:127], v[198:201], v[164:167], v[124:127]
	ds_write_b128 v233, v[4:7] offset:16384
	global_load_dwordx4 v[4:7], v[212:213], off
	s_waitcnt lgkmcnt(8)
	v_mfma_f32_16x16x32_bf16 v[120:123], v[202:205], v[164:167], v[120:123]
	s_waitcnt lgkmcnt(5)
	v_mfma_f32_16x16x32_bf16 v[116:119], v[206:209], v[164:167], v[116:119]
	s_waitcnt lgkmcnt(2)
	v_mfma_f32_16x16x32_bf16 v[112:115], v[176:179], v[164:167], v[112:115]
	s_setprio 3
	v_mfma_f32_16x16x32_bf16 v[108:111], v[198:201], v[172:175], v[108:111]
	ds_write_b128 v233, v[20:23] offset:20480
	v_lshl_add_u64 v[20:21], v[212:213], 0, s[18:19]
	global_load_dwordx4 v[20:23], v[20:21], off
	v_mfma_f32_16x16x32_bf16 v[104:107], v[202:205], v[172:175], v[104:107]
	v_mfma_f32_16x16x32_bf16 v[100:103], v[206:209], v[172:175], v[100:103]
	v_mfma_f32_16x16x32_bf16 v[96:99], v[176:179], v[172:175], v[96:99]
	v_mfma_f32_16x16x32_bf16 v[92:95], v[198:201], v[180:183], v[92:95]
	ds_write_b128 v233, v[36:39] offset:24576
	v_lshl_add_u64 v[36:37], v[212:213], 0, s[20:21]
	global_load_dwordx4 v[36:39], v[36:37], off
	v_mfma_f32_16x16x32_bf16 v[88:91], v[202:205], v[180:183], v[88:91]
	v_mfma_f32_16x16x32_bf16 v[84:87], v[206:209], v[180:183], v[84:87]
	v_mfma_f32_16x16x32_bf16 v[80:83], v[176:179], v[180:183], v[80:83]
	v_mfma_f32_16x16x32_bf16 v[76:79], v[198:201], v[168:171], v[76:79]
	ds_write_b128 v233, v[60:63] offset:28672
	v_lshl_add_u64 v[60:61], v[212:213], 0, s[22:23]
	global_load_dwordx4 v[60:63], v[60:61], off
	v_mfma_f32_16x16x32_bf16 v[72:75], v[202:205], v[168:171], v[72:75]
	v_mfma_f32_16x16x32_bf16 v[68:71], v[206:209], v[168:171], v[68:71]
	v_mfma_f32_16x16x32_bf16 v[64:67], v[176:179], v[168:171], v[64:67]
	v_lshl_add_u64 v[148:149], v[148:149], 0, s[24:25]
	v_lshl_add_u64 v[150:151], v[150:151], 0, s[24:25]
	s_and_b64 vcc, exec, vcc
	s_setprio 0
	s_waitcnt lgkmcnt(0)
	s_barrier
	s_cbranch_vccz .LBB0_1609
	s_and_b64 vcc, exec, s[6:7]
	s_cbranch_vccz .LBB0_1612
	s_waitcnt vmcnt(0)
	s_waitcnt vmcnt(0)

; #define MFMA16(a, b, c) __builtin_amdgcn_mfma_f32_16x16x32_bf16((a), (b), (c), 0, 0, 0)
; DI void gld(u32x4v& r, const void* p) { asm volatile("global_load_dwordx4 %0, %1, off" : "=v"(r) : "v"(p) : "memory"); }
; #define WAIT_SET(N, a, b) asm volatile("s_waitcnt vmcnt(" #N ")" : "+v"(a[0]), "+v"(a[1]), "+v"(a[2]), "+v"(a[3]), "+v"(b[0]), "+v"(b[1]), "+v"(b[2]), "+v"(b[3]) :: "memory")
; DI void gemm_half(f32x4 (&acc)[4][4], const char* sa, const char* sb, int o0, int o1, u32x4v (&ra)[4], u32x4v (&rb)[4],
;                   char* stw, const bf16_t* Agn, const bf16_t* Bgn, int lda, int ldb) {
;   bf16x8 af0[4], bf0[4], af1[4], bf1[4];
; #pragma unroll
;   for (int i = 0; i < 4; ++i) { af0[i] = *(const bf16x8*)(sa + i * 16 * 128 + o0); bf0[i] = *(const bf16x8*)(sb + i * 16 * 128 + o0); }
;   __builtin_amdgcn_sched_barrier(0);
;   WAIT_SET(8, ra, rb);
; #pragma unroll
;   for (int g = 0; g < 8; ++g) {
; #pragma unroll
;     for (int ni = 0; ni < 4; ++ni) {
;       if (g < 4) acc[g][ni] = MFMA16(bf0[ni], af0[g], acc[g][ni]);
;       else acc[g - 4][ni] = MFMA16(bf1[ni], af1[g - 4], acc[g - 4][ni]);
;     }
;     if (g < 4) { af1[g] = *(const bf16x8*)(sa + g * 16 * 128 + o1); bf1[g] = *(const bf16x8*)(sb + g * 16 * 128 + o1);
;                  *(u32x4v*)(stw + g * 32 * 128) = ra[g]; gld(ra[g], Agn + (size_t)g * 32 * lda); }
;     else { *(u32x4v*)(stw + TILE_B + (g - 4) * 32 * 128) = rb[g - 4]; gld(rb[g - 4], Bgn + (size_t)(g - 4) * 32 * ldb); }
;     __builtin_amdgcn_sched_barrier(0);
;   }
; DI void gemm_kloop(f32x4 (&acc)[4][4], const bf16_t* Ag, const bf16_t* Bg, int lda, int ldb, int K, char* smem,
;                    u32x4v (&ra)[4], u32x4v (&rb)[4], u32x4v (&rc)[4], u32x4v (&rd)[4], bool pre,
;                    const bf16_t* Agn, const bf16_t* Bgn, bool hasnext) {
;     ...
;   for (int kt = 0; kt < nk; kt += 2) {
;     const bool last = kt + 2 >= nk;
;     const bf16_t* pa1 = last ? (hasnext ? Agn + 64 : Alast) : Ag + (size_t)(kt + 3) * 64;
;     const bf16_t* pb1 = last ? (hasnext ? Bgn + 64 : Blast) : Bg + (size_t)(kt + 3) * 64;
;     gemm_half(acc, sa0, sb0, o0, o1, rc, rd, st + 2 * TILE_B, pa1, pb1, lda, ldb);
;     __syncthreads();
.LBB0_1632:
	s_add_i32 s2, s2, 2
	s_cmp_gt_u32 s2, 29
	v_lshl_add_u64 v[158:159], v[148:149], 0, v[134:135]
	s_cselect_b64 vcc, -1, 0
	v_lshl_add_u64 v[164:165], v[158:159], 0, s[26:27]
	v_lshl_add_u64 v[212:213], v[150:151], 0, v[134:135]
	v_cndmask_b32_e32 v211, v165, v145, vcc
	v_cndmask_b32_e32 v210, v164, v144, vcc
	v_lshl_add_u64 v[164:165], v[212:213], 0, s[30:31]
	v_add_u32_e32 v184, v154, v156
	v_add_u32_e32 v228, v155, v156
	v_cndmask_b32_e32 v227, v165, v147, vcc
	v_cndmask_b32_e32 v226, v164, v146, vcc
	ds_read_b128 v[164:167], v184
	ds_read_b128 v[168:171], v228 offset:16384
	ds_read_b128 v[172:175], v184 offset:2048
	ds_read_b128 v[176:179], v228 offset:18432
	ds_read_b128 v[180:183], v184 offset:4096
	ds_read_b128 v[186:189], v228 offset:20480
	ds_read_b128 v[190:193], v184 offset:6144
	ds_read_b128 v[194:197], v228 offset:22528
	s_waitcnt vmcnt(8)
	s_setprio 1
	v_add_u32_e32 v229, v154, v157
	v_add_u32_e32 v230, v155, v157
	v_add_u32_e32 v231, v152, v153
	s_waitcnt lgkmcnt(6)
	v_mfma_f32_16x16x32_bf16 v[124:127], v[168:171], v[164:167], v[124:127]
	ds_read_b128 v[198:201], v230 offset:16384
	s_waitcnt lgkmcnt(5)
	v_mfma_f32_16x16x32_bf16 v[120:123], v[176:179], v[164:167], v[120:123]
	s_waitcnt lgkmcnt(3)
	v_mfma_f32_16x16x32_bf16 v[116:119], v[186:189], v[164:167], v[116:119]
	s_waitcnt lgkmcnt(1)
	v_mfma_f32_16x16x32_bf16 v[112:115], v[194:197], v[164:167], v[112:115]
	ds_read_b128 v[164:167], v229
	ds_write_b128 v231, v[12:15] offset:32768
	global_load_dwordx4 v[12:15], v[210:211], off
	v_mfma_f32_16x16x32_bf16 v[108:111], v[168:171], v[172:175], v[108:111]
	v_mfma_f32_16x16x32_bf16 v[104:107], v[176:179], v[172:175], v[104:107]
	v_mfma_f32_16x16x32_bf16 v[100:103], v[186:189], v[172:175], v[100:103]
	v_mfma_f32_16x16x32_bf16 v[96:99], v[194:197], v[172:175], v[96:99]
	ds_read_b128 v[172:175], v229 offset:2048
	ds_read_b128 v[202:205], v230 offset:18432
	ds_write_b128 v231, v[24:27] offset:36864
	v_lshl_add_u64 v[24:25], v[210:211], 0, s[20:21]
	global_load_dwordx4 v[24:27], v[24:25], off
	s_setprio 2
	v_mfma_f32_16x16x32_bf16 v[92:95], v[168:171], v[180:183], v[92:95]
	v_mfma_f32_16x16x32_bf16 v[88:91], v[176:179], v[180:183], v[88:91]
	v_mfma_f32_16x16x32_bf16 v[84:87], v[186:189], v[180:183], v[84:87]
	v_mfma_f32_16x16x32_bf16 v[80:83], v[194:197], v[180:183], v[80:83]
	ds_read_b128 v[180:183], v229 offset:4096
	ds_read_b128 v[206:209], v230 offset:20480
	ds_write_b128 v231, v[40:43] offset:40960
	v_lshl_add_u64 v[40:41], v[210:211], 0, s[22:23]
	global_load_dwordx4 v[40:43], v[40:41], off
	v_mfma_f32_16x16x32_bf16 v[76:79], v[168:171], v[190:193], v[76:79]
	v_mfma_f32_16x16x32_bf16 v[72:75], v[176:179], v[190:193], v[72:75]
	ds_read_b128 v[168:171], v229 offset:6144
	ds_read_b128 v[176:179], v230 offset:22528
	ds_write_b128 v231, v[48:51] offset:45056
	v_lshl_add_u64 v[48:49], v[210:211], 0, s[24:25]
	v_mfma_f32_16x16x32_bf16 v[68:71], v[186:189], v[190:193], v[68:71]
	global_load_dwordx4 v[48:51], v[48:49], off
	v_mfma_f32_16x16x32_bf16 v[64:67], v[194:197], v[190:193], v[64:67]
	s_waitcnt lgkmcnt(10)
	v_mfma_f32_16x16x32_bf16 v[124:127], v[198:201], v[164:167], v[124:127]
	ds_write_b128 v231, v[16:19] offset:49152
	global_load_dwordx4 v[16:19], v[226:227], off
	s_waitcnt lgkmcnt(8)
	v_mfma_f32_16x16x32_bf16 v[120:123], v[202:205], v[164:167], v[120:123]
	s_waitcnt lgkmcnt(5)
	v_mfma_f32_16x16x32_bf16 v[116:119], v[206:209], v[164:167], v[116:119]
	s_waitcnt lgkmcnt(2)
	v_mfma_f32_16x16x32_bf16 v[112:115], v[176:179], v[164:167], v[112:115]
	s_setprio 3
	v_mfma_f32_16x16x32_bf16 v[108:111], v[198:201], v[172:175], v[108:111]
	ds_write_b128 v231, v[28:31] offset:53248
	v_lshl_add_u64 v[28:29], v[226:227], 0, s[20:21]
	global_load_dwordx4 v[28:31], v[28:29], off
	v_mfma_f32_16x16x32_bf16 v[104:107], v[202:205], v[172:175], v[104:107]
	v_mfma_f32_16x16x32_bf16 v[100:103], v[206:209], v[172:175], v[100:103]
	v_mfma_f32_16x16x32_bf16 v[96:99], v[176:179], v[172:175], v[96:99]
	v_mfma_f32_16x16x32_bf16 v[92:95], v[198:201], v[180:183], v[92:95]
	ds_write_b128 v231, v[44:47] offset:57344
	v_lshl_add_u64 v[44:45], v[226:227], 0, s[22:23]
	global_load_dwordx4 v[44:47], v[44:45], off
	v_mfma_f32_16x16x32_bf16 v[88:91], v[202:205], v[180:183], v[88:91]
	v_mfma_f32_16x16x32_bf16 v[84:87], v[206:209], v[180:183], v[84:87]
	v_mfma_f32_16x16x32_bf16 v[80:83], v[176:179], v[180:183], v[80:83]
	v_mfma_f32_16x16x32_bf16 v[76:79], v[198:201], v[168:171], v[76:79]
	ds_write_b128 v231, v[52:55] offset:61440
	v_lshl_add_u64 v[52:53], v[226:227], 0, s[24:25]
	global_load_dwordx4 v[52:55], v[52:53], off
	v_mfma_f32_16x16x32_bf16 v[72:75], v[202:205], v[168:171], v[72:75]
	v_mfma_f32_16x16x32_bf16 v[68:71], v[206:209], v[168:171], v[68:71]
	v_mfma_f32_16x16x32_bf16 v[64:67], v[176:179], v[168:171], v[64:67]
	s_cmp_lt_u32 s2, 28
	s_cselect_b64 s[4:5], -1, 0
	s_and_b64 s[6:7], s[0:1], vcc
	v_lshl_add_u64 v[158:159], v[158:159], 0, s[34:35]
	v_cndmask_b32_e64 v164, v140, v136, s[6:7]
	v_cndmask_b32_e64 v165, v141, v137, s[6:7]
	v_cndmask_b32_e64 v159, v165, v159, s[4:5]
	v_cndmask_b32_e64 v158, v164, v158, s[4:5]
	v_lshl_add_u64 v[164:165], v[212:213], 0, s[36:37]
	v_cndmask_b32_e64 v166, v142, v138, s[6:7]
	v_cndmask_b32_e64 v167, v143, v139, s[6:7]
	s_setprio 0
	s_waitcnt lgkmcnt(0)
	s_barrier
; #define MFMA16(a, b, c) __builtin_amdgcn_mfma_f32_16x16x32_bf16((a), (b), (c), 0, 0, 0)
; DI void gld(u32x4v& r, const void* p) { asm volatile("global_load_dwordx4 %0, %1, off" : "=v"(r) : "v"(p) : "memory"); }
; #define WAIT_SET(N, a, b) asm volatile("s_waitcnt vmcnt(" #N ")" : "+v"(a[0]), "+v"(a[1]), "+v"(a[2]), "+v"(a[3]), "+v"(b[0]), "+v"(b[1]), "+v"(b[2]), "+v"(b[3]) :: "memory")
; DI void gemm_half(f32x4 (&acc)[4][4], const char* sa, const char* sb, int o0, int o1, u32x4v (&ra)[4], u32x4v (&rb)[4],
;                   char* stw, const bf16_t* Agn, const bf16_t* Bgn, int lda, int ldb) {
;   bf16x8 af0[4], bf0[4], af1[4], bf1[4];
; #pragma unroll
;   for (int i = 0; i < 4; ++i) { af0[i] = *(const bf16x8*)(sa + i * 16 * 128 + o0); bf0[i] = *(const bf16x8*)(sb + i * 16 * 128 + o0); }
;   __builtin_amdgcn_sched_barrier(0);
;   WAIT_SET(8, ra, rb);
; #pragma unroll
;   for (int g = 0; g < 8; ++g) {
; #pragma unroll
;     for (int ni = 0; ni < 4; ++ni) {
;       if (g < 4) acc[g][ni] = MFMA16(bf0[ni], af0[g], acc[g][ni]);
;       else acc[g - 4][ni] = MFMA16(bf1[ni], af1[g - 4], acc[g - 4][ni]);
;     }
;     if (g < 4) { af1[g] = *(const bf16x8*)(sa + g * 16 * 128 + o1); bf1[g] = *(const bf16x8*)(sb + g * 16 * 128 + o1);
;                  *(u32x4v*)(stw + g * 32 * 128) = ra[g]; gld(ra[g], Agn + (size_t)g * 32 * lda); }
;     else { *(u32x4v*)(stw + TILE_B + (g - 4) * 32 * 128) = rb[g - 4]; gld(rb[g - 4], Bgn + (size_t)(g - 4) * 32 * ldb); }
;     __builtin_amdgcn_sched_barrier(0);
;   }
; DI void gemm_kloop(f32x4 (&acc)[4][4], const bf16_t* Ag, const bf16_t* Bg, int lda, int ldb, int K, char* smem,
;                    u32x4v (&ra)[4], u32x4v (&rb)[4], u32x4v (&rc)[4], u32x4v (&rd)[4], bool pre,
;                    const bf16_t* Agn, const bf16_t* Bgn, bool hasnext) {
;     ...
;     const bf16_t* pa0 = kt + 4 < nk ? Ag + (size_t)(kt + 4) * 64 : ((last && hasnext) ? Agn : Alast);
;     const bf16_t* pb0 = kt + 4 < nk ? Bg + (size_t)(kt + 4) * 64 : ((last && hasnext) ? Bgn : Blast);
;     gemm_half(acc, sa0 + 2 * TILE_B, sb0 + 2 * TILE_B, o0, o1, ra, rb, st, pa0, pb0, lda, ldb);
;     __syncthreads();
;   }
;   if (!hasnext) { WAIT_SET(0, ra, rb); WAIT_SET(0, rc, rd); }
	v_cndmask_b32_e64 v211, v167, v165, s[4:5]
	v_cndmask_b32_e64 v210, v166, v164, s[4:5]
	ds_read_b128 v[164:167], v184 offset:32768
	ds_read_b128 v[168:171], v228 offset:49152
	ds_read_b128 v[172:175], v184 offset:34816
	ds_read_b128 v[176:179], v228 offset:51200
	ds_read_b128 v[180:183], v184 offset:36864
	ds_read_b128 v[186:189], v228 offset:53248
	ds_read_b128 v[190:193], v184 offset:38912
	ds_read_b128 v[194:197], v228 offset:55296
	s_waitcnt vmcnt(8)
	s_setprio 1
	s_waitcnt lgkmcnt(6)
	v_mfma_f32_16x16x32_bf16 v[124:127], v[168:171], v[164:167], v[124:127]
	s_waitcnt lgkmcnt(4)
	v_mfma_f32_16x16x32_bf16 v[120:123], v[176:179], v[164:167], v[120:123]
	s_waitcnt lgkmcnt(2)
	v_mfma_f32_16x16x32_bf16 v[116:119], v[186:189], v[164:167], v[116:119]
	s_waitcnt lgkmcnt(0)
	v_mfma_f32_16x16x32_bf16 v[112:115], v[194:197], v[164:167], v[112:115]
	ds_read_b128 v[164:167], v229 offset:32768
	ds_read_b128 v[198:201], v230 offset:49152
	ds_write_b128 v231, v[0:3]
	global_load_dwordx4 v[0:3], v[158:159], off
	v_mfma_f32_16x16x32_bf16 v[108:111], v[168:171], v[172:175], v[108:111]
	v_mfma_f32_16x16x32_bf16 v[104:107], v[176:179], v[172:175], v[104:107]
	v_mfma_f32_16x16x32_bf16 v[100:103], v[186:189], v[172:175], v[100:103]
	v_mfma_f32_16x16x32_bf16 v[96:99], v[194:197], v[172:175], v[96:99]
	ds_read_b128 v[172:175], v229 offset:34816
	ds_read_b128 v[202:205], v230 offset:51200
	ds_write_b128 v231, v[8:11] offset:4096
	v_lshl_add_u64 v[8:9], v[158:159], 0, s[20:21]
	global_load_dwordx4 v[8:11], v[8:9], off
	s_setprio 2
	v_mfma_f32_16x16x32_bf16 v[92:95], v[168:171], v[180:183], v[92:95]
	v_mfma_f32_16x16x32_bf16 v[88:91], v[176:179], v[180:183], v[88:91]
	v_mfma_f32_16x16x32_bf16 v[84:87], v[186:189], v[180:183], v[84:87]
	v_mfma_f32_16x16x32_bf16 v[80:83], v[194:197], v[180:183], v[80:83]
	ds_read_b128 v[180:183], v229 offset:36864
	ds_read_b128 v[206:209], v230 offset:53248
	ds_write_b128 v231, v[32:35] offset:8192
	v_lshl_add_u64 v[32:33], v[158:159], 0, s[22:23]
	global_load_dwordx4 v[32:35], v[32:33], off
	v_mfma_f32_16x16x32_bf16 v[76:79], v[168:171], v[190:193], v[76:79]
	v_mfma_f32_16x16x32_bf16 v[72:75], v[176:179], v[190:193], v[72:75]
	ds_read_b128 v[168:171], v229 offset:38912
	ds_read_b128 v[176:179], v230 offset:55296
	ds_write_b128 v231, v[56:59] offset:12288
	v_lshl_add_u64 v[56:57], v[158:159], 0, s[24:25]
	v_mfma_f32_16x16x32_bf16 v[68:71], v[186:189], v[190:193], v[68:71]
	global_load_dwordx4 v[56:59], v[56:57], off
	v_mfma_f32_16x16x32_bf16 v[64:67], v[194:197], v[190:193], v[64:67]
	s_waitcnt lgkmcnt(10)
	v_mfma_f32_16x16x32_bf16 v[124:127], v[198:201], v[164:167], v[124:127]
	ds_write_b128 v231, v[4:7] offset:16384
	global_load_dwordx4 v[4:7], v[210:211], off
	s_waitcnt lgkmcnt(8)
	v_mfma_f32_16x16x32_bf16 v[120:123], v[202:205], v[164:167], v[120:123]
	s_waitcnt lgkmcnt(5)
	v_mfma_f32_16x16x32_bf16 v[116:119], v[206:209], v[164:167], v[116:119]
	s_waitcnt lgkmcnt(2)
	v_mfma_f32_16x16x32_bf16 v[112:115], v[176:179], v[164:167], v[112:115]
	s_setprio 3
	v_mfma_f32_16x16x32_bf16 v[108:111], v[198:201], v[172:175], v[108:111]
	ds_write_b128 v231, v[20:23] offset:20480
	v_lshl_add_u64 v[20:21], v[210:211], 0, s[20:21]
	global_load_dwordx4 v[20:23], v[20:21], off
	v_mfma_f32_16x16x32_bf16 v[104:107], v[202:205], v[172:175], v[104:107]
	v_mfma_f32_16x16x32_bf16 v[100:103], v[206:209], v[172:175], v[100:103]
	v_mfma_f32_16x16x32_bf16 v[96:99], v[176:179], v[172:175], v[96:99]
	v_mfma_f32_16x16x32_bf16 v[92:95], v[198:201], v[180:183], v[92:95]
	ds_write_b128 v231, v[36:39] offset:24576
	v_lshl_add_u64 v[36:37], v[210:211], 0, s[22:23]
	global_load_dwordx4 v[36:39], v[36:37], off
	v_mfma_f32_16x16x32_bf16 v[88:91], v[202:205], v[180:183], v[88:91]
	v_mfma_f32_16x16x32_bf16 v[84:87], v[206:209], v[180:183], v[84:87]
	v_mfma_f32_16x16x32_bf16 v[80:83], v[176:179], v[180:183], v[80:83]
	v_mfma_f32_16x16x32_bf16 v[76:79], v[198:201], v[168:171], v[76:79]
	ds_write_b128 v231, v[60:63] offset:28672
	v_lshl_add_u64 v[60:61], v[210:211], 0, s[24:25]
	global_load_dwordx4 v[60:63], v[60:61], off
	v_mfma_f32_16x16x32_bf16 v[72:75], v[202:205], v[168:171], v[72:75]
	v_mfma_f32_16x16x32_bf16 v[68:71], v[206:209], v[168:171], v[68:71]
	v_mfma_f32_16x16x32_bf16 v[64:67], v[176:179], v[168:171], v[64:67]
	v_lshl_add_u64 v[148:149], v[148:149], 0, s[28:29]
	v_lshl_add_u64 v[150:151], v[150:151], 0, s[28:29]
	s_and_b64 vcc, exec, vcc
	s_setprio 0
	s_waitcnt lgkmcnt(0)
	s_barrier
	s_cbranch_vccz .LBB0_1632
	s_and_b64 vcc, exec, s[8:9]
	s_cbranch_vccz .LBB0_1635
	s_waitcnt vmcnt(0)
	s_waitcnt vmcnt(0)

; #define MFMA16(a, b, c) __builtin_amdgcn_mfma_f32_16x16x32_bf16((a), (b), (c), 0, 0, 0)
; DI void gld(u32x4v& r, const void* p) { asm volatile("global_load_dwordx4 %0, %1, off" : "=v"(r) : "v"(p) : "memory"); }
; #define WAIT_SET(N, a, b) asm volatile("s_waitcnt vmcnt(" #N ")" : "+v"(a[0]), "+v"(a[1]), "+v"(a[2]), "+v"(a[3]), "+v"(b[0]), "+v"(b[1]), "+v"(b[2]), "+v"(b[3]) :: "memory")
; DI void gemm_half(f32x4 (&acc)[4][4], const char* sa, const char* sb, int o0, int o1, u32x4v (&ra)[4], u32x4v (&rb)[4],
;                   char* stw, const bf16_t* Agn, const bf16_t* Bgn, int lda, int ldb) {
;   bf16x8 af0[4], bf0[4], af1[4], bf1[4];
; #pragma unroll
;   for (int i = 0; i < 4; ++i) { af0[i] = *(const bf16x8*)(sa + i * 16 * 128 + o0); bf0[i] = *(const bf16x8*)(sb + i * 16 * 128 + o0); }
;   __builtin_amdgcn_sched_barrier(0);
;   WAIT_SET(8, ra, rb);
; #pragma unroll
;   for (int g = 0; g < 8; ++g) {
; #pragma unroll
;     for (int ni = 0; ni < 4; ++ni) {
;       if (g < 4) acc[g][ni] = MFMA16(bf0[ni], af0[g], acc[g][ni]);
;       else acc[g - 4][ni] = MFMA16(bf1[ni], af1[g - 4], acc[g - 4][ni]);
;     }
;     if (g < 4) { af1[g] = *(const bf16x8*)(sa + g * 16 * 128 + o1); bf1[g] = *(const bf16x8*)(sb + g * 16 * 128 + o1);
;                  *(u32x4v*)(stw + g * 32 * 128) = ra[g]; gld(ra[g], Agn + (size_t)g * 32 * lda); }
;     else { *(u32x4v*)(stw + TILE_B + (g - 4) * 32 * 128) = rb[g - 4]; gld(rb[g - 4], Bgn + (size_t)(g - 4) * 32 * ldb); }
;     __builtin_amdgcn_sched_barrier(0);
;   }
; DI void gemm_kloop(f32x4 (&acc)[4][4], const bf16_t* Ag, const bf16_t* Bg, int lda, int ldb, int K, char* smem,
;                    u32x4v (&ra)[4], u32x4v (&rb)[4], u32x4v (&rc)[4], u32x4v (&rd)[4], bool pre,
;                    const bf16_t* Agn, const bf16_t* Bgn, bool hasnext) {
;     ...
;   for (int kt = 0; kt < nk; kt += 2) {
;     const bool last = kt + 2 >= nk;
;     const bf16_t* pa1 = last ? (hasnext ? Agn + 64 : Alast) : Ag + (size_t)(kt + 3) * 64;
;     const bf16_t* pb1 = last ? (hasnext ? Bgn + 64 : Blast) : Bg + (size_t)(kt + 3) * 64;
;     gemm_half(acc, sa0, sb0, o0, o1, rc, rd, st + 2 * TILE_B, pa1, pb1, lda, ldb);
;     __syncthreads();
.LBB0_2033:
	s_add_i32 s18, s18, 2
	s_cmpk_gt_u32 s18, 0x55
	v_lshl_add_u64 v[182:183], v[146:147], 0, v[184:185]
	s_mov_b64 s[0:1], 0x11800180
	s_cselect_b64 vcc, -1, 0
	v_lshl_add_u64 v[158:159], v[182:183], 0, s[0:1]
	v_lshl_add_u64 v[208:209], v[148:149], 0, v[184:185]
	s_mov_b64 s[0:1], 0x2c00180
	v_cndmask_b32_e32 v207, v159, v133, vcc
	v_cndmask_b32_e32 v206, v158, v142, vcc
	v_lshl_add_u64 v[158:159], v[208:209], 0, s[0:1]
	v_add_u32_e32 v212, v154, v156
	v_add_u32_e32 v213, v155, v156
	v_cndmask_b32_e32 v211, v159, v143, vcc
	v_cndmask_b32_e32 v210, v158, v144, vcc
	ds_read_b128 v[158:161], v212
	ds_read_b128 v[162:165], v213 offset:16384
	ds_read_b128 v[166:169], v212 offset:2048
	ds_read_b128 v[170:173], v213 offset:18432
	ds_read_b128 v[174:177], v212 offset:4096
	ds_read_b128 v[178:181], v213 offset:20480
	ds_read_b128 v[186:189], v212 offset:6144
	ds_read_b128 v[190:193], v213 offset:22528
	s_waitcnt vmcnt(8)
	s_setprio 1
	v_add_u32_e32 v226, v154, v157
	v_add_u32_e32 v227, v155, v157
	v_add_u32_e32 v228, v152, v153
	s_waitcnt lgkmcnt(6)
	v_mfma_f32_16x16x32_bf16 v[124:127], v[162:165], v[158:161], v[124:127]
	ds_read_b128 v[194:197], v227 offset:16384
	s_waitcnt lgkmcnt(5)
	v_mfma_f32_16x16x32_bf16 v[120:123], v[170:173], v[158:161], v[120:123]
	s_waitcnt lgkmcnt(3)
	v_mfma_f32_16x16x32_bf16 v[116:119], v[178:181], v[158:161], v[116:119]
	s_waitcnt lgkmcnt(1)
	v_mfma_f32_16x16x32_bf16 v[112:115], v[190:193], v[158:161], v[112:115]
	ds_read_b128 v[158:161], v226
	ds_write_b128 v228, v[8:11] offset:32768
	global_load_dwordx4 v[8:11], v[206:207], off
	v_mfma_f32_16x16x32_bf16 v[108:111], v[162:165], v[166:169], v[108:111]
	v_mfma_f32_16x16x32_bf16 v[104:107], v[170:173], v[166:169], v[104:107]
	v_mfma_f32_16x16x32_bf16 v[100:103], v[178:181], v[166:169], v[100:103]
	v_mfma_f32_16x16x32_bf16 v[96:99], v[190:193], v[166:169], v[96:99]
	ds_read_b128 v[166:169], v226 offset:2048
	ds_read_b128 v[198:201], v227 offset:18432
	ds_write_b128 v228, v[24:27] offset:36864
	v_lshl_add_u64 v[24:25], v[206:207], 0, s[22:23]
	global_load_dwordx4 v[24:27], v[24:25], off
	s_setprio 2
	v_mfma_f32_16x16x32_bf16 v[92:95], v[162:165], v[174:177], v[92:95]
	v_mfma_f32_16x16x32_bf16 v[88:91], v[170:173], v[174:177], v[88:91]
	v_mfma_f32_16x16x32_bf16 v[84:87], v[178:181], v[174:177], v[84:87]
	v_mfma_f32_16x16x32_bf16 v[80:83], v[190:193], v[174:177], v[80:83]
	ds_read_b128 v[174:177], v226 offset:4096
	ds_read_b128 v[202:205], v227 offset:20480
	ds_write_b128 v228, v[40:43] offset:40960
	v_lshl_add_u64 v[40:41], v[206:207], 0, s[26:27]
	global_load_dwordx4 v[40:43], v[40:41], off
	v_mfma_f32_16x16x32_bf16 v[76:79], v[162:165], v[186:189], v[76:79]
	v_mfma_f32_16x16x32_bf16 v[72:75], v[170:173], v[186:189], v[72:75]
	ds_read_b128 v[162:165], v226 offset:6144
	ds_read_b128 v[170:173], v227 offset:22528
	ds_write_b128 v228, v[48:51] offset:45056
	v_lshl_add_u64 v[48:49], v[206:207], 0, s[20:21]
	v_mfma_f32_16x16x32_bf16 v[68:71], v[178:181], v[186:189], v[68:71]
	global_load_dwordx4 v[48:51], v[48:49], off
	v_mfma_f32_16x16x32_bf16 v[64:67], v[190:193], v[186:189], v[64:67]
	s_waitcnt lgkmcnt(10)
	v_mfma_f32_16x16x32_bf16 v[124:127], v[194:197], v[158:161], v[124:127]
	ds_write_b128 v228, v[12:15] offset:49152
	global_load_dwordx4 v[12:15], v[210:211], off
	s_waitcnt lgkmcnt(8)
	v_mfma_f32_16x16x32_bf16 v[120:123], v[198:201], v[158:161], v[120:123]
	s_waitcnt lgkmcnt(5)
	v_mfma_f32_16x16x32_bf16 v[116:119], v[202:205], v[158:161], v[116:119]
	s_waitcnt lgkmcnt(2)
	v_mfma_f32_16x16x32_bf16 v[112:115], v[170:173], v[158:161], v[112:115]
	s_setprio 3
	v_mfma_f32_16x16x32_bf16 v[108:111], v[194:197], v[166:169], v[108:111]
	ds_write_b128 v228, v[28:31] offset:53248
	v_lshl_add_u64 v[28:29], v[210:211], 0, s[22:23]
	global_load_dwordx4 v[28:31], v[28:29], off
	v_mfma_f32_16x16x32_bf16 v[104:107], v[198:201], v[166:169], v[104:107]
	v_mfma_f32_16x16x32_bf16 v[100:103], v[202:205], v[166:169], v[100:103]
	v_mfma_f32_16x16x32_bf16 v[96:99], v[170:173], v[166:169], v[96:99]
	v_mfma_f32_16x16x32_bf16 v[92:95], v[194:197], v[174:177], v[92:95]
	ds_write_b128 v228, v[44:47] offset:57344
	v_lshl_add_u64 v[44:45], v[210:211], 0, s[26:27]
	global_load_dwordx4 v[44:47], v[44:45], off
	v_mfma_f32_16x16x32_bf16 v[88:91], v[198:201], v[174:177], v[88:91]
	v_mfma_f32_16x16x32_bf16 v[84:87], v[202:205], v[174:177], v[84:87]
	v_mfma_f32_16x16x32_bf16 v[80:83], v[170:173], v[174:177], v[80:83]
	v_mfma_f32_16x16x32_bf16 v[76:79], v[194:197], v[162:165], v[76:79]
	ds_write_b128 v228, v[52:55] offset:61440
	v_lshl_add_u64 v[52:53], v[210:211], 0, s[20:21]
	global_load_dwordx4 v[52:55], v[52:53], off
	v_mfma_f32_16x16x32_bf16 v[72:75], v[198:201], v[162:165], v[72:75]
	v_mfma_f32_16x16x32_bf16 v[68:71], v[202:205], v[162:165], v[68:71]
	v_mfma_f32_16x16x32_bf16 v[64:67], v[170:173], v[162:165], v[64:67]
	s_cmpk_lt_u32 s18, 0x54
	s_mov_b64 s[4:5], 0x11800200
	s_cselect_b64 s[0:1], -1, 0
	v_lshl_add_u64 v[158:159], v[182:183], 0, s[4:5]
	s_and_b64 s[4:5], s[12:13], vcc
	v_cndmask_b32_e64 v160, v138, v134, s[4:5]
	v_cndmask_b32_e64 v161, v139, v135, s[4:5]
	s_mov_b64 s[20:21], 0x2c00200
	v_cndmask_b32_e64 v183, v161, v159, s[0:1]
	v_cndmask_b32_e64 v182, v160, v158, s[0:1]
	v_lshl_add_u64 v[158:159], v[208:209], 0, s[20:21]
	v_cndmask_b32_e64 v160, v140, v136, s[4:5]
	v_cndmask_b32_e64 v161, v141, v137, s[4:5]
	s_setprio 0
	s_waitcnt lgkmcnt(0)
	s_barrier
; #define MFMA16(a, b, c) __builtin_amdgcn_mfma_f32_16x16x32_bf16((a), (b), (c), 0, 0, 0)
; DI void gld(u32x4v& r, const void* p) { asm volatile("global_load_dwordx4 %0, %1, off" : "=v"(r) : "v"(p) : "memory"); }
; #define WAIT_SET(N, a, b) asm volatile("s_waitcnt vmcnt(" #N ")" : "+v"(a[0]), "+v"(a[1]), "+v"(a[2]), "+v"(a[3]), "+v"(b[0]), "+v"(b[1]), "+v"(b[2]), "+v"(b[3]) :: "memory")
; DI void gemm_half(f32x4 (&acc)[4][4], const char* sa, const char* sb, int o0, int o1, u32x4v (&ra)[4], u32x4v (&rb)[4],
;                   char* stw, const bf16_t* Agn, const bf16_t* Bgn, int lda, int ldb) {
;   bf16x8 af0[4], bf0[4], af1[4], bf1[4];
; #pragma unroll
;   for (int i = 0; i < 4; ++i) { af0[i] = *(const bf16x8*)(sa + i * 16 * 128 + o0); bf0[i] = *(const bf16x8*)(sb + i * 16 * 128 + o0); }
;   __builtin_amdgcn_sched_barrier(0);
;   WAIT_SET(8, ra, rb);
; #pragma unroll
;   for (int g = 0; g < 8; ++g) {
; #pragma unroll
;     for (int ni = 0; ni < 4; ++ni) {
;       if (g < 4) acc[g][ni] = MFMA16(bf0[ni], af0[g], acc[g][ni]);
;       else acc[g - 4][ni] = MFMA16(bf1[ni], af1[g - 4], acc[g - 4][ni]);
;     }
;     if (g < 4) { af1[g] = *(const bf16x8*)(sa + g * 16 * 128 + o1); bf1[g] = *(const bf16x8*)(sb + g * 16 * 128 + o1);
;                  *(u32x4v*)(stw + g * 32 * 128) = ra[g]; gld(ra[g], Agn + (size_t)g * 32 * lda); }
;     else { *(u32x4v*)(stw + TILE_B + (g - 4) * 32 * 128) = rb[g - 4]; gld(rb[g - 4], Bgn + (size_t)(g - 4) * 32 * ldb); }
;     __builtin_amdgcn_sched_barrier(0);
;   }
; DI void gemm_kloop(f32x4 (&acc)[4][4], const bf16_t* Ag, const bf16_t* Bg, int lda, int ldb, int K, char* smem,
;                    u32x4v (&ra)[4], u32x4v (&rb)[4], u32x4v (&rc)[4], u32x4v (&rd)[4], bool pre,
;                    const bf16_t* Agn, const bf16_t* Bgn, bool hasnext) {
;     ...
;     const bf16_t* pa0 = kt + 4 < nk ? Ag + (size_t)(kt + 4) * 64 : ((last && hasnext) ? Agn : Alast);
;     const bf16_t* pb0 = kt + 4 < nk ? Bg + (size_t)(kt + 4) * 64 : ((last && hasnext) ? Bgn : Blast);
;     gemm_half(acc, sa0 + 2 * TILE_B, sb0 + 2 * TILE_B, o0, o1, ra, rb, st, pa0, pb0, lda, ldb);
;     __syncthreads();
;   }
;   if (!hasnext) { WAIT_SET(0, ra, rb); WAIT_SET(0, rc, rd); }
	v_cndmask_b32_e64 v207, v161, v159, s[0:1]
	v_cndmask_b32_e64 v206, v160, v158, s[0:1]
	ds_read_b128 v[158:161], v212 offset:32768
	ds_read_b128 v[162:165], v213 offset:49152
	ds_read_b128 v[166:169], v212 offset:34816
	ds_read_b128 v[170:173], v213 offset:51200
	ds_read_b128 v[174:177], v212 offset:36864
	ds_read_b128 v[178:181], v213 offset:53248
	ds_read_b128 v[186:189], v212 offset:38912
	ds_read_b128 v[190:193], v213 offset:55296
	s_mov_b64 s[20:21], 0x108000
	s_waitcnt vmcnt(8)
	s_setprio 1
	s_waitcnt lgkmcnt(6)
	v_mfma_f32_16x16x32_bf16 v[124:127], v[162:165], v[158:161], v[124:127]
	s_waitcnt lgkmcnt(4)
	v_mfma_f32_16x16x32_bf16 v[120:123], v[170:173], v[158:161], v[120:123]
	s_waitcnt lgkmcnt(2)
	v_mfma_f32_16x16x32_bf16 v[116:119], v[178:181], v[158:161], v[116:119]
	s_waitcnt lgkmcnt(0)
	v_mfma_f32_16x16x32_bf16 v[112:115], v[190:193], v[158:161], v[112:115]
	ds_read_b128 v[158:161], v226 offset:32768
	ds_read_b128 v[194:197], v227 offset:49152
	ds_write_b128 v228, v[0:3]
	global_load_dwordx4 v[0:3], v[182:183], off
	v_mfma_f32_16x16x32_bf16 v[108:111], v[162:165], v[166:169], v[108:111]
	v_mfma_f32_16x16x32_bf16 v[104:107], v[170:173], v[166:169], v[104:107]
	v_mfma_f32_16x16x32_bf16 v[100:103], v[178:181], v[166:169], v[100:103]
	v_mfma_f32_16x16x32_bf16 v[96:99], v[190:193], v[166:169], v[96:99]
	ds_read_b128 v[166:169], v226 offset:34816
	ds_read_b128 v[198:201], v227 offset:51200
	ds_write_b128 v228, v[16:19] offset:4096
	v_lshl_add_u64 v[16:17], v[182:183], 0, s[22:23]
	global_load_dwordx4 v[16:19], v[16:17], off
	s_setprio 2
	v_mfma_f32_16x16x32_bf16 v[92:95], v[162:165], v[174:177], v[92:95]
	v_mfma_f32_16x16x32_bf16 v[88:91], v[170:173], v[174:177], v[88:91]
	v_mfma_f32_16x16x32_bf16 v[84:87], v[178:181], v[174:177], v[84:87]
	v_mfma_f32_16x16x32_bf16 v[80:83], v[190:193], v[174:177], v[80:83]
	ds_read_b128 v[174:177], v226 offset:36864
	ds_read_b128 v[202:205], v227 offset:53248
	ds_write_b128 v228, v[32:35] offset:8192
	v_lshl_add_u64 v[32:33], v[182:183], 0, s[26:27]
	global_load_dwordx4 v[32:35], v[32:33], off
	v_mfma_f32_16x16x32_bf16 v[76:79], v[162:165], v[186:189], v[76:79]
	v_mfma_f32_16x16x32_bf16 v[72:75], v[170:173], v[186:189], v[72:75]
	ds_read_b128 v[162:165], v226 offset:38912
	ds_read_b128 v[170:173], v227 offset:55296
	ds_write_b128 v228, v[56:59] offset:12288
	v_lshl_add_u64 v[56:57], v[182:183], 0, s[20:21]
	v_mfma_f32_16x16x32_bf16 v[68:71], v[178:181], v[186:189], v[68:71]
	global_load_dwordx4 v[56:59], v[56:57], off
	v_mfma_f32_16x16x32_bf16 v[64:67], v[190:193], v[186:189], v[64:67]
	s_waitcnt lgkmcnt(10)
	v_mfma_f32_16x16x32_bf16 v[124:127], v[194:197], v[158:161], v[124:127]
	ds_write_b128 v228, v[4:7] offset:16384
	global_load_dwordx4 v[4:7], v[206:207], off
	s_waitcnt lgkmcnt(8)
	v_mfma_f32_16x16x32_bf16 v[120:123], v[198:201], v[158:161], v[120:123]
	s_waitcnt lgkmcnt(5)
	v_mfma_f32_16x16x32_bf16 v[116:119], v[202:205], v[158:161], v[116:119]
	s_waitcnt lgkmcnt(2)
	v_mfma_f32_16x16x32_bf16 v[112:115], v[170:173], v[158:161], v[112:115]
	s_setprio 3
	v_mfma_f32_16x16x32_bf16 v[108:111], v[194:197], v[166:169], v[108:111]
	ds_write_b128 v228, v[20:23] offset:20480
	v_lshl_add_u64 v[20:21], v[206:207], 0, s[22:23]
	global_load_dwordx4 v[20:23], v[20:21], off
	v_mfma_f32_16x16x32_bf16 v[104:107], v[198:201], v[166:169], v[104:107]
	v_mfma_f32_16x16x32_bf16 v[100:103], v[202:205], v[166:169], v[100:103]
	v_mfma_f32_16x16x32_bf16 v[96:99], v[170:173], v[166:169], v[96:99]
	v_mfma_f32_16x16x32_bf16 v[92:95], v[194:197], v[174:177], v[92:95]
	ds_write_b128 v228, v[36:39] offset:24576
	v_lshl_add_u64 v[36:37], v[206:207], 0, s[26:27]
	global_load_dwordx4 v[36:39], v[36:37], off
	v_mfma_f32_16x16x32_bf16 v[88:91], v[198:201], v[174:177], v[88:91]
	v_mfma_f32_16x16x32_bf16 v[84:87], v[202:205], v[174:177], v[84:87]
	v_mfma_f32_16x16x32_bf16 v[80:83], v[170:173], v[174:177], v[80:83]
	v_mfma_f32_16x16x32_bf16 v[76:79], v[194:197], v[162:165], v[76:79]
	ds_write_b128 v228, v[60:63] offset:28672
	v_lshl_add_u64 v[60:61], v[206:207], 0, s[20:21]
	global_load_dwordx4 v[60:63], v[60:61], off
	v_mfma_f32_16x16x32_bf16 v[72:75], v[198:201], v[162:165], v[72:75]
	v_mfma_f32_16x16x32_bf16 v[68:71], v[202:205], v[162:165], v[68:71]
	v_mfma_f32_16x16x32_bf16 v[64:67], v[170:173], v[162:165], v[64:67]
	v_lshl_add_u64 v[146:147], v[146:147], 0, s[28:29]
	v_lshl_add_u64 v[148:149], v[148:149], 0, s[28:29]
	s_and_b64 vcc, exec, vcc
	s_setprio 0
	s_waitcnt lgkmcnt(0)
	s_barrier
	s_cbranch_vccz .LBB0_2033
	s_and_b64 vcc, exec, s[10:11]
	s_cbranch_vccz .LBB0_2022
	s_waitcnt vmcnt(0)
	s_waitcnt vmcnt(0)
	s_branch .LBB0_2022

; #define MFMA16(a, b, c) __builtin_amdgcn_mfma_f32_16x16x32_bf16((a), (b), (c), 0, 0, 0)
; DI void gld(u32x4v& r, const void* p) { asm volatile("global_load_dwordx4 %0, %1, off" : "=v"(r) : "v"(p) : "memory"); }
; #define WAIT_SET(N, a, b) asm volatile("s_waitcnt vmcnt(" #N ")" : "+v"(a[0]), "+v"(a[1]), "+v"(a[2]), "+v"(a[3]), "+v"(b[0]), "+v"(b[1]), "+v"(b[2]), "+v"(b[3]) :: "memory")
; DI void gemm_half(f32x4 (&acc)[4][4], const char* sa, const char* sb, int o0, int o1, u32x4v (&ra)[4], u32x4v (&rb)[4],
;                   char* stw, const bf16_t* Agn, const bf16_t* Bgn, int lda, int ldb) {
;   bf16x8 af0[4], bf0[4], af1[4], bf1[4];
; #pragma unroll
;   for (int i = 0; i < 4; ++i) { af0[i] = *(const bf16x8*)(sa + i * 16 * 128 + o0); bf0[i] = *(const bf16x8*)(sb + i * 16 * 128 + o0); }
;   __builtin_amdgcn_sched_barrier(0);
;   WAIT_SET(8, ra, rb);
; #pragma unroll
;   for (int g = 0; g < 8; ++g) {
; #pragma unroll
;     for (int ni = 0; ni < 4; ++ni) {
;       if (g < 4) acc[g][ni] = MFMA16(bf0[ni], af0[g], acc[g][ni]);
;       else acc[g - 4][ni] = MFMA16(bf1[ni], af1[g - 4], acc[g - 4][ni]);
;     }
;     if (g < 4) { af1[g] = *(const bf16x8*)(sa + g * 16 * 128 + o1); bf1[g] = *(const bf16x8*)(sb + g * 16 * 128 + o1);
;                  *(u32x4v*)(stw + g * 32 * 128) = ra[g]; gld(ra[g], Agn + (size_t)g * 32 * lda); }
;     else { *(u32x4v*)(stw + TILE_B + (g - 4) * 32 * 128) = rb[g - 4]; gld(rb[g - 4], Bgn + (size_t)(g - 4) * 32 * ldb); }
;     __builtin_amdgcn_sched_barrier(0);
;   }
; DI void gemm_kloop(f32x4 (&acc)[4][4], const bf16_t* Ag, const bf16_t* Bg, int lda, int ldb, int K, char* smem,
;                    u32x4v (&ra)[4], u32x4v (&rb)[4], u32x4v (&rc)[4], u32x4v (&rd)[4], bool pre,
;                    const bf16_t* Agn, const bf16_t* Bgn, bool hasnext) {
;     ...
;   for (int kt = 0; kt < nk; kt += 2) {
;     const bool last = kt + 2 >= nk;
;     const bf16_t* pa1 = last ? (hasnext ? Agn + 64 : Alast) : Ag + (size_t)(kt + 3) * 64;
;     const bf16_t* pb1 = last ? (hasnext ? Bgn + 64 : Blast) : Bg + (size_t)(kt + 3) * 64;
;     gemm_half(acc, sa0, sb0, o0, o1, rc, rd, st + 2 * TILE_B, pa1, pb1, lda, ldb);
;     __syncthreads();
.LBB0_2052:
	s_add_i32 s13, s13, 2
	s_cmp_gt_u32 s13, 29
	v_lshl_add_u64 v[206:207], v[146:147], 0, v[132:133]
	s_cselect_b64 vcc, -1, 0
	v_lshl_add_u64 v[160:161], v[206:207], 0, s[26:27]
	v_lshl_add_u64 v[210:211], v[148:149], 0, v[132:133]
	v_cndmask_b32_e32 v209, v161, v143, vcc
	v_cndmask_b32_e32 v208, v160, v142, vcc
	v_lshl_add_u64 v[160:161], v[210:211], 0, s[28:29]
	v_add_u32_e32 v159, v155, v157
	v_add_u32_e32 v226, v156, v157
	v_cndmask_b32_e32 v213, v161, v145, vcc
	v_cndmask_b32_e32 v212, v160, v144, vcc
	ds_read_b128 v[160:163], v159
	ds_read_b128 v[164:167], v226 offset:16384
	ds_read_b128 v[168:171], v159 offset:2048
	ds_read_b128 v[172:175], v226 offset:18432
	ds_read_b128 v[176:179], v159 offset:4096
	ds_read_b128 v[180:183], v226 offset:20480
	ds_read_b128 v[186:189], v159 offset:6144
	ds_read_b128 v[190:193], v226 offset:22528
	s_waitcnt vmcnt(8)
	s_setprio 1
	v_add_u32_e32 v227, v155, v158
	v_add_u32_e32 v228, v156, v158
	v_add_u32_e32 v229, v153, v154
	s_waitcnt lgkmcnt(6)
	v_mfma_f32_16x16x32_bf16 v[124:127], v[164:167], v[160:163], v[124:127]
	ds_read_b128 v[194:197], v228 offset:16384
	s_waitcnt lgkmcnt(5)
	v_mfma_f32_16x16x32_bf16 v[116:119], v[172:175], v[160:163], v[116:119]
	s_waitcnt lgkmcnt(3)
	v_mfma_f32_16x16x32_bf16 v[120:123], v[180:183], v[160:163], v[120:123]
	s_waitcnt lgkmcnt(1)
	v_mfma_f32_16x16x32_bf16 v[112:115], v[190:193], v[160:163], v[112:115]
	ds_read_b128 v[160:163], v227
	ds_write_b128 v229, v[8:11] offset:32768
	global_load_dwordx4 v[8:11], v[208:209], off
	v_mfma_f32_16x16x32_bf16 v[108:111], v[164:167], v[168:171], v[108:111]
	v_mfma_f32_16x16x32_bf16 v[100:103], v[172:175], v[168:171], v[100:103]
	v_mfma_f32_16x16x32_bf16 v[104:107], v[180:183], v[168:171], v[104:107]
	v_mfma_f32_16x16x32_bf16 v[96:99], v[190:193], v[168:171], v[96:99]
	ds_read_b128 v[168:171], v227 offset:2048
	ds_read_b128 v[198:201], v228 offset:18432
	ds_write_b128 v229, v[24:27] offset:36864
	v_lshl_add_u64 v[24:25], v[208:209], 0, s[16:17]
	global_load_dwordx4 v[24:27], v[24:25], off
	s_setprio 2
	v_mfma_f32_16x16x32_bf16 v[92:95], v[164:167], v[176:179], v[92:95]
	v_mfma_f32_16x16x32_bf16 v[84:87], v[172:175], v[176:179], v[84:87]
	v_mfma_f32_16x16x32_bf16 v[88:91], v[180:183], v[176:179], v[88:91]
	v_mfma_f32_16x16x32_bf16 v[80:83], v[190:193], v[176:179], v[80:83]
	ds_read_b128 v[176:179], v227 offset:4096
	ds_read_b128 v[202:205], v228 offset:20480
	ds_write_b128 v229, v[40:43] offset:40960
	v_lshl_add_u64 v[40:41], v[208:209], 0, s[18:19]
	global_load_dwordx4 v[40:43], v[40:41], off
	v_mfma_f32_16x16x32_bf16 v[76:79], v[164:167], v[186:189], v[76:79]
	v_mfma_f32_16x16x32_bf16 v[68:71], v[172:175], v[186:189], v[68:71]
	ds_read_b128 v[164:167], v227 offset:6144
	ds_read_b128 v[172:175], v228 offset:22528
	ds_write_b128 v229, v[48:51] offset:45056
	v_lshl_add_u64 v[48:49], v[208:209], 0, s[20:21]
	v_mfma_f32_16x16x32_bf16 v[72:75], v[180:183], v[186:189], v[72:75]
	global_load_dwordx4 v[48:51], v[48:49], off
	v_mfma_f32_16x16x32_bf16 v[64:67], v[190:193], v[186:189], v[64:67]
	s_waitcnt lgkmcnt(10)
	v_mfma_f32_16x16x32_bf16 v[124:127], v[194:197], v[160:163], v[124:127]
	ds_write_b128 v229, v[12:15] offset:49152
	global_load_dwordx4 v[12:15], v[212:213], off
	s_waitcnt lgkmcnt(8)
	v_mfma_f32_16x16x32_bf16 v[116:119], v[198:201], v[160:163], v[116:119]
	s_waitcnt lgkmcnt(5)
	v_mfma_f32_16x16x32_bf16 v[120:123], v[202:205], v[160:163], v[120:123]
	s_waitcnt lgkmcnt(2)
	v_mfma_f32_16x16x32_bf16 v[112:115], v[172:175], v[160:163], v[112:115]
	s_setprio 3
	v_mfma_f32_16x16x32_bf16 v[108:111], v[194:197], v[168:171], v[108:111]
	ds_write_b128 v229, v[28:31] offset:53248
	v_lshl_add_u64 v[28:29], v[212:213], 0, s[16:17]
	global_load_dwordx4 v[28:31], v[28:29], off
	v_mfma_f32_16x16x32_bf16 v[100:103], v[198:201], v[168:171], v[100:103]
	v_mfma_f32_16x16x32_bf16 v[104:107], v[202:205], v[168:171], v[104:107]
	v_mfma_f32_16x16x32_bf16 v[96:99], v[172:175], v[168:171], v[96:99]
	v_mfma_f32_16x16x32_bf16 v[92:95], v[194:197], v[176:179], v[92:95]
	ds_write_b128 v229, v[44:47] offset:57344
	v_lshl_add_u64 v[44:45], v[212:213], 0, s[18:19]
	global_load_dwordx4 v[44:47], v[44:45], off
	v_mfma_f32_16x16x32_bf16 v[84:87], v[198:201], v[176:179], v[84:87]
	v_mfma_f32_16x16x32_bf16 v[88:91], v[202:205], v[176:179], v[88:91]
	v_mfma_f32_16x16x32_bf16 v[80:83], v[172:175], v[176:179], v[80:83]
	v_mfma_f32_16x16x32_bf16 v[76:79], v[194:197], v[164:167], v[76:79]
	ds_write_b128 v229, v[52:55] offset:61440
	v_lshl_add_u64 v[52:53], v[212:213], 0, s[20:21]
	global_load_dwordx4 v[52:55], v[52:53], off
	v_mfma_f32_16x16x32_bf16 v[68:71], v[198:201], v[164:167], v[68:71]
	v_mfma_f32_16x16x32_bf16 v[72:75], v[202:205], v[164:167], v[72:75]
	v_mfma_f32_16x16x32_bf16 v[64:67], v[172:175], v[164:167], v[64:67]
	s_cmp_lt_u32 s13, 28
	s_cselect_b64 s[0:1], -1, 0
	s_and_b64 s[4:5], s[8:9], vcc
	v_lshl_add_u64 v[160:161], v[206:207], 0, s[22:23]
	v_cndmask_b32_e64 v162, v138, v134, s[4:5]
	v_cndmask_b32_e64 v163, v139, v135, s[4:5]
	v_cndmask_b32_e64 v207, v163, v161, s[0:1]
	v_cndmask_b32_e64 v206, v162, v160, s[0:1]
	v_lshl_add_u64 v[160:161], v[210:211], 0, s[30:31]
	v_cndmask_b32_e64 v162, v140, v136, s[4:5]
	v_cndmask_b32_e64 v163, v141, v137, s[4:5]
	s_setprio 0
	s_waitcnt lgkmcnt(0)
	s_barrier
; #define MFMA16(a, b, c) __builtin_amdgcn_mfma_f32_16x16x32_bf16((a), (b), (c), 0, 0, 0)
; DI void gld(u32x4v& r, const void* p) { asm volatile("global_load_dwordx4 %0, %1, off" : "=v"(r) : "v"(p) : "memory"); }
; #define WAIT_SET(N, a, b) asm volatile("s_waitcnt vmcnt(" #N ")" : "+v"(a[0]), "+v"(a[1]), "+v"(a[2]), "+v"(a[3]), "+v"(b[0]), "+v"(b[1]), "+v"(b[2]), "+v"(b[3]) :: "memory")
; DI void gemm_half(f32x4 (&acc)[4][4], const char* sa, const char* sb, int o0, int o1, u32x4v (&ra)[4], u32x4v (&rb)[4],
;                   char* stw, const bf16_t* Agn, const bf16_t* Bgn, int lda, int ldb) {
;   bf16x8 af0[4], bf0[4], af1[4], bf1[4];
; #pragma unroll
;   for (int i = 0; i < 4; ++i) { af0[i] = *(const bf16x8*)(sa + i * 16 * 128 + o0); bf0[i] = *(const bf16x8*)(sb + i * 16 * 128 + o0); }
;   __builtin_amdgcn_sched_barrier(0);
;   WAIT_SET(8, ra, rb);
; #pragma unroll
;   for (int g = 0; g < 8; ++g) {
; #pragma unroll
;     for (int ni = 0; ni < 4; ++ni) {
;       if (g < 4) acc[g][ni] = MFMA16(bf0[ni], af0[g], acc[g][ni]);
;       else acc[g - 4][ni] = MFMA16(bf1[ni], af1[g - 4], acc[g - 4][ni]);
;     }
;     if (g < 4) { af1[g] = *(const bf16x8*)(sa + g * 16 * 128 + o1); bf1[g] = *(const bf16x8*)(sb + g * 16 * 128 + o1);
;                  *(u32x4v*)(stw + g * 32 * 128) = ra[g]; gld(ra[g], Agn + (size_t)g * 32 * lda); }
;     else { *(u32x4v*)(stw + TILE_B + (g - 4) * 32 * 128) = rb[g - 4]; gld(rb[g - 4], Bgn + (size_t)(g - 4) * 32 * ldb); }
;     __builtin_amdgcn_sched_barrier(0);
;   }
; DI void gemm_kloop(f32x4 (&acc)[4][4], const bf16_t* Ag, const bf16_t* Bg, int lda, int ldb, int K, char* smem,
;                    u32x4v (&ra)[4], u32x4v (&rb)[4], u32x4v (&rc)[4], u32x4v (&rd)[4], bool pre,
;                    const bf16_t* Agn, const bf16_t* Bgn, bool hasnext) {
;     ...
;     const bf16_t* pa0 = kt + 4 < nk ? Ag + (size_t)(kt + 4) * 64 : ((last && hasnext) ? Agn : Alast);
;     const bf16_t* pb0 = kt + 4 < nk ? Bg + (size_t)(kt + 4) * 64 : ((last && hasnext) ? Bgn : Blast);
;     gemm_half(acc, sa0 + 2 * TILE_B, sb0 + 2 * TILE_B, o0, o1, ra, rb, st, pa0, pb0, lda, ldb);
;     __syncthreads();
;   }
;   if (!hasnext) { WAIT_SET(0, ra, rb); WAIT_SET(0, rc, rd); }
	v_cndmask_b32_e64 v209, v163, v161, s[0:1]
	v_cndmask_b32_e64 v208, v162, v160, s[0:1]
	ds_read_b128 v[160:163], v159 offset:32768
	ds_read_b128 v[164:167], v226 offset:49152
	ds_read_b128 v[168:171], v159 offset:34816
	ds_read_b128 v[172:175], v226 offset:51200
	ds_read_b128 v[176:179], v159 offset:36864
	ds_read_b128 v[180:183], v226 offset:53248
	ds_read_b128 v[186:189], v159 offset:38912
	ds_read_b128 v[190:193], v226 offset:55296
	s_waitcnt vmcnt(8)
	s_setprio 1
	s_waitcnt lgkmcnt(6)
	v_mfma_f32_16x16x32_bf16 v[124:127], v[164:167], v[160:163], v[124:127]
	s_waitcnt lgkmcnt(4)
	v_mfma_f32_16x16x32_bf16 v[116:119], v[172:175], v[160:163], v[116:119]
	s_waitcnt lgkmcnt(2)
	v_mfma_f32_16x16x32_bf16 v[120:123], v[180:183], v[160:163], v[120:123]
	s_waitcnt lgkmcnt(0)
	v_mfma_f32_16x16x32_bf16 v[112:115], v[190:193], v[160:163], v[112:115]
	ds_read_b128 v[160:163], v227 offset:32768
	ds_read_b128 v[194:197], v228 offset:49152
	ds_write_b128 v229, v[0:3]
	global_load_dwordx4 v[0:3], v[206:207], off
	v_mfma_f32_16x16x32_bf16 v[108:111], v[164:167], v[168:171], v[108:111]
	v_mfma_f32_16x16x32_bf16 v[100:103], v[172:175], v[168:171], v[100:103]
	v_mfma_f32_16x16x32_bf16 v[104:107], v[180:183], v[168:171], v[104:107]
	v_mfma_f32_16x16x32_bf16 v[96:99], v[190:193], v[168:171], v[96:99]
	ds_read_b128 v[168:171], v227 offset:34816
	ds_read_b128 v[198:201], v228 offset:51200
	ds_write_b128 v229, v[16:19] offset:4096
	v_lshl_add_u64 v[16:17], v[206:207], 0, s[16:17]
	global_load_dwordx4 v[16:19], v[16:17], off
	s_setprio 2
	v_mfma_f32_16x16x32_bf16 v[92:95], v[164:167], v[176:179], v[92:95]
	v_mfma_f32_16x16x32_bf16 v[84:87], v[172:175], v[176:179], v[84:87]
	v_mfma_f32_16x16x32_bf16 v[88:91], v[180:183], v[176:179], v[88:91]
	v_mfma_f32_16x16x32_bf16 v[80:83], v[190:193], v[176:179], v[80:83]
	ds_read_b128 v[176:179], v227 offset:36864
	ds_read_b128 v[202:205], v228 offset:53248
	ds_write_b128 v229, v[32:35] offset:8192
	v_lshl_add_u64 v[32:33], v[206:207], 0, s[18:19]
	global_load_dwordx4 v[32:35], v[32:33], off
	v_mfma_f32_16x16x32_bf16 v[76:79], v[164:167], v[186:189], v[76:79]
	v_mfma_f32_16x16x32_bf16 v[68:71], v[172:175], v[186:189], v[68:71]
	ds_read_b128 v[164:167], v227 offset:38912
	ds_read_b128 v[172:175], v228 offset:55296
	ds_write_b128 v229, v[56:59] offset:12288
	v_lshl_add_u64 v[56:57], v[206:207], 0, s[20:21]
	v_mfma_f32_16x16x32_bf16 v[72:75], v[180:183], v[186:189], v[72:75]
	global_load_dwordx4 v[56:59], v[56:57], off
	v_mfma_f32_16x16x32_bf16 v[64:67], v[190:193], v[186:189], v[64:67]
	s_waitcnt lgkmcnt(10)
	v_mfma_f32_16x16x32_bf16 v[124:127], v[194:197], v[160:163], v[124:127]
	ds_write_b128 v229, v[4:7] offset:16384
	global_load_dwordx4 v[4:7], v[208:209], off
	s_waitcnt lgkmcnt(8)
	v_mfma_f32_16x16x32_bf16 v[116:119], v[198:201], v[160:163], v[116:119]
	s_waitcnt lgkmcnt(5)
	v_mfma_f32_16x16x32_bf16 v[120:123], v[202:205], v[160:163], v[120:123]
	s_waitcnt lgkmcnt(2)
	v_mfma_f32_16x16x32_bf16 v[112:115], v[172:175], v[160:163], v[112:115]
	s_setprio 3
	v_mfma_f32_16x16x32_bf16 v[108:111], v[194:197], v[168:171], v[108:111]
	ds_write_b128 v229, v[20:23] offset:20480
	v_lshl_add_u64 v[20:21], v[208:209], 0, s[16:17]
	global_load_dwordx4 v[20:23], v[20:21], off
	v_mfma_f32_16x16x32_bf16 v[100:103], v[198:201], v[168:171], v[100:103]
	v_mfma_f32_16x16x32_bf16 v[104:107], v[202:205], v[168:171], v[104:107]
	v_mfma_f32_16x16x32_bf16 v[96:99], v[172:175], v[168:171], v[96:99]
	v_mfma_f32_16x16x32_bf16 v[92:95], v[194:197], v[176:179], v[92:95]
	ds_write_b128 v229, v[36:39] offset:24576
	v_lshl_add_u64 v[36:37], v[208:209], 0, s[18:19]
	global_load_dwordx4 v[36:39], v[36:37], off
	v_mfma_f32_16x16x32_bf16 v[84:87], v[198:201], v[176:179], v[84:87]
	v_mfma_f32_16x16x32_bf16 v[88:91], v[202:205], v[176:179], v[88:91]
	v_mfma_f32_16x16x32_bf16 v[80:83], v[172:175], v[176:179], v[80:83]
	v_mfma_f32_16x16x32_bf16 v[76:79], v[194:197], v[164:167], v[76:79]
	ds_write_b128 v229, v[60:63] offset:28672
	v_lshl_add_u64 v[60:61], v[208:209], 0, s[20:21]
	global_load_dwordx4 v[60:63], v[60:61], off
	v_mfma_f32_16x16x32_bf16 v[68:71], v[198:201], v[164:167], v[68:71]
	v_mfma_f32_16x16x32_bf16 v[72:75], v[202:205], v[164:167], v[72:75]
	v_mfma_f32_16x16x32_bf16 v[64:67], v[172:175], v[164:167], v[64:67]
	v_lshl_add_u64 v[146:147], v[146:147], 0, s[24:25]
	v_lshl_add_u64 v[148:149], v[148:149], 0, s[24:25]
	s_and_b64 vcc, exec, vcc
	s_setprio 0
	s_waitcnt lgkmcnt(0)
	s_barrier
	s_cbranch_vccz .LBB0_2052
	v_readlane_b32 s16, v248, 13
	s_and_b64 vcc, exec, s[6:7]
	v_readlane_b32 s17, v248, 14
	v_readlane_b32 s18, v248, 15
	v_readlane_b32 s19, v248, 16
	v_readlane_b32 s20, v248, 17
	v_readlane_b32 s21, v248, 18
	v_readlane_b32 s26, v248, 23
	v_readlane_b32 s27, v248, 24
	v_readlane_b32 s28, v248, 25
	v_readlane_b32 s29, v248, 26
	v_readlane_b32 s30, v248, 27
	v_readlane_b32 s31, v248, 28
	v_readlane_b32 s22, v248, 19
	v_readlane_b32 s23, v248, 20
	v_readlane_b32 s24, v248, 21
	v_readlane_b32 s25, v248, 22
	s_cbranch_vccz .LBB0_2041
	s_waitcnt vmcnt(0)
	s_waitcnt vmcnt(0)
	s_branch .LBB0_2041
